# norm phases use 8 columns per lane with 16-byte write-through stores; hgrn1+diff phase stores write-through and its grid barrier skips the L2 writeback
# baseline (speedup 1.0000x reference)
; DI void norm_phase(const Args& A, int wave_s, int l, int which, int rows) {
;     ...
;     const float* gn = (which == 1 ? C.n1g : C.n2g) + l * 1024;
;     const bool from_in = (l == 0 && which == 1);
;     f32x4 g[4];
; #pragma unroll
;     for (int j = 0; j < 4; ++j) g[j] = *(const f32x4*)(gn + 4 * (C.lane + 64 * j));
;     for (int m0 = C.gw * 2; m0 < rows; m0 += C.NGW * 2) {
;         f32x4 xv[2][4];
;         const float* modp[2];
; #pragma unroll
;         for (int rr = 0; rr < 2; ++rr) {
;             const int m = m0 + rr; const float* xr; int v;
;             if (m < NLAT) { xr = (from_in ? C.x : C.out) + (size_t)m * 1024; v = m >> 13; }
;             else { xr = (from_in ? C.ctx : C.XC) + (size_t)(m - NLAT) * 1024; v = 4; }
;             modp[rr] = C.SM + SM_MOD + (l * 5 + v) * 6144 + (which == 1 ? 0 : 3072);
; #pragma unroll
;             for (int j = 0; j < 4; ++j) xv[rr][j] = ((const f32x4*)xr)[C.lane + 64 * j];
;         }
; #pragma unroll
;         for (int rr = 0; rr < 2; ++rr) {
;             const int m = m0 + rr;
;             f32x4 sh[4], sc[4];
; #pragma unroll
;             for (int j = 0; j < 4; ++j) { const int col = 4 * (C.lane + 64 * j); sh[j] = *(const f32x4*)(modp[rr] + col); sc[j] = *(const f32x4*)(modp[rr] + 1024 + col); }
.LBB0_55:
	s_lshl_b32 s4, s56, 10
	s_mov_b32 s5, s97
	v_writelane_b32 v255, s4, 32
	s_mul_i32 s45, s56, 5
	v_mbcnt_lo_u32_b32 v48, -1, 0
	v_mbcnt_hi_u32_b32 v48, -1, v48
	s_nop 0
	v_writelane_b32 v255, s5, 33
	v_mbcnt_lo_u32_b32 v0, -1, 0
	v_mbcnt_hi_u32_b32 v0, -1, v0
	v_readlane_b32 s6, v255, 32
	v_lshlrev_b32_e32 v1, 5, v0
	v_lshlrev_b32_e32 v2, 4, v0
	v_xor_b32_e32 v4, 1, v0
	v_xor_b32_e32 v5, 2, v0
	v_xor_b32_e32 v6, 4, v0
	v_xor_b32_e32 v7, 8, v0
	v_xor_b32_e32 v8, 16, v0
	v_xor_b32_e32 v9, 32, v0
	v_lshlrev_b32_e32 v4, 2, v4
	v_lshlrev_b32_e32 v5, 2, v5
	v_lshlrev_b32_e32 v6, 2, v6
	v_lshlrev_b32_e32 v7, 2, v7
	v_lshlrev_b32_e32 v8, 2, v8
	v_lshlrev_b32_e32 v9, 2, v9
	v_mov_b32_e32 v60, 0x358637bd
	s_lshr_b32 s6, s6, 10
	s_lshr_b32 s4, s94, 6
	s_lshl_b32 s5, s65, 3
	s_add_u32 s4, s4, s5
	s_lshr_b32 s5, s4, 9
	s_mul_i32 s7, s6, 5
	s_add_u32 s5, s7, s5
	s_mul_i32 s5, s5, 0x6000
	s_add_u32 s24, s88, 0x100000
	s_addc_u32 s25, s89, 0
	s_add_u32 s24, s24, s5
	s_addc_u32 s25, s25, 0
	s_add_u32 s26, s24, 0x1000
	s_addc_u32 s27, s25, 0
	v_readlane_b32 s28, v252, 46
	v_readlane_b32 s29, v252, 47
	s_lshl_b32 s7, s6, 12
	s_nop 1
	s_add_u32 s28, s28, s7
	s_addc_u32 s29, s29, 0
	v_readlane_b32 s8, v252, 31
	v_readlane_b32 s9, v252, 32
	s_add_u32 s30, s88, 0x3400000
	s_addc_u32 s31, s89, 0
	v_readlane_b32 s10, v252, 34
	v_readlane_b32 s11, v252, 35
	v_readlane_b32 s2, v252, 38
	v_readlane_b32 s32, v252, 39
	s_nop 1
	s_cmp_eq_u32 s6, 0
	s_cselect_b32 s8, s10, s8
	s_cselect_b32 s9, s11, s9
	s_cselect_b32 s30, s2, s30
	s_cselect_b32 s31, s32, s31
	s_mov_b32 s2, 1
	s_cmp_lt_u32 s4, 0x400
	s_cselect_b32 s2, s2, 0
	s_and_b32 s7, s4, 0x3ff
	s_lshl_b32 s5, s7, 12
	s_add_u32 s30, s30, s5
	s_addc_u32 s31, s31, 0
	s_lshl_b32 s5, s4, 16
	s_add_u32 s8, s8, s5
	s_addc_u32 s9, s9, 0
	s_add_u32 s10, s88, 0x3800000
	s_addc_u32 s11, s89, 0
	s_lshl_b32 s5, s4, 15
	s_add_u32 s10, s10, s5
	s_addc_u32 s11, s11, 0
	s_mov_b32 s32, 0x3a800000
	global_load_dwordx4 v[24:27], v1, s[28:29]
	global_load_dwordx4 v[28:31], v1, s[28:29] offset:16
	global_load_dwordx4 v[32:35], v1, s[28:29] offset:2048
	global_load_dwordx4 v[36:39], v1, s[28:29] offset:2064
	global_load_dwordx4 v[40:43], v1, s[26:27]
	global_load_dwordx4 v[64:67], v1, s[26:27] offset:16
	global_load_dwordx4 v[68:71], v1, s[26:27] offset:2048
	global_load_dwordx4 v[72:75], v1, s[26:27] offset:2064
	global_load_dwordx4 v[80:83], v1, s[24:25]
	global_load_dwordx4 v[84:87], v1, s[24:25] offset:16
	global_load_dwordx4 v[88:91], v1, s[24:25] offset:2048
	global_load_dwordx4 v[92:95], v1, s[24:25] offset:2064
	global_load_dwordx4 v[96:99], v1, s[8:9]
	global_load_dwordx4 v[100:103], v1, s[8:9] offset:16
	global_load_dwordx4 v[104:107], v1, s[8:9] offset:2048
	global_load_dwordx4 v[108:111], v1, s[8:9] offset:2064
	s_add_u32 s8, s8, 0x1000
	s_addc_u32 s9, s9, 0
	global_load_dwordx4 v[112:115], v1, s[8:9]
	global_load_dwordx4 v[116:119], v1, s[8:9] offset:16
	global_load_dwordx4 v[120:123], v1, s[8:9] offset:2048
	global_load_dwordx4 v[124:127], v1, s[8:9] offset:2064
	s_add_u32 s8, s8, 0x1000
	s_addc_u32 s9, s9, 0
	global_load_dwordx4 v[128:131], v1, s[8:9]
	global_load_dwordx4 v[132:135], v1, s[8:9] offset:16
	global_load_dwordx4 v[136:139], v1, s[8:9] offset:2048
	global_load_dwordx4 v[140:143], v1, s[8:9] offset:2064
	s_add_u32 s8, s8, 0x1000
	s_addc_u32 s9, s9, 0
	global_load_dwordx4 v[144:147], v1, s[8:9]
	global_load_dwordx4 v[148:151], v1, s[8:9] offset:16
	global_load_dwordx4 v[152:155], v1, s[8:9] offset:2048
	global_load_dwordx4 v[156:159], v1, s[8:9] offset:2064
	s_add_u32 s8, s8, 0x1000
	s_addc_u32 s9, s9, 0
	global_load_dwordx4 v[164:167], v1, s[8:9]
	global_load_dwordx4 v[168:171], v1, s[8:9] offset:16
	global_load_dwordx4 v[172:175], v1, s[8:9] offset:2048
	global_load_dwordx4 v[176:179], v1, s[8:9] offset:2064
	s_add_u32 s8, s8, 0x1000
	s_addc_u32 s9, s9, 0
	global_load_dwordx4 v[180:183], v1, s[8:9]
	global_load_dwordx4 v[184:187], v1, s[8:9] offset:16
	global_load_dwordx4 v[188:191], v1, s[8:9] offset:2048
	global_load_dwordx4 v[192:195], v1, s[8:9] offset:2064
	s_add_u32 s8, s8, 0x1000
	s_addc_u32 s9, s9, 0
	global_load_dwordx4 v[196:199], v1, s[8:9]
	global_load_dwordx4 v[200:203], v1, s[8:9] offset:16
	global_load_dwordx4 v[204:207], v1, s[8:9] offset:2048
	global_load_dwordx4 v[208:211], v1, s[8:9] offset:2064
	s_add_u32 s8, s8, 0x1000
	s_addc_u32 s9, s9, 0
	global_load_dwordx4 v[212:215], v1, s[8:9]
	global_load_dwordx4 v[216:219], v1, s[8:9] offset:16
	global_load_dwordx4 v[220:223], v1, s[8:9] offset:2048
	global_load_dwordx4 v[224:227], v1, s[8:9] offset:2064
	s_add_u32 s8, s8, 0x1000
	s_addc_u32 s9, s9, 0
	s_waitcnt vmcnt(32)
	v_pk_add_f32 v[40:41], v[40:41], 1.0 op_sel_hi:[1,0]
	v_pk_add_f32 v[42:43], v[42:43], 1.0 op_sel_hi:[1,0]
	v_pk_add_f32 v[64:65], v[64:65], 1.0 op_sel_hi:[1,0]
	v_pk_add_f32 v[66:67], v[66:67], 1.0 op_sel_hi:[1,0]
	v_pk_add_f32 v[68:69], v[68:69], 1.0 op_sel_hi:[1,0]
	v_pk_add_f32 v[70:71], v[70:71], 1.0 op_sel_hi:[1,0]
	v_pk_add_f32 v[72:73], v[72:73], 1.0 op_sel_hi:[1,0]
	v_pk_add_f32 v[74:75], v[74:75], 1.0 op_sel_hi:[1,0]
	s_waitcnt vmcnt(16)
; DI unsigned pk2(float lo, float hi) { return f2bf(lo) | (f2bf(hi) << 16); }
; DI void norm_phase(const Args& A, int wave_s, int l, int which, int rows) {
;     ...
;             float ss = 0.f;
; #pragma unroll
;             for (int j = 0; j < 4; ++j) ss += (xv[rr][j].x * xv[rr][j].x + xv[rr][j].y * xv[rr][j].y) + (xv[rr][j].z * xv[rr][j].z + xv[rr][j].w * xv[rr][j].w);
;             ss = wave_sum(C.lane, ss);
;             const float rs = rsqrtf(ss * (1.f / 1024.f) + EPS);
; #pragma unroll
;             for (int j = 0; j < 4; ++j) { const int col = 4 * (C.lane + 64 * j);
;                 const f32x4 y = xv[rr][j] * rs * g[j] * (sc[j] + 1.f) + sh[j];
;                 v2u o; o.x = pk2(y.x, y.y); o.y = pk2(y.z, y.w);
;                 *(v2u*)(C.H + (size_t)m * 1024 + col) = o; }
	v_mul_f32_e32 v10, v96, v96
	v_fmac_f32_e32 v10, v97, v97
	v_fmac_f32_e32 v10, v98, v98
	v_fmac_f32_e32 v10, v99, v99
	v_fmac_f32_e32 v10, v100, v100
	v_fmac_f32_e32 v10, v101, v101
	v_fmac_f32_e32 v10, v102, v102
	v_fmac_f32_e32 v10, v103, v103
	v_fmac_f32_e32 v10, v104, v104
	v_fmac_f32_e32 v10, v105, v105
	v_fmac_f32_e32 v10, v106, v106
	v_fmac_f32_e32 v10, v107, v107
	v_fmac_f32_e32 v10, v108, v108
	v_fmac_f32_e32 v10, v109, v109
	v_fmac_f32_e32 v10, v110, v110
	v_fmac_f32_e32 v10, v111, v111
	v_mul_f32_e32 v11, v112, v112
	v_fmac_f32_e32 v11, v113, v113
	v_fmac_f32_e32 v11, v114, v114
	v_fmac_f32_e32 v11, v115, v115
	v_fmac_f32_e32 v11, v116, v116
	v_fmac_f32_e32 v11, v117, v117
	v_fmac_f32_e32 v11, v118, v118
	v_fmac_f32_e32 v11, v119, v119
	v_fmac_f32_e32 v11, v120, v120
	v_fmac_f32_e32 v11, v121, v121
	v_fmac_f32_e32 v11, v122, v122
	v_fmac_f32_e32 v11, v123, v123
	v_fmac_f32_e32 v11, v124, v124
	v_fmac_f32_e32 v11, v125, v125
	v_fmac_f32_e32 v11, v126, v126
	v_fmac_f32_e32 v11, v127, v127
	v_mul_f32_e32 v12, v128, v128
	v_fmac_f32_e32 v12, v129, v129
	v_fmac_f32_e32 v12, v130, v130
	v_fmac_f32_e32 v12, v131, v131
	v_fmac_f32_e32 v12, v132, v132
	v_fmac_f32_e32 v12, v133, v133
	v_fmac_f32_e32 v12, v134, v134
	v_fmac_f32_e32 v12, v135, v135
	v_fmac_f32_e32 v12, v136, v136
	v_fmac_f32_e32 v12, v137, v137
	v_fmac_f32_e32 v12, v138, v138
	v_fmac_f32_e32 v12, v139, v139
	v_fmac_f32_e32 v12, v140, v140
	v_fmac_f32_e32 v12, v141, v141
	v_fmac_f32_e32 v12, v142, v142
	v_fmac_f32_e32 v12, v143, v143
	v_mul_f32_e32 v13, v144, v144
	v_fmac_f32_e32 v13, v145, v145
	v_fmac_f32_e32 v13, v146, v146
	v_fmac_f32_e32 v13, v147, v147
	v_fmac_f32_e32 v13, v148, v148
	v_fmac_f32_e32 v13, v149, v149
	v_fmac_f32_e32 v13, v150, v150
	v_fmac_f32_e32 v13, v151, v151
	v_fmac_f32_e32 v13, v152, v152
	v_fmac_f32_e32 v13, v153, v153
	v_fmac_f32_e32 v13, v154, v154
	v_fmac_f32_e32 v13, v155, v155
	v_fmac_f32_e32 v13, v156, v156
	v_fmac_f32_e32 v13, v157, v157
	v_fmac_f32_e32 v13, v158, v158
	v_fmac_f32_e32 v13, v159, v159
	ds_bpermute_b32 v14, v4, v10
	ds_bpermute_b32 v15, v4, v11
	ds_bpermute_b32 v16, v4, v12
	ds_bpermute_b32 v17, v4, v13
	s_waitcnt lgkmcnt(0)
	v_add_f32_e32 v10, v10, v14
	v_add_f32_e32 v11, v11, v15
	v_add_f32_e32 v12, v12, v16
	v_add_f32_e32 v13, v13, v17
	ds_bpermute_b32 v14, v5, v10
	ds_bpermute_b32 v15, v5, v11
	ds_bpermute_b32 v16, v5, v12
	ds_bpermute_b32 v17, v5, v13
	s_waitcnt lgkmcnt(0)
	v_add_f32_e32 v10, v10, v14
	v_add_f32_e32 v11, v11, v15
	v_add_f32_e32 v12, v12, v16
	v_add_f32_e32 v13, v13, v17
	ds_bpermute_b32 v14, v6, v10
	ds_bpermute_b32 v15, v6, v11
	ds_bpermute_b32 v16, v6, v12
	ds_bpermute_b32 v17, v6, v13
	s_waitcnt lgkmcnt(0)
	v_add_f32_e32 v10, v10, v14
	v_add_f32_e32 v11, v11, v15
	v_add_f32_e32 v12, v12, v16
	v_add_f32_e32 v13, v13, v17
	ds_bpermute_b32 v14, v7, v10
	ds_bpermute_b32 v15, v7, v11
	ds_bpermute_b32 v16, v7, v12
	ds_bpermute_b32 v17, v7, v13
	s_waitcnt lgkmcnt(0)
	v_add_f32_e32 v10, v10, v14
	v_add_f32_e32 v11, v11, v15
	v_add_f32_e32 v12, v12, v16
	v_add_f32_e32 v13, v13, v17
	ds_bpermute_b32 v14, v8, v10
	ds_bpermute_b32 v15, v8, v11
	ds_bpermute_b32 v16, v8, v12
	ds_bpermute_b32 v17, v8, v13
	s_waitcnt lgkmcnt(0)
	v_add_f32_e32 v10, v10, v14
	v_add_f32_e32 v11, v11, v15
	v_add_f32_e32 v12, v12, v16
	v_add_f32_e32 v13, v13, v17
	ds_bpermute_b32 v14, v9, v10
	ds_bpermute_b32 v15, v9, v11
	ds_bpermute_b32 v16, v9, v12
	ds_bpermute_b32 v17, v9, v13
	s_waitcnt lgkmcnt(0)
	v_add_f32_e32 v10, v10, v14
	v_add_f32_e32 v11, v11, v15
	v_add_f32_e32 v12, v12, v16
	v_add_f32_e32 v13, v13, v17
	v_fma_f32 v10, v10, s32, v60
	v_fma_f32 v11, v11, s32, v60
	v_fma_f32 v12, v12, s32, v60
	v_fma_f32 v13, v13, s32, v60
	v_rsq_f32_e32 v18, v10
	v_rsq_f32_e32 v20, v11
	v_rsq_f32_e32 v22, v12
	v_rsq_f32_e32 v62, v13
	s_nop 0
	v_pk_mul_f32 v[96:97], v[96:97], v[18:19] op_sel_hi:[1,0]
	v_pk_mul_f32 v[98:99], v[98:99], v[18:19] op_sel_hi:[1,0]
	v_pk_mul_f32 v[100:101], v[100:101], v[18:19] op_sel_hi:[1,0]
	v_pk_mul_f32 v[102:103], v[102:103], v[18:19] op_sel_hi:[1,0]
	v_pk_mul_f32 v[104:105], v[104:105], v[18:19] op_sel_hi:[1,0]
	v_pk_mul_f32 v[106:107], v[106:107], v[18:19] op_sel_hi:[1,0]
	v_pk_mul_f32 v[108:109], v[108:109], v[18:19] op_sel_hi:[1,0]
	v_pk_mul_f32 v[110:111], v[110:111], v[18:19] op_sel_hi:[1,0]
	v_pk_mul_f32 v[96:97], v[24:25], v[96:97]
	v_pk_mul_f32 v[98:99], v[26:27], v[98:99]
	v_pk_mul_f32 v[100:101], v[28:29], v[100:101]
	v_pk_mul_f32 v[102:103], v[30:31], v[102:103]
	v_pk_mul_f32 v[104:105], v[32:33], v[104:105]
	v_pk_mul_f32 v[106:107], v[34:35], v[106:107]
	v_pk_mul_f32 v[108:109], v[36:37], v[108:109]
	v_pk_mul_f32 v[110:111], v[38:39], v[110:111]
	v_pk_fma_f32 v[96:97], v[40:41], v[96:97], v[80:81]
	v_pk_fma_f32 v[98:99], v[42:43], v[98:99], v[82:83]
	v_pk_fma_f32 v[100:101], v[64:65], v[100:101], v[84:85]
	v_pk_fma_f32 v[102:103], v[66:67], v[102:103], v[86:87]
	v_pk_fma_f32 v[104:105], v[68:69], v[104:105], v[88:89]
	v_pk_fma_f32 v[106:107], v[70:71], v[106:107], v[90:91]
	v_pk_fma_f32 v[108:109], v[72:73], v[108:109], v[92:93]
	v_pk_fma_f32 v[110:111], v[74:75], v[110:111], v[94:95]
	v_cvt_pk_bf16_f32 v96, v96, v97
	v_cvt_pk_bf16_f32 v97, v98, v99
	v_cvt_pk_bf16_f32 v98, v100, v101
	v_cvt_pk_bf16_f32 v99, v102, v103
	v_cvt_pk_bf16_f32 v104, v104, v105
	v_cvt_pk_bf16_f32 v105, v106, v107
	v_cvt_pk_bf16_f32 v106, v108, v109
	v_cvt_pk_bf16_f32 v107, v110, v111
	global_store_dwordx4 v2, v[96:99], s[10:11] sc1
	global_store_dwordx4 v2, v[104:107], s[10:11] offset:1024 sc1
	s_add_u32 s10, s10, 0x800
	s_addc_u32 s11, s11, 0
	v_pk_mul_f32 v[112:113], v[112:113], v[20:21] op_sel_hi:[1,0]
; DI unsigned pk2(float lo, float hi) { return f2bf(lo) | (f2bf(hi) << 16); }
; DI void norm_phase(const Args& A, int wave_s, int l, int which, int rows) {
;     ...
;             for (int j = 0; j < 4; ++j) xv[rr][j] = ((const f32x4*)xr)[C.lane + 64 * j];
;     ...
;             float ss = 0.f;
; #pragma unroll
;             for (int j = 0; j < 4; ++j) ss += (xv[rr][j].x * xv[rr][j].x + xv[rr][j].y * xv[rr][j].y) + (xv[rr][j].z * xv[rr][j].z + xv[rr][j].w * xv[rr][j].w);
;             ss = wave_sum(C.lane, ss);
;             const float rs = rsqrtf(ss * (1.f / 1024.f) + EPS);
; #pragma unroll
;             for (int j = 0; j < 4; ++j) { const int col = 4 * (C.lane + 64 * j);
;                 const f32x4 y = xv[rr][j] * rs * g[j] * (sc[j] + 1.f) + sh[j];
;                 v2u o; o.x = pk2(y.x, y.y); o.y = pk2(y.z, y.w);
;                 *(v2u*)(C.H + (size_t)m * 1024 + col) = o; }
	v_pk_mul_f32 v[114:115], v[114:115], v[20:21] op_sel_hi:[1,0]
	v_pk_mul_f32 v[116:117], v[116:117], v[20:21] op_sel_hi:[1,0]
	v_pk_mul_f32 v[118:119], v[118:119], v[20:21] op_sel_hi:[1,0]
	v_pk_mul_f32 v[120:121], v[120:121], v[20:21] op_sel_hi:[1,0]
	v_pk_mul_f32 v[122:123], v[122:123], v[20:21] op_sel_hi:[1,0]
	v_pk_mul_f32 v[124:125], v[124:125], v[20:21] op_sel_hi:[1,0]
	v_pk_mul_f32 v[126:127], v[126:127], v[20:21] op_sel_hi:[1,0]
	v_pk_mul_f32 v[112:113], v[24:25], v[112:113]
	v_pk_mul_f32 v[114:115], v[26:27], v[114:115]
	v_pk_mul_f32 v[116:117], v[28:29], v[116:117]
	v_pk_mul_f32 v[118:119], v[30:31], v[118:119]
	v_pk_mul_f32 v[120:121], v[32:33], v[120:121]
	v_pk_mul_f32 v[122:123], v[34:35], v[122:123]
	v_pk_mul_f32 v[124:125], v[36:37], v[124:125]
	v_pk_mul_f32 v[126:127], v[38:39], v[126:127]
	v_pk_fma_f32 v[112:113], v[40:41], v[112:113], v[80:81]
	v_pk_fma_f32 v[114:115], v[42:43], v[114:115], v[82:83]
	v_pk_fma_f32 v[116:117], v[64:65], v[116:117], v[84:85]
	v_pk_fma_f32 v[118:119], v[66:67], v[118:119], v[86:87]
	v_pk_fma_f32 v[120:121], v[68:69], v[120:121], v[88:89]
	v_pk_fma_f32 v[122:123], v[70:71], v[122:123], v[90:91]
	v_pk_fma_f32 v[124:125], v[72:73], v[124:125], v[92:93]
	v_pk_fma_f32 v[126:127], v[74:75], v[126:127], v[94:95]
	v_cvt_pk_bf16_f32 v112, v112, v113
	v_cvt_pk_bf16_f32 v113, v114, v115
	v_cvt_pk_bf16_f32 v114, v116, v117
	v_cvt_pk_bf16_f32 v115, v118, v119
	v_cvt_pk_bf16_f32 v120, v120, v121
	v_cvt_pk_bf16_f32 v121, v122, v123
	v_cvt_pk_bf16_f32 v122, v124, v125
	v_cvt_pk_bf16_f32 v123, v126, v127
	global_store_dwordx4 v2, v[112:115], s[10:11] sc1
	global_store_dwordx4 v2, v[120:123], s[10:11] offset:1024 sc1
	s_add_u32 s10, s10, 0x800
	s_addc_u32 s11, s11, 0
	v_pk_mul_f32 v[128:129], v[128:129], v[22:23] op_sel_hi:[1,0]
	v_pk_mul_f32 v[130:131], v[130:131], v[22:23] op_sel_hi:[1,0]
	v_pk_mul_f32 v[132:133], v[132:133], v[22:23] op_sel_hi:[1,0]
	v_pk_mul_f32 v[134:135], v[134:135], v[22:23] op_sel_hi:[1,0]
	v_pk_mul_f32 v[136:137], v[136:137], v[22:23] op_sel_hi:[1,0]
	v_pk_mul_f32 v[138:139], v[138:139], v[22:23] op_sel_hi:[1,0]
	v_pk_mul_f32 v[140:141], v[140:141], v[22:23] op_sel_hi:[1,0]
	v_pk_mul_f32 v[142:143], v[142:143], v[22:23] op_sel_hi:[1,0]
	v_pk_mul_f32 v[128:129], v[24:25], v[128:129]
	v_pk_mul_f32 v[130:131], v[26:27], v[130:131]
	v_pk_mul_f32 v[132:133], v[28:29], v[132:133]
	v_pk_mul_f32 v[134:135], v[30:31], v[134:135]
	v_pk_mul_f32 v[136:137], v[32:33], v[136:137]
	v_pk_mul_f32 v[138:139], v[34:35], v[138:139]
	v_pk_mul_f32 v[140:141], v[36:37], v[140:141]
	v_pk_mul_f32 v[142:143], v[38:39], v[142:143]
	v_pk_fma_f32 v[128:129], v[40:41], v[128:129], v[80:81]
	v_pk_fma_f32 v[130:131], v[42:43], v[130:131], v[82:83]
	v_pk_fma_f32 v[132:133], v[64:65], v[132:133], v[84:85]
	v_pk_fma_f32 v[134:135], v[66:67], v[134:135], v[86:87]
	v_pk_fma_f32 v[136:137], v[68:69], v[136:137], v[88:89]
	v_pk_fma_f32 v[138:139], v[70:71], v[138:139], v[90:91]
	v_pk_fma_f32 v[140:141], v[72:73], v[140:141], v[92:93]
	v_pk_fma_f32 v[142:143], v[74:75], v[142:143], v[94:95]
	v_cvt_pk_bf16_f32 v128, v128, v129
	v_cvt_pk_bf16_f32 v129, v130, v131
	v_cvt_pk_bf16_f32 v130, v132, v133
	v_cvt_pk_bf16_f32 v131, v134, v135
	v_cvt_pk_bf16_f32 v136, v136, v137
	v_cvt_pk_bf16_f32 v137, v138, v139
	v_cvt_pk_bf16_f32 v138, v140, v141
	v_cvt_pk_bf16_f32 v139, v142, v143
	global_store_dwordx4 v2, v[128:131], s[10:11] sc1
	global_store_dwordx4 v2, v[136:139], s[10:11] offset:1024 sc1
	s_add_u32 s10, s10, 0x800
	s_addc_u32 s11, s11, 0
	v_pk_mul_f32 v[144:145], v[144:145], v[62:63] op_sel_hi:[1,0]
	v_pk_mul_f32 v[146:147], v[146:147], v[62:63] op_sel_hi:[1,0]
	v_pk_mul_f32 v[148:149], v[148:149], v[62:63] op_sel_hi:[1,0]
	v_pk_mul_f32 v[150:151], v[150:151], v[62:63] op_sel_hi:[1,0]
	v_pk_mul_f32 v[152:153], v[152:153], v[62:63] op_sel_hi:[1,0]
	v_pk_mul_f32 v[154:155], v[154:155], v[62:63] op_sel_hi:[1,0]
	v_pk_mul_f32 v[156:157], v[156:157], v[62:63] op_sel_hi:[1,0]
	v_pk_mul_f32 v[158:159], v[158:159], v[62:63] op_sel_hi:[1,0]
	v_pk_mul_f32 v[144:145], v[24:25], v[144:145]
	v_pk_mul_f32 v[146:147], v[26:27], v[146:147]
	v_pk_mul_f32 v[148:149], v[28:29], v[148:149]
	v_pk_mul_f32 v[150:151], v[30:31], v[150:151]
	v_pk_mul_f32 v[152:153], v[32:33], v[152:153]
	v_pk_mul_f32 v[154:155], v[34:35], v[154:155]
	v_pk_mul_f32 v[156:157], v[36:37], v[156:157]
	v_pk_mul_f32 v[158:159], v[38:39], v[158:159]
	v_pk_fma_f32 v[144:145], v[40:41], v[144:145], v[80:81]
	v_pk_fma_f32 v[146:147], v[42:43], v[146:147], v[82:83]
	v_pk_fma_f32 v[148:149], v[64:65], v[148:149], v[84:85]
	v_pk_fma_f32 v[150:151], v[66:67], v[150:151], v[86:87]
	v_pk_fma_f32 v[152:153], v[68:69], v[152:153], v[88:89]
	v_pk_fma_f32 v[154:155], v[70:71], v[154:155], v[90:91]
	v_pk_fma_f32 v[156:157], v[72:73], v[156:157], v[92:93]
	v_pk_fma_f32 v[158:159], v[74:75], v[158:159], v[94:95]
	v_cvt_pk_bf16_f32 v144, v144, v145
	v_cvt_pk_bf16_f32 v145, v146, v147
	v_cvt_pk_bf16_f32 v146, v148, v149
	v_cvt_pk_bf16_f32 v147, v150, v151
	v_cvt_pk_bf16_f32 v152, v152, v153
	v_cvt_pk_bf16_f32 v153, v154, v155
	v_cvt_pk_bf16_f32 v154, v156, v157
	v_cvt_pk_bf16_f32 v155, v158, v159
	global_store_dwordx4 v2, v[144:147], s[10:11] sc1
	global_store_dwordx4 v2, v[152:155], s[10:11] offset:1024 sc1
	s_add_u32 s10, s10, 0x800
	s_addc_u32 s11, s11, 0
	global_load_dwordx4 v[96:99], v1, s[8:9]
	global_load_dwordx4 v[100:103], v1, s[8:9] offset:16
	global_load_dwordx4 v[104:107], v1, s[8:9] offset:2048
	global_load_dwordx4 v[108:111], v1, s[8:9] offset:2064
	s_add_u32 s8, s8, 0x1000
	s_addc_u32 s9, s9, 0
	global_load_dwordx4 v[112:115], v1, s[8:9]
	global_load_dwordx4 v[116:119], v1, s[8:9] offset:16
	global_load_dwordx4 v[120:123], v1, s[8:9] offset:2048
	global_load_dwordx4 v[124:127], v1, s[8:9] offset:2064
	s_add_u32 s8, s8, 0x1000
	s_addc_u32 s9, s9, 0
	global_load_dwordx4 v[128:131], v1, s[8:9]
	global_load_dwordx4 v[132:135], v1, s[8:9] offset:16
	global_load_dwordx4 v[136:139], v1, s[8:9] offset:2048
	global_load_dwordx4 v[140:143], v1, s[8:9] offset:2064
	s_add_u32 s8, s8, 0x1000
	s_addc_u32 s9, s9, 0
	global_load_dwordx4 v[144:147], v1, s[8:9]
	global_load_dwordx4 v[148:151], v1, s[8:9] offset:16
	global_load_dwordx4 v[152:155], v1, s[8:9] offset:2048
	global_load_dwordx4 v[156:159], v1, s[8:9] offset:2064
	s_add_u32 s8, s8, 0x1000
	s_addc_u32 s9, s9, 0
	s_waitcnt vmcnt(24)
; DI unsigned pk2(float lo, float hi) { return f2bf(lo) | (f2bf(hi) << 16); }
; DI void norm_phase(const Args& A, int wave_s, int l, int which, int rows) {
;     ...
;             float ss = 0.f;
; #pragma unroll
;             for (int j = 0; j < 4; ++j) ss += (xv[rr][j].x * xv[rr][j].x + xv[rr][j].y * xv[rr][j].y) + (xv[rr][j].z * xv[rr][j].z + xv[rr][j].w * xv[rr][j].w);
;             ss = wave_sum(C.lane, ss);
;             const float rs = rsqrtf(ss * (1.f / 1024.f) + EPS);
; #pragma unroll
;             for (int j = 0; j < 4; ++j) { const int col = 4 * (C.lane + 64 * j);
;                 const f32x4 y = xv[rr][j] * rs * g[j] * (sc[j] + 1.f) + sh[j];
;                 v2u o; o.x = pk2(y.x, y.y); o.y = pk2(y.z, y.w);
;                 *(v2u*)(C.H + (size_t)m * 1024 + col) = o; }
	v_mul_f32_e32 v10, v164, v164
	v_fmac_f32_e32 v10, v165, v165
	v_fmac_f32_e32 v10, v166, v166
	v_fmac_f32_e32 v10, v167, v167
	v_fmac_f32_e32 v10, v168, v168
	v_fmac_f32_e32 v10, v169, v169
	v_fmac_f32_e32 v10, v170, v170
	v_fmac_f32_e32 v10, v171, v171
	v_fmac_f32_e32 v10, v172, v172
	v_fmac_f32_e32 v10, v173, v173
	v_fmac_f32_e32 v10, v174, v174
	v_fmac_f32_e32 v10, v175, v175
	v_fmac_f32_e32 v10, v176, v176
	v_fmac_f32_e32 v10, v177, v177
	v_fmac_f32_e32 v10, v178, v178
	v_fmac_f32_e32 v10, v179, v179
	v_mul_f32_e32 v11, v180, v180
	v_fmac_f32_e32 v11, v181, v181
	v_fmac_f32_e32 v11, v182, v182
	v_fmac_f32_e32 v11, v183, v183
	v_fmac_f32_e32 v11, v184, v184
	v_fmac_f32_e32 v11, v185, v185
	v_fmac_f32_e32 v11, v186, v186
	v_fmac_f32_e32 v11, v187, v187
	v_fmac_f32_e32 v11, v188, v188
	v_fmac_f32_e32 v11, v189, v189
	v_fmac_f32_e32 v11, v190, v190
	v_fmac_f32_e32 v11, v191, v191
	v_fmac_f32_e32 v11, v192, v192
	v_fmac_f32_e32 v11, v193, v193
	v_fmac_f32_e32 v11, v194, v194
	v_fmac_f32_e32 v11, v195, v195
	v_mul_f32_e32 v12, v196, v196
	v_fmac_f32_e32 v12, v197, v197
	v_fmac_f32_e32 v12, v198, v198
	v_fmac_f32_e32 v12, v199, v199
	v_fmac_f32_e32 v12, v200, v200
	v_fmac_f32_e32 v12, v201, v201
	v_fmac_f32_e32 v12, v202, v202
	v_fmac_f32_e32 v12, v203, v203
	v_fmac_f32_e32 v12, v204, v204
	v_fmac_f32_e32 v12, v205, v205
	v_fmac_f32_e32 v12, v206, v206
	v_fmac_f32_e32 v12, v207, v207
	v_fmac_f32_e32 v12, v208, v208
	v_fmac_f32_e32 v12, v209, v209
	v_fmac_f32_e32 v12, v210, v210
	v_fmac_f32_e32 v12, v211, v211
	v_mul_f32_e32 v13, v212, v212
	v_fmac_f32_e32 v13, v213, v213
	v_fmac_f32_e32 v13, v214, v214
	v_fmac_f32_e32 v13, v215, v215
	v_fmac_f32_e32 v13, v216, v216
	v_fmac_f32_e32 v13, v217, v217
	v_fmac_f32_e32 v13, v218, v218
	v_fmac_f32_e32 v13, v219, v219
	v_fmac_f32_e32 v13, v220, v220
	v_fmac_f32_e32 v13, v221, v221
	v_fmac_f32_e32 v13, v222, v222
	v_fmac_f32_e32 v13, v223, v223
	v_fmac_f32_e32 v13, v224, v224
	v_fmac_f32_e32 v13, v225, v225
	v_fmac_f32_e32 v13, v226, v226
	v_fmac_f32_e32 v13, v227, v227
	ds_bpermute_b32 v14, v4, v10
	ds_bpermute_b32 v15, v4, v11
	ds_bpermute_b32 v16, v4, v12
	ds_bpermute_b32 v17, v4, v13
	s_waitcnt lgkmcnt(0)
	v_add_f32_e32 v10, v10, v14
	v_add_f32_e32 v11, v11, v15
	v_add_f32_e32 v12, v12, v16
	v_add_f32_e32 v13, v13, v17
	ds_bpermute_b32 v14, v5, v10
	ds_bpermute_b32 v15, v5, v11
	ds_bpermute_b32 v16, v5, v12
	ds_bpermute_b32 v17, v5, v13
	s_waitcnt lgkmcnt(0)
	v_add_f32_e32 v10, v10, v14
	v_add_f32_e32 v11, v11, v15
	v_add_f32_e32 v12, v12, v16
	v_add_f32_e32 v13, v13, v17
	ds_bpermute_b32 v14, v6, v10
	ds_bpermute_b32 v15, v6, v11
	ds_bpermute_b32 v16, v6, v12
	ds_bpermute_b32 v17, v6, v13
	s_waitcnt lgkmcnt(0)
	v_add_f32_e32 v10, v10, v14
	v_add_f32_e32 v11, v11, v15
	v_add_f32_e32 v12, v12, v16
	v_add_f32_e32 v13, v13, v17
	ds_bpermute_b32 v14, v7, v10
	ds_bpermute_b32 v15, v7, v11
	ds_bpermute_b32 v16, v7, v12
	ds_bpermute_b32 v17, v7, v13
	s_waitcnt lgkmcnt(0)
	v_add_f32_e32 v10, v10, v14
	v_add_f32_e32 v11, v11, v15
	v_add_f32_e32 v12, v12, v16
	v_add_f32_e32 v13, v13, v17
	ds_bpermute_b32 v14, v8, v10
	ds_bpermute_b32 v15, v8, v11
	ds_bpermute_b32 v16, v8, v12
	ds_bpermute_b32 v17, v8, v13
	s_waitcnt lgkmcnt(0)
	v_add_f32_e32 v10, v10, v14
	v_add_f32_e32 v11, v11, v15
	v_add_f32_e32 v12, v12, v16
	v_add_f32_e32 v13, v13, v17
	ds_bpermute_b32 v14, v9, v10
	ds_bpermute_b32 v15, v9, v11
	ds_bpermute_b32 v16, v9, v12
	ds_bpermute_b32 v17, v9, v13
	s_waitcnt lgkmcnt(0)
	v_add_f32_e32 v10, v10, v14
	v_add_f32_e32 v11, v11, v15
	v_add_f32_e32 v12, v12, v16
	v_add_f32_e32 v13, v13, v17
	v_fma_f32 v10, v10, s32, v60
	v_fma_f32 v11, v11, s32, v60
	v_fma_f32 v12, v12, s32, v60
	v_fma_f32 v13, v13, s32, v60
	v_rsq_f32_e32 v18, v10
	v_rsq_f32_e32 v20, v11
	v_rsq_f32_e32 v22, v12
	v_rsq_f32_e32 v62, v13
	s_nop 0
	v_pk_mul_f32 v[164:165], v[164:165], v[18:19] op_sel_hi:[1,0]
	v_pk_mul_f32 v[166:167], v[166:167], v[18:19] op_sel_hi:[1,0]
	v_pk_mul_f32 v[168:169], v[168:169], v[18:19] op_sel_hi:[1,0]
	v_pk_mul_f32 v[170:171], v[170:171], v[18:19] op_sel_hi:[1,0]
	v_pk_mul_f32 v[172:173], v[172:173], v[18:19] op_sel_hi:[1,0]
	v_pk_mul_f32 v[174:175], v[174:175], v[18:19] op_sel_hi:[1,0]
	v_pk_mul_f32 v[176:177], v[176:177], v[18:19] op_sel_hi:[1,0]
	v_pk_mul_f32 v[178:179], v[178:179], v[18:19] op_sel_hi:[1,0]
	v_pk_mul_f32 v[164:165], v[24:25], v[164:165]
	v_pk_mul_f32 v[166:167], v[26:27], v[166:167]
	v_pk_mul_f32 v[168:169], v[28:29], v[168:169]
	v_pk_mul_f32 v[170:171], v[30:31], v[170:171]
	v_pk_mul_f32 v[172:173], v[32:33], v[172:173]
	v_pk_mul_f32 v[174:175], v[34:35], v[174:175]
	v_pk_mul_f32 v[176:177], v[36:37], v[176:177]
	v_pk_mul_f32 v[178:179], v[38:39], v[178:179]
	v_pk_fma_f32 v[164:165], v[40:41], v[164:165], v[80:81]
	v_pk_fma_f32 v[166:167], v[42:43], v[166:167], v[82:83]
	v_pk_fma_f32 v[168:169], v[64:65], v[168:169], v[84:85]
	v_pk_fma_f32 v[170:171], v[66:67], v[170:171], v[86:87]
	v_pk_fma_f32 v[172:173], v[68:69], v[172:173], v[88:89]
	v_pk_fma_f32 v[174:175], v[70:71], v[174:175], v[90:91]
	v_pk_fma_f32 v[176:177], v[72:73], v[176:177], v[92:93]
	v_pk_fma_f32 v[178:179], v[74:75], v[178:179], v[94:95]
	v_cvt_pk_bf16_f32 v164, v164, v165
	v_cvt_pk_bf16_f32 v165, v166, v167
	v_cvt_pk_bf16_f32 v166, v168, v169
	v_cvt_pk_bf16_f32 v167, v170, v171
	v_cvt_pk_bf16_f32 v172, v172, v173
	v_cvt_pk_bf16_f32 v173, v174, v175
	v_cvt_pk_bf16_f32 v174, v176, v177
	v_cvt_pk_bf16_f32 v175, v178, v179
	global_store_dwordx4 v2, v[164:167], s[10:11] sc1
	global_store_dwordx4 v2, v[172:175], s[10:11] offset:1024 sc1
	s_add_u32 s10, s10, 0x800
	s_addc_u32 s11, s11, 0
	v_pk_mul_f32 v[180:181], v[180:181], v[20:21] op_sel_hi:[1,0]
; DI unsigned pk2(float lo, float hi) { return f2bf(lo) | (f2bf(hi) << 16); }
; DI void norm_phase(const Args& A, int wave_s, int l, int which, int rows) {
;     ...
;             for (int j = 0; j < 4; ++j) xv[rr][j] = ((const f32x4*)xr)[C.lane + 64 * j];
;     ...
;             float ss = 0.f;
; #pragma unroll
;             for (int j = 0; j < 4; ++j) ss += (xv[rr][j].x * xv[rr][j].x + xv[rr][j].y * xv[rr][j].y) + (xv[rr][j].z * xv[rr][j].z + xv[rr][j].w * xv[rr][j].w);
;             ss = wave_sum(C.lane, ss);
;             const float rs = rsqrtf(ss * (1.f / 1024.f) + EPS);
; #pragma unroll
;             for (int j = 0; j < 4; ++j) { const int col = 4 * (C.lane + 64 * j);
;                 const f32x4 y = xv[rr][j] * rs * g[j] * (sc[j] + 1.f) + sh[j];
;                 v2u o; o.x = pk2(y.x, y.y); o.y = pk2(y.z, y.w);
;                 *(v2u*)(C.H + (size_t)m * 1024 + col) = o; }
	v_pk_mul_f32 v[182:183], v[182:183], v[20:21] op_sel_hi:[1,0]
	v_pk_mul_f32 v[184:185], v[184:185], v[20:21] op_sel_hi:[1,0]
	v_pk_mul_f32 v[186:187], v[186:187], v[20:21] op_sel_hi:[1,0]
	v_pk_mul_f32 v[188:189], v[188:189], v[20:21] op_sel_hi:[1,0]
	v_pk_mul_f32 v[190:191], v[190:191], v[20:21] op_sel_hi:[1,0]
	v_pk_mul_f32 v[192:193], v[192:193], v[20:21] op_sel_hi:[1,0]
	v_pk_mul_f32 v[194:195], v[194:195], v[20:21] op_sel_hi:[1,0]
	v_pk_mul_f32 v[180:181], v[24:25], v[180:181]
	v_pk_mul_f32 v[182:183], v[26:27], v[182:183]
	v_pk_mul_f32 v[184:185], v[28:29], v[184:185]
	v_pk_mul_f32 v[186:187], v[30:31], v[186:187]
	v_pk_mul_f32 v[188:189], v[32:33], v[188:189]
	v_pk_mul_f32 v[190:191], v[34:35], v[190:191]
	v_pk_mul_f32 v[192:193], v[36:37], v[192:193]
	v_pk_mul_f32 v[194:195], v[38:39], v[194:195]
	v_pk_fma_f32 v[180:181], v[40:41], v[180:181], v[80:81]
	v_pk_fma_f32 v[182:183], v[42:43], v[182:183], v[82:83]
	v_pk_fma_f32 v[184:185], v[64:65], v[184:185], v[84:85]
	v_pk_fma_f32 v[186:187], v[66:67], v[186:187], v[86:87]
	v_pk_fma_f32 v[188:189], v[68:69], v[188:189], v[88:89]
	v_pk_fma_f32 v[190:191], v[70:71], v[190:191], v[90:91]
	v_pk_fma_f32 v[192:193], v[72:73], v[192:193], v[92:93]
	v_pk_fma_f32 v[194:195], v[74:75], v[194:195], v[94:95]
	v_cvt_pk_bf16_f32 v180, v180, v181
	v_cvt_pk_bf16_f32 v181, v182, v183
	v_cvt_pk_bf16_f32 v182, v184, v185
	v_cvt_pk_bf16_f32 v183, v186, v187
	v_cvt_pk_bf16_f32 v188, v188, v189
	v_cvt_pk_bf16_f32 v189, v190, v191
	v_cvt_pk_bf16_f32 v190, v192, v193
	v_cvt_pk_bf16_f32 v191, v194, v195
	global_store_dwordx4 v2, v[180:183], s[10:11] sc1
	global_store_dwordx4 v2, v[188:191], s[10:11] offset:1024 sc1
	s_add_u32 s10, s10, 0x800
	s_addc_u32 s11, s11, 0
	v_pk_mul_f32 v[196:197], v[196:197], v[22:23] op_sel_hi:[1,0]
	v_pk_mul_f32 v[198:199], v[198:199], v[22:23] op_sel_hi:[1,0]
	v_pk_mul_f32 v[200:201], v[200:201], v[22:23] op_sel_hi:[1,0]
	v_pk_mul_f32 v[202:203], v[202:203], v[22:23] op_sel_hi:[1,0]
	v_pk_mul_f32 v[204:205], v[204:205], v[22:23] op_sel_hi:[1,0]
	v_pk_mul_f32 v[206:207], v[206:207], v[22:23] op_sel_hi:[1,0]
	v_pk_mul_f32 v[208:209], v[208:209], v[22:23] op_sel_hi:[1,0]
	v_pk_mul_f32 v[210:211], v[210:211], v[22:23] op_sel_hi:[1,0]
	v_pk_mul_f32 v[196:197], v[24:25], v[196:197]
	v_pk_mul_f32 v[198:199], v[26:27], v[198:199]
	v_pk_mul_f32 v[200:201], v[28:29], v[200:201]
	v_pk_mul_f32 v[202:203], v[30:31], v[202:203]
	v_pk_mul_f32 v[204:205], v[32:33], v[204:205]
	v_pk_mul_f32 v[206:207], v[34:35], v[206:207]
	v_pk_mul_f32 v[208:209], v[36:37], v[208:209]
	v_pk_mul_f32 v[210:211], v[38:39], v[210:211]
	v_pk_fma_f32 v[196:197], v[40:41], v[196:197], v[80:81]
	v_pk_fma_f32 v[198:199], v[42:43], v[198:199], v[82:83]
	v_pk_fma_f32 v[200:201], v[64:65], v[200:201], v[84:85]
	v_pk_fma_f32 v[202:203], v[66:67], v[202:203], v[86:87]
	v_pk_fma_f32 v[204:205], v[68:69], v[204:205], v[88:89]
	v_pk_fma_f32 v[206:207], v[70:71], v[206:207], v[90:91]
	v_pk_fma_f32 v[208:209], v[72:73], v[208:209], v[92:93]
	v_pk_fma_f32 v[210:211], v[74:75], v[210:211], v[94:95]
	v_cvt_pk_bf16_f32 v196, v196, v197
	v_cvt_pk_bf16_f32 v197, v198, v199
	v_cvt_pk_bf16_f32 v198, v200, v201
	v_cvt_pk_bf16_f32 v199, v202, v203
	v_cvt_pk_bf16_f32 v204, v204, v205
	v_cvt_pk_bf16_f32 v205, v206, v207
	v_cvt_pk_bf16_f32 v206, v208, v209
	v_cvt_pk_bf16_f32 v207, v210, v211
	global_store_dwordx4 v2, v[196:199], s[10:11] sc1
	global_store_dwordx4 v2, v[204:207], s[10:11] offset:1024 sc1
	s_add_u32 s10, s10, 0x800
	s_addc_u32 s11, s11, 0
	v_pk_mul_f32 v[212:213], v[212:213], v[62:63] op_sel_hi:[1,0]
	v_pk_mul_f32 v[214:215], v[214:215], v[62:63] op_sel_hi:[1,0]
	v_pk_mul_f32 v[216:217], v[216:217], v[62:63] op_sel_hi:[1,0]
	v_pk_mul_f32 v[218:219], v[218:219], v[62:63] op_sel_hi:[1,0]
	v_pk_mul_f32 v[220:221], v[220:221], v[62:63] op_sel_hi:[1,0]
	v_pk_mul_f32 v[222:223], v[222:223], v[62:63] op_sel_hi:[1,0]
	v_pk_mul_f32 v[224:225], v[224:225], v[62:63] op_sel_hi:[1,0]
	v_pk_mul_f32 v[226:227], v[226:227], v[62:63] op_sel_hi:[1,0]
	v_pk_mul_f32 v[212:213], v[24:25], v[212:213]
	v_pk_mul_f32 v[214:215], v[26:27], v[214:215]
	v_pk_mul_f32 v[216:217], v[28:29], v[216:217]
	v_pk_mul_f32 v[218:219], v[30:31], v[218:219]
	v_pk_mul_f32 v[220:221], v[32:33], v[220:221]
	v_pk_mul_f32 v[222:223], v[34:35], v[222:223]
	v_pk_mul_f32 v[224:225], v[36:37], v[224:225]
	v_pk_mul_f32 v[226:227], v[38:39], v[226:227]
	v_pk_fma_f32 v[212:213], v[40:41], v[212:213], v[80:81]
	v_pk_fma_f32 v[214:215], v[42:43], v[214:215], v[82:83]
	v_pk_fma_f32 v[216:217], v[64:65], v[216:217], v[84:85]
	v_pk_fma_f32 v[218:219], v[66:67], v[218:219], v[86:87]
	v_pk_fma_f32 v[220:221], v[68:69], v[220:221], v[88:89]
	v_pk_fma_f32 v[222:223], v[70:71], v[222:223], v[90:91]
	v_pk_fma_f32 v[224:225], v[72:73], v[224:225], v[92:93]
	v_pk_fma_f32 v[226:227], v[74:75], v[226:227], v[94:95]
	v_cvt_pk_bf16_f32 v212, v212, v213
	v_cvt_pk_bf16_f32 v213, v214, v215
	v_cvt_pk_bf16_f32 v214, v216, v217
	v_cvt_pk_bf16_f32 v215, v218, v219
	v_cvt_pk_bf16_f32 v220, v220, v221
	v_cvt_pk_bf16_f32 v221, v222, v223
	v_cvt_pk_bf16_f32 v222, v224, v225
	v_cvt_pk_bf16_f32 v223, v226, v227
	global_store_dwordx4 v2, v[212:215], s[10:11] sc1
	global_store_dwordx4 v2, v[220:223], s[10:11] offset:1024 sc1
	s_add_u32 s10, s10, 0x800
	s_addc_u32 s11, s11, 0
	global_load_dwordx4 v[164:167], v1, s[8:9]
	global_load_dwordx4 v[168:171], v1, s[8:9] offset:16
	global_load_dwordx4 v[172:175], v1, s[8:9] offset:2048
	global_load_dwordx4 v[176:179], v1, s[8:9] offset:2064
	s_add_u32 s8, s8, 0x1000
	s_addc_u32 s9, s9, 0
	global_load_dwordx4 v[180:183], v1, s[8:9]
	global_load_dwordx4 v[184:187], v1, s[8:9] offset:16
	global_load_dwordx4 v[188:191], v1, s[8:9] offset:2048
	global_load_dwordx4 v[192:195], v1, s[8:9] offset:2064
	s_add_u32 s8, s8, 0x1000
	s_addc_u32 s9, s9, 0
	global_load_dwordx4 v[196:199], v1, s[8:9]
	global_load_dwordx4 v[200:203], v1, s[8:9] offset:16
	global_load_dwordx4 v[204:207], v1, s[8:9] offset:2048
	global_load_dwordx4 v[208:211], v1, s[8:9] offset:2064
	s_add_u32 s8, s8, 0x1000
	s_addc_u32 s9, s9, 0
	global_load_dwordx4 v[212:215], v1, s[8:9]
	global_load_dwordx4 v[216:219], v1, s[8:9] offset:16
	global_load_dwordx4 v[220:223], v1, s[8:9] offset:2048
	global_load_dwordx4 v[224:227], v1, s[8:9] offset:2064
	s_add_u32 s8, s8, 0x1000
	s_addc_u32 s9, s9, 0
	s_waitcnt vmcnt(24)
; DI unsigned pk2(float lo, float hi) { return f2bf(lo) | (f2bf(hi) << 16); }
; DI void norm_phase(const Args& A, int wave_s, int l, int which, int rows) {
;     ...
;             float ss = 0.f;
; #pragma unroll
;             for (int j = 0; j < 4; ++j) ss += (xv[rr][j].x * xv[rr][j].x + xv[rr][j].y * xv[rr][j].y) + (xv[rr][j].z * xv[rr][j].z + xv[rr][j].w * xv[rr][j].w);
;             ss = wave_sum(C.lane, ss);
;             const float rs = rsqrtf(ss * (1.f / 1024.f) + EPS);
; #pragma unroll
;             for (int j = 0; j < 4; ++j) { const int col = 4 * (C.lane + 64 * j);
;                 const f32x4 y = xv[rr][j] * rs * g[j] * (sc[j] + 1.f) + sh[j];
;                 v2u o; o.x = pk2(y.x, y.y); o.y = pk2(y.z, y.w);
;                 *(v2u*)(C.H + (size_t)m * 1024 + col) = o; }
	v_mul_f32_e32 v10, v96, v96
	v_fmac_f32_e32 v10, v97, v97
	v_fmac_f32_e32 v10, v98, v98
	v_fmac_f32_e32 v10, v99, v99
	v_fmac_f32_e32 v10, v100, v100
	v_fmac_f32_e32 v10, v101, v101
	v_fmac_f32_e32 v10, v102, v102
	v_fmac_f32_e32 v10, v103, v103
	v_fmac_f32_e32 v10, v104, v104
	v_fmac_f32_e32 v10, v105, v105
	v_fmac_f32_e32 v10, v106, v106
	v_fmac_f32_e32 v10, v107, v107
	v_fmac_f32_e32 v10, v108, v108
	v_fmac_f32_e32 v10, v109, v109
	v_fmac_f32_e32 v10, v110, v110
	v_fmac_f32_e32 v10, v111, v111
	v_mul_f32_e32 v11, v112, v112
	v_fmac_f32_e32 v11, v113, v113
	v_fmac_f32_e32 v11, v114, v114
	v_fmac_f32_e32 v11, v115, v115
	v_fmac_f32_e32 v11, v116, v116
	v_fmac_f32_e32 v11, v117, v117
	v_fmac_f32_e32 v11, v118, v118
	v_fmac_f32_e32 v11, v119, v119
	v_fmac_f32_e32 v11, v120, v120
	v_fmac_f32_e32 v11, v121, v121
	v_fmac_f32_e32 v11, v122, v122
	v_fmac_f32_e32 v11, v123, v123
	v_fmac_f32_e32 v11, v124, v124
	v_fmac_f32_e32 v11, v125, v125
	v_fmac_f32_e32 v11, v126, v126
	v_fmac_f32_e32 v11, v127, v127
	v_mul_f32_e32 v12, v128, v128
	v_fmac_f32_e32 v12, v129, v129
	v_fmac_f32_e32 v12, v130, v130
	v_fmac_f32_e32 v12, v131, v131
	v_fmac_f32_e32 v12, v132, v132
	v_fmac_f32_e32 v12, v133, v133
	v_fmac_f32_e32 v12, v134, v134
	v_fmac_f32_e32 v12, v135, v135
	v_fmac_f32_e32 v12, v136, v136
	v_fmac_f32_e32 v12, v137, v137
	v_fmac_f32_e32 v12, v138, v138
	v_fmac_f32_e32 v12, v139, v139
	v_fmac_f32_e32 v12, v140, v140
	v_fmac_f32_e32 v12, v141, v141
	v_fmac_f32_e32 v12, v142, v142
	v_fmac_f32_e32 v12, v143, v143
	v_mul_f32_e32 v13, v144, v144
	v_fmac_f32_e32 v13, v145, v145
	v_fmac_f32_e32 v13, v146, v146
	v_fmac_f32_e32 v13, v147, v147
	v_fmac_f32_e32 v13, v148, v148
	v_fmac_f32_e32 v13, v149, v149
	v_fmac_f32_e32 v13, v150, v150
	v_fmac_f32_e32 v13, v151, v151
	v_fmac_f32_e32 v13, v152, v152
	v_fmac_f32_e32 v13, v153, v153
	v_fmac_f32_e32 v13, v154, v154
	v_fmac_f32_e32 v13, v155, v155
	v_fmac_f32_e32 v13, v156, v156
	v_fmac_f32_e32 v13, v157, v157
	v_fmac_f32_e32 v13, v158, v158
	v_fmac_f32_e32 v13, v159, v159
	ds_bpermute_b32 v14, v4, v10
	ds_bpermute_b32 v15, v4, v11
	ds_bpermute_b32 v16, v4, v12
	ds_bpermute_b32 v17, v4, v13
	s_waitcnt lgkmcnt(0)
	v_add_f32_e32 v10, v10, v14
	v_add_f32_e32 v11, v11, v15
	v_add_f32_e32 v12, v12, v16
	v_add_f32_e32 v13, v13, v17
	ds_bpermute_b32 v14, v5, v10
	ds_bpermute_b32 v15, v5, v11
	ds_bpermute_b32 v16, v5, v12
	ds_bpermute_b32 v17, v5, v13
	s_waitcnt lgkmcnt(0)
	v_add_f32_e32 v10, v10, v14
	v_add_f32_e32 v11, v11, v15
	v_add_f32_e32 v12, v12, v16
	v_add_f32_e32 v13, v13, v17
	ds_bpermute_b32 v14, v6, v10
	ds_bpermute_b32 v15, v6, v11
	ds_bpermute_b32 v16, v6, v12
	ds_bpermute_b32 v17, v6, v13
	s_waitcnt lgkmcnt(0)
	v_add_f32_e32 v10, v10, v14
	v_add_f32_e32 v11, v11, v15
	v_add_f32_e32 v12, v12, v16
	v_add_f32_e32 v13, v13, v17
	ds_bpermute_b32 v14, v7, v10
	ds_bpermute_b32 v15, v7, v11
	ds_bpermute_b32 v16, v7, v12
	ds_bpermute_b32 v17, v7, v13
	s_waitcnt lgkmcnt(0)
	v_add_f32_e32 v10, v10, v14
	v_add_f32_e32 v11, v11, v15
	v_add_f32_e32 v12, v12, v16
	v_add_f32_e32 v13, v13, v17
	ds_bpermute_b32 v14, v8, v10
	ds_bpermute_b32 v15, v8, v11
	ds_bpermute_b32 v16, v8, v12
	ds_bpermute_b32 v17, v8, v13
	s_waitcnt lgkmcnt(0)
	v_add_f32_e32 v10, v10, v14
	v_add_f32_e32 v11, v11, v15
	v_add_f32_e32 v12, v12, v16
	v_add_f32_e32 v13, v13, v17
	ds_bpermute_b32 v14, v9, v10
	ds_bpermute_b32 v15, v9, v11
	ds_bpermute_b32 v16, v9, v12
	ds_bpermute_b32 v17, v9, v13
	s_waitcnt lgkmcnt(0)
	v_add_f32_e32 v10, v10, v14
	v_add_f32_e32 v11, v11, v15
	v_add_f32_e32 v12, v12, v16
	v_add_f32_e32 v13, v13, v17
	v_fma_f32 v10, v10, s32, v60
	v_fma_f32 v11, v11, s32, v60
	v_fma_f32 v12, v12, s32, v60
	v_fma_f32 v13, v13, s32, v60
	v_rsq_f32_e32 v18, v10
	v_rsq_f32_e32 v20, v11
	v_rsq_f32_e32 v22, v12
	v_rsq_f32_e32 v62, v13
	s_nop 0
	v_pk_mul_f32 v[96:97], v[96:97], v[18:19] op_sel_hi:[1,0]
	v_pk_mul_f32 v[98:99], v[98:99], v[18:19] op_sel_hi:[1,0]
	v_pk_mul_f32 v[100:101], v[100:101], v[18:19] op_sel_hi:[1,0]
	v_pk_mul_f32 v[102:103], v[102:103], v[18:19] op_sel_hi:[1,0]
	v_pk_mul_f32 v[104:105], v[104:105], v[18:19] op_sel_hi:[1,0]
	v_pk_mul_f32 v[106:107], v[106:107], v[18:19] op_sel_hi:[1,0]
	v_pk_mul_f32 v[108:109], v[108:109], v[18:19] op_sel_hi:[1,0]
	v_pk_mul_f32 v[110:111], v[110:111], v[18:19] op_sel_hi:[1,0]
	v_pk_mul_f32 v[96:97], v[24:25], v[96:97]
	v_pk_mul_f32 v[98:99], v[26:27], v[98:99]
	v_pk_mul_f32 v[100:101], v[28:29], v[100:101]
	v_pk_mul_f32 v[102:103], v[30:31], v[102:103]
	v_pk_mul_f32 v[104:105], v[32:33], v[104:105]
	v_pk_mul_f32 v[106:107], v[34:35], v[106:107]
	v_pk_mul_f32 v[108:109], v[36:37], v[108:109]
	v_pk_mul_f32 v[110:111], v[38:39], v[110:111]
	v_pk_fma_f32 v[96:97], v[40:41], v[96:97], v[80:81]
	v_pk_fma_f32 v[98:99], v[42:43], v[98:99], v[82:83]
	v_pk_fma_f32 v[100:101], v[64:65], v[100:101], v[84:85]
	v_pk_fma_f32 v[102:103], v[66:67], v[102:103], v[86:87]
	v_pk_fma_f32 v[104:105], v[68:69], v[104:105], v[88:89]
	v_pk_fma_f32 v[106:107], v[70:71], v[106:107], v[90:91]
	v_pk_fma_f32 v[108:109], v[72:73], v[108:109], v[92:93]
	v_pk_fma_f32 v[110:111], v[74:75], v[110:111], v[94:95]
	v_cvt_pk_bf16_f32 v96, v96, v97
	v_cvt_pk_bf16_f32 v97, v98, v99
	v_cvt_pk_bf16_f32 v98, v100, v101
	v_cvt_pk_bf16_f32 v99, v102, v103
	v_cvt_pk_bf16_f32 v104, v104, v105
	v_cvt_pk_bf16_f32 v105, v106, v107
	v_cvt_pk_bf16_f32 v106, v108, v109
	v_cvt_pk_bf16_f32 v107, v110, v111
	global_store_dwordx4 v2, v[96:99], s[10:11] sc1
	global_store_dwordx4 v2, v[104:107], s[10:11] offset:1024 sc1
	s_add_u32 s10, s10, 0x800
	s_addc_u32 s11, s11, 0
	v_pk_mul_f32 v[112:113], v[112:113], v[20:21] op_sel_hi:[1,0]
; DI unsigned pk2(float lo, float hi) { return f2bf(lo) | (f2bf(hi) << 16); }
; DI void norm_phase(const Args& A, int wave_s, int l, int which, int rows) {
;     ...
;             else { xr = (from_in ? C.ctx : C.XC) + (size_t)(m - NLAT) * 1024; v = 4; }
;             modp[rr] = C.SM + SM_MOD + (l * 5 + v) * 6144 + (which == 1 ? 0 : 3072);
; #pragma unroll
;             for (int j = 0; j < 4; ++j) xv[rr][j] = ((const f32x4*)xr)[C.lane + 64 * j];
;         }
; #pragma unroll
;         for (int rr = 0; rr < 2; ++rr) {
;             const int m = m0 + rr;
;             f32x4 sh[4], sc[4];
; #pragma unroll
;             for (int j = 0; j < 4; ++j) { const int col = 4 * (C.lane + 64 * j); sh[j] = *(const f32x4*)(modp[rr] + col); sc[j] = *(const f32x4*)(modp[rr] + 1024 + col); }
;             float ss = 0.f;
; #pragma unroll
;             for (int j = 0; j < 4; ++j) ss += (xv[rr][j].x * xv[rr][j].x + xv[rr][j].y * xv[rr][j].y) + (xv[rr][j].z * xv[rr][j].z + xv[rr][j].w * xv[rr][j].w);
;             ss = wave_sum(C.lane, ss);
;             const float rs = rsqrtf(ss * (1.f / 1024.f) + EPS);
; #pragma unroll
;             for (int j = 0; j < 4; ++j) { const int col = 4 * (C.lane + 64 * j);
;                 const f32x4 y = xv[rr][j] * rs * g[j] * (sc[j] + 1.f) + sh[j];
;                 v2u o; o.x = pk2(y.x, y.y); o.y = pk2(y.z, y.w);
;                 *(v2u*)(C.H + (size_t)m * 1024 + col) = o; }
	v_pk_mul_f32 v[114:115], v[114:115], v[20:21] op_sel_hi:[1,0]
	v_pk_mul_f32 v[116:117], v[116:117], v[20:21] op_sel_hi:[1,0]
	v_pk_mul_f32 v[118:119], v[118:119], v[20:21] op_sel_hi:[1,0]
	v_pk_mul_f32 v[120:121], v[120:121], v[20:21] op_sel_hi:[1,0]
	v_pk_mul_f32 v[122:123], v[122:123], v[20:21] op_sel_hi:[1,0]
	v_pk_mul_f32 v[124:125], v[124:125], v[20:21] op_sel_hi:[1,0]
	v_pk_mul_f32 v[126:127], v[126:127], v[20:21] op_sel_hi:[1,0]
	v_pk_mul_f32 v[112:113], v[24:25], v[112:113]
	v_pk_mul_f32 v[114:115], v[26:27], v[114:115]
	v_pk_mul_f32 v[116:117], v[28:29], v[116:117]
	v_pk_mul_f32 v[118:119], v[30:31], v[118:119]
	v_pk_mul_f32 v[120:121], v[32:33], v[120:121]
	v_pk_mul_f32 v[122:123], v[34:35], v[122:123]
	v_pk_mul_f32 v[124:125], v[36:37], v[124:125]
	v_pk_mul_f32 v[126:127], v[38:39], v[126:127]
	v_pk_fma_f32 v[112:113], v[40:41], v[112:113], v[80:81]
	v_pk_fma_f32 v[114:115], v[42:43], v[114:115], v[82:83]
	v_pk_fma_f32 v[116:117], v[64:65], v[116:117], v[84:85]
	v_pk_fma_f32 v[118:119], v[66:67], v[118:119], v[86:87]
	v_pk_fma_f32 v[120:121], v[68:69], v[120:121], v[88:89]
	v_pk_fma_f32 v[122:123], v[70:71], v[122:123], v[90:91]
	v_pk_fma_f32 v[124:125], v[72:73], v[124:125], v[92:93]
	v_pk_fma_f32 v[126:127], v[74:75], v[126:127], v[94:95]
	v_cvt_pk_bf16_f32 v112, v112, v113
	v_cvt_pk_bf16_f32 v113, v114, v115
	v_cvt_pk_bf16_f32 v114, v116, v117
	v_cvt_pk_bf16_f32 v115, v118, v119
	v_cvt_pk_bf16_f32 v120, v120, v121
	v_cvt_pk_bf16_f32 v121, v122, v123
	v_cvt_pk_bf16_f32 v122, v124, v125
	v_cvt_pk_bf16_f32 v123, v126, v127
	global_store_dwordx4 v2, v[112:115], s[10:11] sc1
	global_store_dwordx4 v2, v[120:123], s[10:11] offset:1024 sc1
	s_add_u32 s10, s10, 0x800
	s_addc_u32 s11, s11, 0
	v_pk_mul_f32 v[128:129], v[128:129], v[22:23] op_sel_hi:[1,0]
	v_pk_mul_f32 v[130:131], v[130:131], v[22:23] op_sel_hi:[1,0]
	v_pk_mul_f32 v[132:133], v[132:133], v[22:23] op_sel_hi:[1,0]
	v_pk_mul_f32 v[134:135], v[134:135], v[22:23] op_sel_hi:[1,0]
	v_pk_mul_f32 v[136:137], v[136:137], v[22:23] op_sel_hi:[1,0]
	v_pk_mul_f32 v[138:139], v[138:139], v[22:23] op_sel_hi:[1,0]
	v_pk_mul_f32 v[140:141], v[140:141], v[22:23] op_sel_hi:[1,0]
	v_pk_mul_f32 v[142:143], v[142:143], v[22:23] op_sel_hi:[1,0]
	v_pk_mul_f32 v[128:129], v[24:25], v[128:129]
	v_pk_mul_f32 v[130:131], v[26:27], v[130:131]
	v_pk_mul_f32 v[132:133], v[28:29], v[132:133]
	v_pk_mul_f32 v[134:135], v[30:31], v[134:135]
	v_pk_mul_f32 v[136:137], v[32:33], v[136:137]
	v_pk_mul_f32 v[138:139], v[34:35], v[138:139]
	v_pk_mul_f32 v[140:141], v[36:37], v[140:141]
	v_pk_mul_f32 v[142:143], v[38:39], v[142:143]
	v_pk_fma_f32 v[128:129], v[40:41], v[128:129], v[80:81]
	v_pk_fma_f32 v[130:131], v[42:43], v[130:131], v[82:83]
	v_pk_fma_f32 v[132:133], v[64:65], v[132:133], v[84:85]
	v_pk_fma_f32 v[134:135], v[66:67], v[134:135], v[86:87]
	v_pk_fma_f32 v[136:137], v[68:69], v[136:137], v[88:89]
	v_pk_fma_f32 v[138:139], v[70:71], v[138:139], v[90:91]
	v_pk_fma_f32 v[140:141], v[72:73], v[140:141], v[92:93]
	v_pk_fma_f32 v[142:143], v[74:75], v[142:143], v[94:95]
	v_cvt_pk_bf16_f32 v128, v128, v129
	v_cvt_pk_bf16_f32 v129, v130, v131
	v_cvt_pk_bf16_f32 v130, v132, v133
	v_cvt_pk_bf16_f32 v131, v134, v135
	v_cvt_pk_bf16_f32 v136, v136, v137
	v_cvt_pk_bf16_f32 v137, v138, v139
	v_cvt_pk_bf16_f32 v138, v140, v141
	v_cvt_pk_bf16_f32 v139, v142, v143
	global_store_dwordx4 v2, v[128:131], s[10:11] sc1
	global_store_dwordx4 v2, v[136:139], s[10:11] offset:1024 sc1
	s_add_u32 s10, s10, 0x800
	s_addc_u32 s11, s11, 0
	v_pk_mul_f32 v[144:145], v[144:145], v[62:63] op_sel_hi:[1,0]
	v_pk_mul_f32 v[146:147], v[146:147], v[62:63] op_sel_hi:[1,0]
	v_pk_mul_f32 v[148:149], v[148:149], v[62:63] op_sel_hi:[1,0]
	v_pk_mul_f32 v[150:151], v[150:151], v[62:63] op_sel_hi:[1,0]
	v_pk_mul_f32 v[152:153], v[152:153], v[62:63] op_sel_hi:[1,0]
	v_pk_mul_f32 v[154:155], v[154:155], v[62:63] op_sel_hi:[1,0]
	v_pk_mul_f32 v[156:157], v[156:157], v[62:63] op_sel_hi:[1,0]
	v_pk_mul_f32 v[158:159], v[158:159], v[62:63] op_sel_hi:[1,0]
	v_pk_mul_f32 v[144:145], v[24:25], v[144:145]
	v_pk_mul_f32 v[146:147], v[26:27], v[146:147]
	v_pk_mul_f32 v[148:149], v[28:29], v[148:149]
	v_pk_mul_f32 v[150:151], v[30:31], v[150:151]
	v_pk_mul_f32 v[152:153], v[32:33], v[152:153]
	v_pk_mul_f32 v[154:155], v[34:35], v[154:155]
	v_pk_mul_f32 v[156:157], v[36:37], v[156:157]
	v_pk_mul_f32 v[158:159], v[38:39], v[158:159]
	v_pk_fma_f32 v[144:145], v[40:41], v[144:145], v[80:81]
	v_pk_fma_f32 v[146:147], v[42:43], v[146:147], v[82:83]
	v_pk_fma_f32 v[148:149], v[64:65], v[148:149], v[84:85]
	v_pk_fma_f32 v[150:151], v[66:67], v[150:151], v[86:87]
	v_pk_fma_f32 v[152:153], v[68:69], v[152:153], v[88:89]
	v_pk_fma_f32 v[154:155], v[70:71], v[154:155], v[90:91]
	v_pk_fma_f32 v[156:157], v[72:73], v[156:157], v[92:93]
	v_pk_fma_f32 v[158:159], v[74:75], v[158:159], v[94:95]
	v_cvt_pk_bf16_f32 v144, v144, v145
	v_cvt_pk_bf16_f32 v145, v146, v147
	v_cvt_pk_bf16_f32 v146, v148, v149
	v_cvt_pk_bf16_f32 v147, v150, v151
	v_cvt_pk_bf16_f32 v152, v152, v153
	v_cvt_pk_bf16_f32 v153, v154, v155
	v_cvt_pk_bf16_f32 v154, v156, v157
	v_cvt_pk_bf16_f32 v155, v158, v159
	global_store_dwordx4 v2, v[144:147], s[10:11] sc1
	global_store_dwordx4 v2, v[152:155], s[10:11] offset:1024 sc1
	s_add_u32 s10, s10, 0x800
	s_addc_u32 s11, s11, 0
	s_mul_i32 s5, s6, 5
	s_add_u32 s5, s5, 4
	s_mul_i32 s5, s5, 0x6000
	s_add_u32 s24, s88, 0x100000
	s_addc_u32 s25, s89, 0
	s_add_u32 s24, s24, s5
	s_addc_u32 s25, s25, 0
	s_add_u32 s26, s24, 0x1000
	s_addc_u32 s27, s25, 0
	global_load_dwordx4 v[96:99], v1, s[30:31]
	global_load_dwordx4 v[100:103], v1, s[30:31] offset:16
	global_load_dwordx4 v[104:107], v1, s[30:31] offset:2048
	global_load_dwordx4 v[108:111], v1, s[30:31] offset:2064
	global_load_dwordx4 v[112:115], v1, s[26:27]
	global_load_dwordx4 v[116:119], v1, s[26:27] offset:16
	global_load_dwordx4 v[120:123], v1, s[26:27] offset:2048
	global_load_dwordx4 v[124:127], v1, s[26:27] offset:2064
	global_load_dwordx4 v[128:131], v1, s[24:25]
	global_load_dwordx4 v[132:135], v1, s[24:25] offset:16
	global_load_dwordx4 v[136:139], v1, s[24:25] offset:2048
	global_load_dwordx4 v[140:143], v1, s[24:25] offset:2064
	s_waitcnt vmcnt(20)
; DI unsigned pk2(float lo, float hi) { return f2bf(lo) | (f2bf(hi) << 16); }
; DI void norm_phase(const Args& A, int wave_s, int l, int which, int rows) {
;     ...
;             float ss = 0.f;
; #pragma unroll
;             for (int j = 0; j < 4; ++j) ss += (xv[rr][j].x * xv[rr][j].x + xv[rr][j].y * xv[rr][j].y) + (xv[rr][j].z * xv[rr][j].z + xv[rr][j].w * xv[rr][j].w);
;             ss = wave_sum(C.lane, ss);
;             const float rs = rsqrtf(ss * (1.f / 1024.f) + EPS);
; #pragma unroll
;             for (int j = 0; j < 4; ++j) { const int col = 4 * (C.lane + 64 * j);
;                 const f32x4 y = xv[rr][j] * rs * g[j] * (sc[j] + 1.f) + sh[j];
;                 v2u o; o.x = pk2(y.x, y.y); o.y = pk2(y.z, y.w);
;                 *(v2u*)(C.H + (size_t)m * 1024 + col) = o; }
	v_mul_f32_e32 v10, v164, v164
	v_fmac_f32_e32 v10, v165, v165
	v_fmac_f32_e32 v10, v166, v166
	v_fmac_f32_e32 v10, v167, v167
	v_fmac_f32_e32 v10, v168, v168
	v_fmac_f32_e32 v10, v169, v169
	v_fmac_f32_e32 v10, v170, v170
	v_fmac_f32_e32 v10, v171, v171
	v_fmac_f32_e32 v10, v172, v172
	v_fmac_f32_e32 v10, v173, v173
	v_fmac_f32_e32 v10, v174, v174
	v_fmac_f32_e32 v10, v175, v175
	v_fmac_f32_e32 v10, v176, v176
	v_fmac_f32_e32 v10, v177, v177
	v_fmac_f32_e32 v10, v178, v178
	v_fmac_f32_e32 v10, v179, v179
	v_mul_f32_e32 v11, v180, v180
	v_fmac_f32_e32 v11, v181, v181
	v_fmac_f32_e32 v11, v182, v182
	v_fmac_f32_e32 v11, v183, v183
	v_fmac_f32_e32 v11, v184, v184
	v_fmac_f32_e32 v11, v185, v185
	v_fmac_f32_e32 v11, v186, v186
	v_fmac_f32_e32 v11, v187, v187
	v_fmac_f32_e32 v11, v188, v188
	v_fmac_f32_e32 v11, v189, v189
	v_fmac_f32_e32 v11, v190, v190
	v_fmac_f32_e32 v11, v191, v191
	v_fmac_f32_e32 v11, v192, v192
	v_fmac_f32_e32 v11, v193, v193
	v_fmac_f32_e32 v11, v194, v194
	v_fmac_f32_e32 v11, v195, v195
	v_mul_f32_e32 v12, v196, v196
	v_fmac_f32_e32 v12, v197, v197
	v_fmac_f32_e32 v12, v198, v198
	v_fmac_f32_e32 v12, v199, v199
	v_fmac_f32_e32 v12, v200, v200
	v_fmac_f32_e32 v12, v201, v201
	v_fmac_f32_e32 v12, v202, v202
	v_fmac_f32_e32 v12, v203, v203
	v_fmac_f32_e32 v12, v204, v204
	v_fmac_f32_e32 v12, v205, v205
	v_fmac_f32_e32 v12, v206, v206
	v_fmac_f32_e32 v12, v207, v207
	v_fmac_f32_e32 v12, v208, v208
	v_fmac_f32_e32 v12, v209, v209
	v_fmac_f32_e32 v12, v210, v210
	v_fmac_f32_e32 v12, v211, v211
	v_mul_f32_e32 v13, v212, v212
	v_fmac_f32_e32 v13, v213, v213
	v_fmac_f32_e32 v13, v214, v214
	v_fmac_f32_e32 v13, v215, v215
	v_fmac_f32_e32 v13, v216, v216
	v_fmac_f32_e32 v13, v217, v217
	v_fmac_f32_e32 v13, v218, v218
	v_fmac_f32_e32 v13, v219, v219
	v_fmac_f32_e32 v13, v220, v220
	v_fmac_f32_e32 v13, v221, v221
	v_fmac_f32_e32 v13, v222, v222
	v_fmac_f32_e32 v13, v223, v223
	v_fmac_f32_e32 v13, v224, v224
	v_fmac_f32_e32 v13, v225, v225
	v_fmac_f32_e32 v13, v226, v226
	v_fmac_f32_e32 v13, v227, v227
	ds_bpermute_b32 v14, v4, v10
	ds_bpermute_b32 v15, v4, v11
	ds_bpermute_b32 v16, v4, v12
	ds_bpermute_b32 v17, v4, v13
	s_waitcnt lgkmcnt(0)
	v_add_f32_e32 v10, v10, v14
	v_add_f32_e32 v11, v11, v15
	v_add_f32_e32 v12, v12, v16
	v_add_f32_e32 v13, v13, v17
	ds_bpermute_b32 v14, v5, v10
	ds_bpermute_b32 v15, v5, v11
	ds_bpermute_b32 v16, v5, v12
	ds_bpermute_b32 v17, v5, v13
	s_waitcnt lgkmcnt(0)
	v_add_f32_e32 v10, v10, v14
	v_add_f32_e32 v11, v11, v15
	v_add_f32_e32 v12, v12, v16
	v_add_f32_e32 v13, v13, v17
	ds_bpermute_b32 v14, v6, v10
	ds_bpermute_b32 v15, v6, v11
	ds_bpermute_b32 v16, v6, v12
	ds_bpermute_b32 v17, v6, v13
	s_waitcnt lgkmcnt(0)
	v_add_f32_e32 v10, v10, v14
	v_add_f32_e32 v11, v11, v15
	v_add_f32_e32 v12, v12, v16
	v_add_f32_e32 v13, v13, v17
	ds_bpermute_b32 v14, v7, v10
	ds_bpermute_b32 v15, v7, v11
	ds_bpermute_b32 v16, v7, v12
	ds_bpermute_b32 v17, v7, v13
	s_waitcnt lgkmcnt(0)
	v_add_f32_e32 v10, v10, v14
	v_add_f32_e32 v11, v11, v15
	v_add_f32_e32 v12, v12, v16
	v_add_f32_e32 v13, v13, v17
	ds_bpermute_b32 v14, v8, v10
	ds_bpermute_b32 v15, v8, v11
	ds_bpermute_b32 v16, v8, v12
	ds_bpermute_b32 v17, v8, v13
	s_waitcnt lgkmcnt(0)
	v_add_f32_e32 v10, v10, v14
	v_add_f32_e32 v11, v11, v15
	v_add_f32_e32 v12, v12, v16
	v_add_f32_e32 v13, v13, v17
	ds_bpermute_b32 v14, v9, v10
	ds_bpermute_b32 v15, v9, v11
	ds_bpermute_b32 v16, v9, v12
	ds_bpermute_b32 v17, v9, v13
	s_waitcnt lgkmcnt(0)
	v_add_f32_e32 v10, v10, v14
	v_add_f32_e32 v11, v11, v15
	v_add_f32_e32 v12, v12, v16
	v_add_f32_e32 v13, v13, v17
	v_fma_f32 v10, v10, s32, v60
	v_fma_f32 v11, v11, s32, v60
	v_fma_f32 v12, v12, s32, v60
	v_fma_f32 v13, v13, s32, v60
	v_rsq_f32_e32 v18, v10
	v_rsq_f32_e32 v20, v11
	v_rsq_f32_e32 v22, v12
	v_rsq_f32_e32 v62, v13
	s_nop 0
	v_pk_mul_f32 v[164:165], v[164:165], v[18:19] op_sel_hi:[1,0]
	v_pk_mul_f32 v[166:167], v[166:167], v[18:19] op_sel_hi:[1,0]
	v_pk_mul_f32 v[168:169], v[168:169], v[18:19] op_sel_hi:[1,0]
	v_pk_mul_f32 v[170:171], v[170:171], v[18:19] op_sel_hi:[1,0]
	v_pk_mul_f32 v[172:173], v[172:173], v[18:19] op_sel_hi:[1,0]
	v_pk_mul_f32 v[174:175], v[174:175], v[18:19] op_sel_hi:[1,0]
	v_pk_mul_f32 v[176:177], v[176:177], v[18:19] op_sel_hi:[1,0]
	v_pk_mul_f32 v[178:179], v[178:179], v[18:19] op_sel_hi:[1,0]
	v_pk_mul_f32 v[164:165], v[24:25], v[164:165]
	v_pk_mul_f32 v[166:167], v[26:27], v[166:167]
	v_pk_mul_f32 v[168:169], v[28:29], v[168:169]
	v_pk_mul_f32 v[170:171], v[30:31], v[170:171]
	v_pk_mul_f32 v[172:173], v[32:33], v[172:173]
	v_pk_mul_f32 v[174:175], v[34:35], v[174:175]
	v_pk_mul_f32 v[176:177], v[36:37], v[176:177]
	v_pk_mul_f32 v[178:179], v[38:39], v[178:179]
	v_pk_fma_f32 v[164:165], v[40:41], v[164:165], v[80:81]
	v_pk_fma_f32 v[166:167], v[42:43], v[166:167], v[82:83]
	v_pk_fma_f32 v[168:169], v[64:65], v[168:169], v[84:85]
	v_pk_fma_f32 v[170:171], v[66:67], v[170:171], v[86:87]
	v_pk_fma_f32 v[172:173], v[68:69], v[172:173], v[88:89]
	v_pk_fma_f32 v[174:175], v[70:71], v[174:175], v[90:91]
	v_pk_fma_f32 v[176:177], v[72:73], v[176:177], v[92:93]
	v_pk_fma_f32 v[178:179], v[74:75], v[178:179], v[94:95]
	v_cvt_pk_bf16_f32 v164, v164, v165
	v_cvt_pk_bf16_f32 v165, v166, v167
	v_cvt_pk_bf16_f32 v166, v168, v169
	v_cvt_pk_bf16_f32 v167, v170, v171
	v_cvt_pk_bf16_f32 v172, v172, v173
	v_cvt_pk_bf16_f32 v173, v174, v175
	v_cvt_pk_bf16_f32 v174, v176, v177
	v_cvt_pk_bf16_f32 v175, v178, v179
	global_store_dwordx4 v2, v[164:167], s[10:11] sc1
	global_store_dwordx4 v2, v[172:175], s[10:11] offset:1024 sc1
	s_add_u32 s10, s10, 0x800
	s_addc_u32 s11, s11, 0
	v_pk_mul_f32 v[180:181], v[180:181], v[20:21] op_sel_hi:[1,0]
; DI unsigned pk2(float lo, float hi) { return f2bf(lo) | (f2bf(hi) << 16); }
; DI void norm_phase(const Args& A, int wave_s, int l, int which, int rows) {
;     ...
;             if (m < NLAT) { xr = (from_in ? C.x : C.out) + (size_t)m * 1024; v = m >> 13; }
;             else { xr = (from_in ? C.ctx : C.XC) + (size_t)(m - NLAT) * 1024; v = 4; }
;             modp[rr] = C.SM + SM_MOD + (l * 5 + v) * 6144 + (which == 1 ? 0 : 3072);
;     ...
;             for (int j = 0; j < 4; ++j) { const int col = 4 * (C.lane + 64 * j);
;                 const f32x4 y = xv[rr][j] * rs * g[j] * (sc[j] + 1.f) + sh[j];
;                 v2u o; o.x = pk2(y.x, y.y); o.y = pk2(y.z, y.w);
;                 *(v2u*)(C.H + (size_t)m * 1024 + col) = o; }
	v_pk_mul_f32 v[182:183], v[182:183], v[20:21] op_sel_hi:[1,0]
	v_pk_mul_f32 v[184:185], v[184:185], v[20:21] op_sel_hi:[1,0]
	v_pk_mul_f32 v[186:187], v[186:187], v[20:21] op_sel_hi:[1,0]
	v_pk_mul_f32 v[188:189], v[188:189], v[20:21] op_sel_hi:[1,0]
	v_pk_mul_f32 v[190:191], v[190:191], v[20:21] op_sel_hi:[1,0]
	v_pk_mul_f32 v[192:193], v[192:193], v[20:21] op_sel_hi:[1,0]
	v_pk_mul_f32 v[194:195], v[194:195], v[20:21] op_sel_hi:[1,0]
	v_pk_mul_f32 v[180:181], v[24:25], v[180:181]
	v_pk_mul_f32 v[182:183], v[26:27], v[182:183]
	v_pk_mul_f32 v[184:185], v[28:29], v[184:185]
	v_pk_mul_f32 v[186:187], v[30:31], v[186:187]
	v_pk_mul_f32 v[188:189], v[32:33], v[188:189]
	v_pk_mul_f32 v[190:191], v[34:35], v[190:191]
	v_pk_mul_f32 v[192:193], v[36:37], v[192:193]
	v_pk_mul_f32 v[194:195], v[38:39], v[194:195]
	v_pk_fma_f32 v[180:181], v[40:41], v[180:181], v[80:81]
	v_pk_fma_f32 v[182:183], v[42:43], v[182:183], v[82:83]
	v_pk_fma_f32 v[184:185], v[64:65], v[184:185], v[84:85]
	v_pk_fma_f32 v[186:187], v[66:67], v[186:187], v[86:87]
	v_pk_fma_f32 v[188:189], v[68:69], v[188:189], v[88:89]
	v_pk_fma_f32 v[190:191], v[70:71], v[190:191], v[90:91]
	v_pk_fma_f32 v[192:193], v[72:73], v[192:193], v[92:93]
	v_pk_fma_f32 v[194:195], v[74:75], v[194:195], v[94:95]
	v_cvt_pk_bf16_f32 v180, v180, v181
	v_cvt_pk_bf16_f32 v181, v182, v183
	v_cvt_pk_bf16_f32 v182, v184, v185
	v_cvt_pk_bf16_f32 v183, v186, v187
	v_cvt_pk_bf16_f32 v188, v188, v189
	v_cvt_pk_bf16_f32 v189, v190, v191
	v_cvt_pk_bf16_f32 v190, v192, v193
	v_cvt_pk_bf16_f32 v191, v194, v195
	global_store_dwordx4 v2, v[180:183], s[10:11] sc1
	global_store_dwordx4 v2, v[188:191], s[10:11] offset:1024 sc1
	s_add_u32 s10, s10, 0x800
	s_addc_u32 s11, s11, 0
	v_pk_mul_f32 v[196:197], v[196:197], v[22:23] op_sel_hi:[1,0]
	v_pk_mul_f32 v[198:199], v[198:199], v[22:23] op_sel_hi:[1,0]
	v_pk_mul_f32 v[200:201], v[200:201], v[22:23] op_sel_hi:[1,0]
	v_pk_mul_f32 v[202:203], v[202:203], v[22:23] op_sel_hi:[1,0]
	v_pk_mul_f32 v[204:205], v[204:205], v[22:23] op_sel_hi:[1,0]
	v_pk_mul_f32 v[206:207], v[206:207], v[22:23] op_sel_hi:[1,0]
	v_pk_mul_f32 v[208:209], v[208:209], v[22:23] op_sel_hi:[1,0]
	v_pk_mul_f32 v[210:211], v[210:211], v[22:23] op_sel_hi:[1,0]
	v_pk_mul_f32 v[196:197], v[24:25], v[196:197]
	v_pk_mul_f32 v[198:199], v[26:27], v[198:199]
	v_pk_mul_f32 v[200:201], v[28:29], v[200:201]
	v_pk_mul_f32 v[202:203], v[30:31], v[202:203]
	v_pk_mul_f32 v[204:205], v[32:33], v[204:205]
	v_pk_mul_f32 v[206:207], v[34:35], v[206:207]
	v_pk_mul_f32 v[208:209], v[36:37], v[208:209]
	v_pk_mul_f32 v[210:211], v[38:39], v[210:211]
	v_pk_fma_f32 v[196:197], v[40:41], v[196:197], v[80:81]
	v_pk_fma_f32 v[198:199], v[42:43], v[198:199], v[82:83]
	v_pk_fma_f32 v[200:201], v[64:65], v[200:201], v[84:85]
	v_pk_fma_f32 v[202:203], v[66:67], v[202:203], v[86:87]
	v_pk_fma_f32 v[204:205], v[68:69], v[204:205], v[88:89]
	v_pk_fma_f32 v[206:207], v[70:71], v[206:207], v[90:91]
	v_pk_fma_f32 v[208:209], v[72:73], v[208:209], v[92:93]
	v_pk_fma_f32 v[210:211], v[74:75], v[210:211], v[94:95]
	v_cvt_pk_bf16_f32 v196, v196, v197
	v_cvt_pk_bf16_f32 v197, v198, v199
	v_cvt_pk_bf16_f32 v198, v200, v201
	v_cvt_pk_bf16_f32 v199, v202, v203
	v_cvt_pk_bf16_f32 v204, v204, v205
	v_cvt_pk_bf16_f32 v205, v206, v207
	v_cvt_pk_bf16_f32 v206, v208, v209
	v_cvt_pk_bf16_f32 v207, v210, v211
	global_store_dwordx4 v2, v[196:199], s[10:11] sc1
	global_store_dwordx4 v2, v[204:207], s[10:11] offset:1024 sc1
	s_add_u32 s10, s10, 0x800
	s_addc_u32 s11, s11, 0
	v_pk_mul_f32 v[212:213], v[212:213], v[62:63] op_sel_hi:[1,0]
	v_pk_mul_f32 v[214:215], v[214:215], v[62:63] op_sel_hi:[1,0]
	v_pk_mul_f32 v[216:217], v[216:217], v[62:63] op_sel_hi:[1,0]
	v_pk_mul_f32 v[218:219], v[218:219], v[62:63] op_sel_hi:[1,0]
	v_pk_mul_f32 v[220:221], v[220:221], v[62:63] op_sel_hi:[1,0]
	v_pk_mul_f32 v[222:223], v[222:223], v[62:63] op_sel_hi:[1,0]
	v_pk_mul_f32 v[224:225], v[224:225], v[62:63] op_sel_hi:[1,0]
	v_pk_mul_f32 v[226:227], v[226:227], v[62:63] op_sel_hi:[1,0]
	v_pk_mul_f32 v[212:213], v[24:25], v[212:213]
	v_pk_mul_f32 v[214:215], v[26:27], v[214:215]
	v_pk_mul_f32 v[216:217], v[28:29], v[216:217]
	v_pk_mul_f32 v[218:219], v[30:31], v[218:219]
	v_pk_mul_f32 v[220:221], v[32:33], v[220:221]
	v_pk_mul_f32 v[222:223], v[34:35], v[222:223]
	v_pk_mul_f32 v[224:225], v[36:37], v[224:225]
	v_pk_mul_f32 v[226:227], v[38:39], v[226:227]
	v_pk_fma_f32 v[212:213], v[40:41], v[212:213], v[80:81]
	v_pk_fma_f32 v[214:215], v[42:43], v[214:215], v[82:83]
	v_pk_fma_f32 v[216:217], v[64:65], v[216:217], v[84:85]
	v_pk_fma_f32 v[218:219], v[66:67], v[218:219], v[86:87]
	v_pk_fma_f32 v[220:221], v[68:69], v[220:221], v[88:89]
	v_pk_fma_f32 v[222:223], v[70:71], v[222:223], v[90:91]
	v_pk_fma_f32 v[224:225], v[72:73], v[224:225], v[92:93]
	v_pk_fma_f32 v[226:227], v[74:75], v[226:227], v[94:95]
	v_cvt_pk_bf16_f32 v212, v212, v213
	v_cvt_pk_bf16_f32 v213, v214, v215
	v_cvt_pk_bf16_f32 v214, v216, v217
	v_cvt_pk_bf16_f32 v215, v218, v219
	v_cvt_pk_bf16_f32 v220, v220, v221
	v_cvt_pk_bf16_f32 v221, v222, v223
	v_cvt_pk_bf16_f32 v222, v224, v225
	v_cvt_pk_bf16_f32 v223, v226, v227
	global_store_dwordx4 v2, v[212:215], s[10:11] sc1
	global_store_dwordx4 v2, v[220:223], s[10:11] offset:1024 sc1
	s_add_u32 s10, s10, 0x800
	s_addc_u32 s11, s11, 0
	s_add_u32 s10, s88, 0x3800000
	s_addc_u32 s11, s89, 0
	s_add_u32 s10, s10, 0x4000000
	s_addc_u32 s11, s11, 0
	s_lshl_b32 s5, s7, 11
	s_add_u32 s10, s10, s5
	s_addc_u32 s11, s11, 0
	s_waitcnt vmcnt(8)
	v_pk_add_f32 v[112:113], v[112:113], 1.0 op_sel_hi:[1,0]
	v_pk_add_f32 v[114:115], v[114:115], 1.0 op_sel_hi:[1,0]
	v_pk_add_f32 v[116:117], v[116:117], 1.0 op_sel_hi:[1,0]
	v_pk_add_f32 v[118:119], v[118:119], 1.0 op_sel_hi:[1,0]
	v_pk_add_f32 v[120:121], v[120:121], 1.0 op_sel_hi:[1,0]
	v_pk_add_f32 v[122:123], v[122:123], 1.0 op_sel_hi:[1,0]
	v_pk_add_f32 v[124:125], v[124:125], 1.0 op_sel_hi:[1,0]
	v_pk_add_f32 v[126:127], v[126:127], 1.0 op_sel_hi:[1,0]
	s_cmp_eq_u32 s2, 0
	s_cbranch_scc1 .Lnorm_n1_done
; DI unsigned pk2(float lo, float hi) { return f2bf(lo) | (f2bf(hi) << 16); }
; DI void norm_phase(const Args& A, int wave_s, int l, int which, int rows) {
;     ...
;             float ss = 0.f;
; #pragma unroll
;             for (int j = 0; j < 4; ++j) ss += (xv[rr][j].x * xv[rr][j].x + xv[rr][j].y * xv[rr][j].y) + (xv[rr][j].z * xv[rr][j].z + xv[rr][j].w * xv[rr][j].w);
;             ss = wave_sum(C.lane, ss);
;             const float rs = rsqrtf(ss * (1.f / 1024.f) + EPS);
; #pragma unroll
;             for (int j = 0; j < 4; ++j) { const int col = 4 * (C.lane + 64 * j);
;                 const f32x4 y = xv[rr][j] * rs * g[j] * (sc[j] + 1.f) + sh[j];
;                 v2u o; o.x = pk2(y.x, y.y); o.y = pk2(y.z, y.w);
;                 *(v2u*)(C.H + (size_t)m * 1024 + col) = o; }
	v_mul_f32_e32 v10, v96, v96
	v_fmac_f32_e32 v10, v97, v97
	v_fmac_f32_e32 v10, v98, v98
	v_fmac_f32_e32 v10, v99, v99
	v_fmac_f32_e32 v10, v100, v100
	v_fmac_f32_e32 v10, v101, v101
	v_fmac_f32_e32 v10, v102, v102
	v_fmac_f32_e32 v10, v103, v103
	v_fmac_f32_e32 v10, v104, v104
	v_fmac_f32_e32 v10, v105, v105
	v_fmac_f32_e32 v10, v106, v106
	v_fmac_f32_e32 v10, v107, v107
	v_fmac_f32_e32 v10, v108, v108
	v_fmac_f32_e32 v10, v109, v109
	v_fmac_f32_e32 v10, v110, v110
	v_fmac_f32_e32 v10, v111, v111
	ds_bpermute_b32 v14, v4, v10
	s_waitcnt lgkmcnt(0)
	v_add_f32_e32 v10, v10, v14
	ds_bpermute_b32 v14, v5, v10
	s_waitcnt lgkmcnt(0)
	v_add_f32_e32 v10, v10, v14
	ds_bpermute_b32 v14, v6, v10
	s_waitcnt lgkmcnt(0)
	v_add_f32_e32 v10, v10, v14
	ds_bpermute_b32 v14, v7, v10
	s_waitcnt lgkmcnt(0)
	v_add_f32_e32 v10, v10, v14
	ds_bpermute_b32 v14, v8, v10
	s_waitcnt lgkmcnt(0)
	v_add_f32_e32 v10, v10, v14
	ds_bpermute_b32 v14, v9, v10
	s_waitcnt lgkmcnt(0)
	v_add_f32_e32 v10, v10, v14
	v_fma_f32 v10, v10, s32, v60
	v_rsq_f32_e32 v18, v10
	s_nop 0
	v_pk_mul_f32 v[96:97], v[96:97], v[18:19] op_sel_hi:[1,0]
	v_pk_mul_f32 v[98:99], v[98:99], v[18:19] op_sel_hi:[1,0]
	v_pk_mul_f32 v[100:101], v[100:101], v[18:19] op_sel_hi:[1,0]
	v_pk_mul_f32 v[102:103], v[102:103], v[18:19] op_sel_hi:[1,0]
	v_pk_mul_f32 v[104:105], v[104:105], v[18:19] op_sel_hi:[1,0]
	v_pk_mul_f32 v[106:107], v[106:107], v[18:19] op_sel_hi:[1,0]
	v_pk_mul_f32 v[108:109], v[108:109], v[18:19] op_sel_hi:[1,0]
	v_pk_mul_f32 v[110:111], v[110:111], v[18:19] op_sel_hi:[1,0]
	v_pk_mul_f32 v[96:97], v[24:25], v[96:97]
	v_pk_mul_f32 v[98:99], v[26:27], v[98:99]
	v_pk_mul_f32 v[100:101], v[28:29], v[100:101]
	v_pk_mul_f32 v[102:103], v[30:31], v[102:103]
	v_pk_mul_f32 v[104:105], v[32:33], v[104:105]
	v_pk_mul_f32 v[106:107], v[34:35], v[106:107]
	v_pk_mul_f32 v[108:109], v[36:37], v[108:109]
	v_pk_mul_f32 v[110:111], v[38:39], v[110:111]
	v_pk_fma_f32 v[96:97], v[112:113], v[96:97], v[128:129]
	v_pk_fma_f32 v[98:99], v[114:115], v[98:99], v[130:131]
	v_pk_fma_f32 v[100:101], v[116:117], v[100:101], v[132:133]
	v_pk_fma_f32 v[102:103], v[118:119], v[102:103], v[134:135]
	v_pk_fma_f32 v[104:105], v[120:121], v[104:105], v[136:137]
	v_pk_fma_f32 v[106:107], v[122:123], v[106:107], v[138:139]
	v_pk_fma_f32 v[108:109], v[124:125], v[108:109], v[140:141]
	v_pk_fma_f32 v[110:111], v[126:127], v[110:111], v[142:143]
	v_cvt_pk_bf16_f32 v96, v96, v97
	v_cvt_pk_bf16_f32 v97, v98, v99
	v_cvt_pk_bf16_f32 v98, v100, v101
	v_cvt_pk_bf16_f32 v99, v102, v103
	v_cvt_pk_bf16_f32 v104, v104, v105
	v_cvt_pk_bf16_f32 v105, v106, v107
	v_cvt_pk_bf16_f32 v106, v108, v109
	v_cvt_pk_bf16_f32 v107, v110, v111
	global_store_dwordx4 v2, v[96:99], s[10:11] sc1
	global_store_dwordx4 v2, v[104:107], s[10:11] offset:1024 sc1

; #define LAS __attribute__((address_space(3)))
; #define MFMA32(a, b, c) __builtin_amdgcn_mfma_f32_32x32x16_bf16((a), (b), (c), 0, 0, 0)
; template <int MODE> DI void hgrn_chunk_phase(const Args& A, int wave_s, int l, bool need_ctx, LAS unsigned char* lds) {
;     ...
; #pragma unroll
;             for (int ks = 0; ks < 4; ++ks) { const bf16x8 a = tr_nat(SP, 16 * ks, 32 * mt, lane), bq = *(LAS bf16x8*)(QQ + (32 * tblk + r) * KV_PITCH + ks * 32 + h5 * 16); O = MFMA32(a, bq, O); }
;             const int pos = 32 * tblk + r, tloc = dir ? 63 - pos : pos;
; #pragma unroll
;             for (int i = 0; i < 16; ++i) { const int dv = 32 * mt + (i & 3) + 8 * (i >> 2) + 4 * h5; OX[(dir * 64 + tloc) * 68 + dv] = O[i]; }
;             __syncthreads();
.LBB0_383:
	ds_read_b64_tr_b16 v[16:17], v70 offset:36864
	ds_read_b64_tr_b16 v[18:19], v70 offset:37440
	ds_read_b128 v[20:23], v72 offset:18432
	ds_read_b128 v[24:27], v72 offset:18464
	s_add_i32 s83, s83, s92
	s_sub_i32 s2, s2, s90
	v_mov_b32_e32 v43, v79
	s_waitcnt lgkmcnt(1)
	v_mfma_f32_32x32x16_bf16 v[0:15], v[16:19], v[20:23], v[0:15]
	ds_read_b64_tr_b16 v[16:17], v70 offset:39168
	ds_read_b64_tr_b16 v[18:19], v70 offset:39744
	v_mov_b32_e32 v41, v80
	v_mov_b32_e32 v40, v85
	v_mov_b32_e32 v42, v76
	v_mov_b32_e32 v106, v92
	s_mov_b32 s59, s95
	v_readlane_b32 s95, v255, 24
	s_waitcnt lgkmcnt(0)
	v_mfma_f32_32x32x16_bf16 v[0:15], v[16:19], v[24:27], v[0:15]
	ds_read_b64_tr_b16 v[16:17], v70 offset:41472
	ds_read_b64_tr_b16 v[18:19], v70 offset:42048
	ds_read_b128 v[20:23], v72 offset:18496
	s_waitcnt lgkmcnt(0)
	v_mfma_f32_32x32x16_bf16 v[0:15], v[16:19], v[20:23], v[0:15]
	ds_read_b64_tr_b16 v[16:17], v70 offset:43776
	ds_read_b64_tr_b16 v[18:19], v70 offset:44352
	ds_read_b128 v[20:23], v72 offset:18528
	s_waitcnt lgkmcnt(0)
	v_mfma_f32_32x32x16_bf16 v[0:15], v[16:19], v[20:23], v[0:15]
	v_add_u32_e32 v16, s96, v61
	s_lshl_b32 s96, s58, 1
	v_ashrrev_i32_e32 v17, 31, v16
	s_nop 8
	ds_write_b128 v66, v[0:3]
	ds_write_b128 v66, v[4:7] offset:32
	ds_write_b128 v66, v[8:11] offset:64
	ds_write_b128 v66, v[12:15] offset:96
	v_mov_b64_e32 v[0:1], s[84:85]
	v_mad_i64_i32 v[0:1], s[54:55], v16, s77, v[0:1]
	v_lshl_add_u64 v[0:1], v[0:1], 0, s[96:97]
	v_lshl_add_u64 v[0:1], v[0:1], 0, v[160:161]
	v_add_co_u32_e32 v0, vcc, s76, v0
	s_waitcnt lgkmcnt(0)
	s_nop 0
	v_addc_co_u32_e32 v1, vcc, 0, v1, vcc
	s_barrier
; DI float shx_(int lane, float v, int m) { return __builtin_bit_cast(float, __builtin_amdgcn_ds_bpermute((lane ^ m) << 2, __builtin_bit_cast(int, v))); }
; DI float silu_f(float x) { return x / (1.f + __expf(-x)); }
; DI unsigned pkbf(float a, float b) { fv2 v = {a, b}; return __builtin_bit_cast(unsigned, __builtin_convertvector(v, bfv2)); }
; template <int MODE> DI void hgrn_chunk_phase(const Args& A, int wave_s, int l, bool need_ctx, LAS unsigned char* lds) {
;     ...
;             {
;                 const int t = C.tid >> 3, part = C.tid & 7; const int row = rbase + t;
;                 float tot[8]; float ss = 0.f;
; #pragma unroll
;                 for (int e = 0; e < 8; ++e) { tot[e] = OX[t * 68 + part * 8 + e] + OX[(64 + t) * 68 + part * 8 + e]; ss += tot[e] * tot[e]; }
;                 ss += shx_(C.lane, ss, 1); ss += shx_(C.lane, ss, 2); ss += shx_(C.lane, ss, 4);
;                 const float rs = rsqrtf(ss * (1.f / 64.f) + EPS);
;                 const v4u gr = *(const v4u*)(C.P + (size_t)row * INW + CB_G + hd * 64 + part * 8);
;                 unsigned res[4];
; #pragma unroll
;                 for (int q = 0; q < 4; ++q) { const float g0 = __builtin_bit_cast(float, gr[q] << 16), g1 = __builtin_bit_cast(float, gr[q] & 0xffff0000u);
;                     const float y0 = tot[2 * q] * rs * C.hgog[l * 64 + part * 8 + 2 * q] * silu_f(g0), y1 = tot[2 * q + 1] * rs * C.hgog[l * 64 + part * 8 + 2 * q + 1] * silu_f(g1);
;                     res[q] = pkbf(y0, y1); }
;                 v4u o; o.x = res[0]; o.y = res[1]; o.z = res[2]; o.w = res[3];
;                 *(v4u*)(C.MIX + (size_t)row * 1024 + 512 + hd * 64 + part * 8) = o;
;             }
	global_load_dwordx4 v[0:3], v[0:1], off
	ds_read_b128 v[12:15], v62
	ds_read_b128 v[4:7], v62 offset:16
	ds_read_b128 v[8:11], v62 offset:17424
	s_waitcnt lgkmcnt(0)
	v_pk_add_f32 v[20:21], v[4:5], v[8:9]
	v_pk_add_f32 v[18:19], v[6:7], v[10:11]
	v_pk_mul_f32 v[26:27], v[20:21], v[20:21]
	v_pk_mul_f32 v[24:25], v[18:19], v[18:19]
	s_waitcnt vmcnt(0)
	v_lshlrev_b32_e32 v28, 16, v2
	v_and_b32_e32 v2, 0xffff0000, v2
	v_mul_f32_e32 v4, 0xbfb8aa3b, v28
	v_mul_f32_e32 v23, 0xbfb8aa3b, v2
	v_exp_f32_e32 v22, v4
	v_exp_f32_e32 v23, v23
	global_load_dwordx4 v[4:7], v[44:45], off offset:16
	global_load_dwordx4 v[8:11], v[44:45], off
	v_pk_add_f32 v[22:23], v[22:23], 1.0 op_sel_hi:[1,0]
	s_nop 0
	v_div_scale_f32 v29, s[54:55], v23, v23, v2
	v_rcp_f32_e32 v30, v29
	s_nop 0
	v_fma_f32 v31, -v29, v30, 1.0
	v_fmac_f32_e32 v30, v31, v30
	v_div_scale_f32 v31, vcc, v2, v23, v2
	v_mul_f32_e32 v32, v31, v30
	v_fma_f32 v33, -v29, v32, v31
	v_fmac_f32_e32 v32, v33, v30
	v_fma_f32 v29, -v29, v32, v31
	v_div_fmas_f32 v29, v29, v30, v32
	v_div_fixup_f32 v23, v29, v23, v2
	v_div_scale_f32 v2, s[54:55], v22, v22, v28
	v_rcp_f32_e32 v29, v2
	s_nop 0
	v_fma_f32 v30, -v2, v29, 1.0
	v_fmac_f32_e32 v29, v30, v29
	v_div_scale_f32 v30, vcc, v28, v22, v28
	v_mul_f32_e32 v31, v30, v29
	v_fma_f32 v32, -v2, v31, v30
	v_fmac_f32_e32 v31, v32, v29
	v_fma_f32 v2, -v2, v31, v30
	v_div_fmas_f32 v2, v2, v29, v31
	v_div_fixup_f32 v22, v2, v22, v28
	v_lshlrev_b32_e32 v2, 16, v1
	v_and_b32_e32 v1, 0xffff0000, v1
	v_mul_f32_e32 v28, 0xbfb8aa3b, v2
	v_mul_f32_e32 v29, 0xbfb8aa3b, v1
	ds_read_b128 v[32:35], v62 offset:17408
	v_exp_f32_e32 v28, v28
	v_exp_f32_e32 v29, v29
	s_waitcnt lgkmcnt(0)
	v_pk_add_f32 v[14:15], v[14:15], v[34:35]
	v_pk_add_f32 v[28:29], v[28:29], 1.0 op_sel_hi:[1,0]
	v_pk_add_f32 v[12:13], v[12:13], v[32:33]
	v_div_scale_f32 v34, s[54:55], v29, v29, v1
	v_rcp_f32_e32 v35, v34
	v_pk_mul_f32 v[32:33], v[12:13], v[12:13]
	v_pk_mul_f32 v[30:31], v[14:15], v[14:15]
	v_fma_f32 v36, -v34, v35, 1.0
	v_fmac_f32_e32 v35, v36, v35
	v_div_scale_f32 v36, vcc, v1, v29, v1
	v_mul_f32_e32 v37, v36, v35
	v_fma_f32 v38, -v34, v37, v36
	v_fmac_f32_e32 v37, v38, v35
	v_fma_f32 v34, -v34, v37, v36
	v_div_fmas_f32 v34, v34, v35, v37
	v_div_fixup_f32 v29, v34, v29, v1
	v_div_scale_f32 v1, s[54:55], v28, v28, v2
	v_rcp_f32_e32 v34, v1
	s_nop 0
	v_fma_f32 v35, -v1, v34, 1.0
	v_fmac_f32_e32 v34, v35, v34
	v_div_scale_f32 v35, vcc, v2, v28, v2
	v_mul_f32_e32 v36, v35, v34
	v_fma_f32 v37, -v1, v36, v35
	v_fmac_f32_e32 v36, v37, v34
	v_fma_f32 v1, -v1, v36, v35
	v_div_fmas_f32 v1, v1, v34, v36
	v_div_fixup_f32 v28, v1, v28, v2
	v_lshlrev_b32_e32 v2, 16, v0
	v_and_b32_e32 v34, 0xffff0000, v0
	v_mul_f32_e32 v0, 0xbfb8aa3b, v2
	v_mul_f32_e32 v1, 0xbfb8aa3b, v34
	v_exp_f32_e32 v0, v0
	v_exp_f32_e32 v1, v1
	s_nop 0
	v_pk_add_f32 v[0:1], v[0:1], 1.0 op_sel_hi:[1,0]
	s_nop 0
	v_div_scale_f32 v35, s[54:55], v1, v1, v34
	v_rcp_f32_e32 v36, v35
	s_nop 0
	v_fma_f32 v37, -v35, v36, 1.0
	v_fmac_f32_e32 v36, v37, v36
	v_div_scale_f32 v37, vcc, v34, v1, v34
	v_mul_f32_e32 v38, v37, v36
	v_fma_f32 v39, -v35, v38, v37
	v_fmac_f32_e32 v38, v39, v36
	v_fma_f32 v35, -v35, v38, v37
	v_div_fmas_f32 v35, v35, v36, v38
	v_div_fixup_f32 v1, v35, v1, v34
	v_div_scale_f32 v34, s[54:55], v0, v0, v2
	v_rcp_f32_e32 v35, v34
	v_mov_b32_e32 v39, v78
	v_fma_f32 v36, -v34, v35, 1.0
	v_fmac_f32_e32 v35, v36, v35
	v_div_scale_f32 v36, vcc, v2, v0, v2
	v_mul_f32_e32 v37, v36, v35
	v_fma_f32 v38, -v34, v37, v36
	v_fmac_f32_e32 v37, v38, v35
	v_fma_f32 v34, -v34, v37, v36
	v_div_fmas_f32 v34, v34, v35, v37
	v_div_fixup_f32 v0, v34, v0, v2
	v_add_f32_e32 v2, v32, v33
	v_add_f32_e32 v2, v2, v30
	v_add_f32_e32 v2, v2, v31
	v_add_f32_e32 v2, v2, v26
	v_add_f32_e32 v2, v2, v27
	v_add_f32_e32 v2, v2, v24
	v_add_f32_e32 v2, v2, v25
	ds_bpermute_b32 v24, v63, v2
	v_mov_b32_e32 v27, v105
	v_mov_b32_e32 v26, v103
	v_mov_b32_e32 v37, v87
	v_mov_b32_e32 v36, v89
	s_waitcnt lgkmcnt(0)
	v_add_f32_e32 v2, v2, v24
	ds_bpermute_b32 v24, v64, v2
	v_mov_b32_e32 v33, v94
	v_mov_b32_e32 v32, v96
	v_mov_b32_e32 v38, v82
	v_mov_b32_e32 v35, v84
	s_waitcnt lgkmcnt(0)
	v_add_f32_e32 v2, v2, v24
	ds_bpermute_b32 v24, v65, v2
	v_mov_b32_e32 v34, v86
	v_mov_b32_e32 v31, v91
	v_mov_b32_e32 v30, v93
	s_waitcnt lgkmcnt(0)
	v_add_f32_e32 v2, v2, v24
	v_fmamk_f32 v2, v2, 0x3c800000, v162
	v_cmp_gt_f32_e32 vcc, s78, v2
	v_mul_f32_e32 v24, 0x4b800000, v2
	s_nop 0
	v_cndmask_b32_e32 v2, v2, v24, vcc
	v_rsq_f32_e32 v2, v2
	s_nop 0
	v_mul_f32_e32 v24, 0x45800000, v2
	v_cndmask_b32_e32 v24, v2, v24, vcc
	v_pk_mul_f32 v[12:13], v[12:13], v[24:25] op_sel_hi:[1,0]
	s_waitcnt vmcnt(0)
	v_pk_mul_f32 v[8:9], v[8:9], v[12:13]
	s_nop 0
	v_pk_mul_f32 v[0:1], v[0:1], v[8:9]
	v_pk_mul_f32 v[8:9], v[14:15], v[24:25] op_sel_hi:[1,0]
	v_cvt_pk_bf16_f32 v0, v0, v1
	v_pk_mul_f32 v[8:9], v[10:11], v[8:9]
	v_lshlrev_b32_e32 v10, 16, v3
	v_pk_mul_f32 v[8:9], v[28:29], v[8:9]
	v_and_b32_e32 v3, 0xffff0000, v3
	v_cvt_pk_bf16_f32 v1, v8, v9
	v_pk_mul_f32 v[8:9], v[20:21], v[24:25] op_sel_hi:[1,0]
	v_mov_b32_e32 v21, v100
	v_pk_mul_f32 v[4:5], v[4:5], v[8:9]
	v_pk_mul_f32 v[8:9], v[18:19], v[24:25] op_sel_hi:[1,0]
	v_pk_mul_f32 v[4:5], v[22:23], v[4:5]
	v_pk_mul_f32 v[6:7], v[6:7], v[8:9]
	v_cvt_pk_bf16_f32 v2, v4, v5
	v_mul_f32_e32 v4, 0xbfb8aa3b, v10
	v_mul_f32_e32 v5, 0xbfb8aa3b, v3
	v_exp_f32_e32 v4, v4
	v_exp_f32_e32 v5, v5
	v_mov_b32_e32 v25, v104
	v_mov_b32_e32 v23, v102
	v_mov_b32_e32 v24, v101
	v_pk_add_f32 v[4:5], v[4:5], 1.0 op_sel_hi:[1,0]
	v_mov_b32_e32 v22, v99
	v_div_scale_f32 v8, s[54:55], v5, v5, v3
	v_rcp_f32_e32 v9, v8
	v_mov_b32_e32 v20, v98
	v_mov_b32_e32 v29, v97
	v_mov_b32_e32 v28, v95
	v_fma_f32 v11, -v8, v9, 1.0
	v_fmac_f32_e32 v9, v11, v9
	v_div_scale_f32 v11, vcc, v3, v5, v3
	v_mul_f32_e32 v12, v11, v9
	v_fma_f32 v13, -v8, v12, v11
	v_fmac_f32_e32 v12, v13, v9
	v_fma_f32 v8, -v8, v12, v11
	v_div_fmas_f32 v8, v8, v9, v12
	v_div_fixup_f32 v5, v8, v5, v3
	v_div_scale_f32 v3, s[54:55], v4, v4, v10
	v_rcp_f32_e32 v8, v3
	s_nop 0
	v_fma_f32 v9, -v3, v8, 1.0
	v_fmac_f32_e32 v8, v9, v8
	v_div_scale_f32 v9, vcc, v10, v4, v10
	v_mul_f32_e32 v11, v9, v8
	v_fma_f32 v12, -v3, v11, v9
	v_fmac_f32_e32 v11, v12, v8
	v_fma_f32 v3, -v3, v11, v9
	v_div_fmas_f32 v3, v3, v8, v11
	v_div_fixup_f32 v4, v3, v4, v10
	v_pk_mul_f32 v[4:5], v[4:5], v[6:7]
	v_mov_b32_e32 v6, v77
	v_cvt_pk_bf16_f32 v3, v4, v5
	v_lshlrev_b64 v[4:5], 11, v[16:17]
	v_lshl_add_u64 v[4:5], s[88:89], 0, v[4:5]
	v_lshl_add_u64 v[4:5], v[4:5], 0, s[96:97]
	v_lshl_add_u64 v[4:5], v[4:5], 0, v[160:161]
	v_add_co_u32_e32 v4, vcc, 0x7a00000, v4
	v_mov_b32_e32 v8, v81
	s_nop 0
	v_addc_co_u32_e32 v5, vcc, 0, v5, vcc
	global_store_dwordx4 v[4:5], v[0:3], off offset:1024 sc1
	s_andn2_b64 vcc, exec, s[74:75]
	v_mov_b32_e32 v4, v75
	v_mov_b32_e32 v2, v74
	v_mov_b32_e32 v12, v83
	v_mov_b32_e32 v11, v88
	v_mov_b32_e32 v10, v90
	s_cbranch_vccz .LBB0_398

; DI void diff_mfma_phase(const Args& A, int wave_s, int l, bool need_ctx, LAS unsigned char* lds) {
;     ...
;         for (int it = 0; it < ntiles; ++it) {
;             const int cur = it & 1;
;             if (it + 1 < ntiles) { const int kr0 = (it + 1 < 64 ? kbase0 : kbase1) + (it + 1) * DT_ROWS;
;                 const char* kb_ = (const char*)(C.P + (size_t)kr0 * INW + CC_K + hd * 64);
;                 kreg[0] = *(const v4u*)(kb_ + sgoff); kreg[1] = *(const v4u*)(kb_ + (size_t)64 * INW * 2 + sgoff); }
;             LAS unsigned char* Kb = lds + cur * DT_IMG; LAS unsigned char* Vb = lds + VOFF0 + cur * DV_IMG;
;             LAS unsigned char* kl = Kb + r * KV_PITCH + h * 16;
;             f32x16 Sc;
;             { const bf16x8 kA0 = *(LAS bf16x8*)(kl), kA1 = *(LAS bf16x8*)(kl + 32); Sc = MFMA32(kA0, Qf[0][0], negM); Sc = MFMA32(kA1, Qf[0][1], Sc); }
; #pragma unroll
;             for (int g = 0; g < 8; ++g) {
;                 const int c = g & 1, sub = g >> 1;
;                 bf16x8 kB0, kB1; f32x16 Sn;
;                 if (g < 7) { LAS unsigned char* kp = kl + (32 * ((g + 1) >> 1)) * KV_PITCH + (c ^ 1) * 64; kB0 = *(LAS bf16x8*)(kp); kB1 = *(LAS bf16x8*)(kp + 32); }
;                 if (c == 0) { O[1][0] = MFMA32(Vs[0], Pp0, O[1][0]); O[1][1] = MFMA32(Vs[2], Pp0, O[1][1]); O[1][0] = MFMA32(Vs[1], Pp1, O[1][0]); O[1][1] = MFMA32(Vs[3], Pp1, O[1][1]); }
;                 else        { O[0][0] = MFMA32(Vs[0], Pp0, O[0][0]); O[0][1] = MFMA32(Vs[2], Pp0, O[0][1]); O[0][0] = MFMA32(Vs[1], Pp1, O[0][0]); O[0][1] = MFMA32(Vs[3], Pp1, O[0][1]); }
;                 float t = 0.f;
; #pragma unroll
;                 for (int i = 0; i < 8; ++i) { Sc[i] = __builtin_amdgcn_exp2f(Sc[i]); t += Sc[i]; }
;                 const bf16x8 Pn0 = PACK8(Sc, 0);
;                 __builtin_amdgcn_sched_barrier(0);
;                 if (g < 7) { Sn = MFMA32(kB0, Qf[c ^ 1][0], negM); Sn = MFMA32(kB1, Qf[c ^ 1][1], Sn); }
;                 __builtin_amdgcn_sched_barrier(0);
;                 if (c == 0) { LAS unsigned char* vp = Vb + (32 * sub) * VP + voff; Vs[0] = tr_pairV(vp); Vs[1] = tr_pairV(vp + 16 * VP); Vs[2] = tr_pairV(vp + 64); Vs[3] = tr_pairV(vp + 16 * VP + 64); }
; #pragma unroll
;                 for (int i = 8; i < 16; ++i) { Sc[i] = __builtin_amdgcn_exp2f(Sc[i]); t += Sc[i]; }
;                 if (c == 0) ls0 += t; else ls1 += t;
.LBB0_406:
	s_and_b32 s18, s15, 1
	s_mul_i32 s9, s18, 0x4800
	v_add_u32_e32 v160, s9, v218
	ds_read_b128 v[64:67], v160
	ds_read_b128 v[80:83], v160 offset:32
	s_add_i32 s14, s15, 1
	s_cmp_lt_u32 s15, 63
	s_cselect_b32 s9, s10, s12
	s_ashr_i32 s15, s9, 31
	s_add_u32 s9, s6, s9
	s_addc_u32 s15, s7, s15
	s_mul_hi_u32 s16, s9, 0x1800
	s_waitcnt lgkmcnt(1)
	v_mfma_f32_32x32x16_bf16 v[64:79], v[64:67], v[108:111], 0
	s_mulk_i32 s15, 0x1800
	s_mulk_i32 s9, 0x1800
	s_add_i32 s16, s16, s15
	s_add_u32 s15, s84, s9
	s_addc_u32 s17, s85, s16
	s_lshl_b32 s9, s11, 1
	s_add_u32 s16, s15, s9
	s_addc_u32 s17, s17, 0
	s_waitcnt lgkmcnt(0)
	v_mfma_f32_32x32x16_bf16 v[64:79], v[80:83], v[104:107], v[64:79]
	v_lshl_add_u64 v[80:81], s[16:17], 0, v[138:139]
	v_add_co_u32_e32 v128, vcc, s76, v80
	s_mul_i32 s15, s18, 0x6000
	s_nop 0
	v_addc_co_u32_e32 v129, vcc, 0, v81, vcc
	v_add_co_u32_e32 v132, vcc, s3, v80
	v_mfma_f32_32x32x16_bf16 v[16:31], v[120:123], v[88:91], v[16:31]
	s_nop 0
	v_addc_co_u32_e32 v133, vcc, 0, v81, vcc
	s_nop 2
	v_exp_f32_e32 v130, v64
	v_exp_f32_e32 v134, v65
	v_exp_f32_e32 v164, v66
	v_exp_f32_e32 v184, v67
	v_exp_f32_e32 v186, v68
	v_mfma_f32_32x32x16_bf16 v[0:15], v[124:127], v[88:91], v[0:15]
	global_load_dwordx4 v[120:123], v[128:129], off offset:1024
	global_load_dwordx4 v[124:127], v[132:133], off offset:1024
	v_exp_f32_e32 v188, v69
	v_exp_f32_e32 v190, v70
	v_exp_f32_e32 v192, v71
	v_add_u32_e32 v147, s15, v219
	s_xor_b32 s15, s18, 1
	s_mul_i32 s16, s15, 0x4800
	v_mfma_f32_32x32x16_bf16 v[16:31], v[116:119], v[92:95], v[16:31]
	ds_read_b128 v[80:83], v160 offset:64
	ds_read_b128 v[116:119], v160 offset:96
	s_add_i32 s16, s16, 0
	v_add3_u32 v166, s16, v214, v212
	v_add3_u32 v167, s16, v215, v212
	v_cvt_pk_bf16_f32 v64, v130, v134
	v_cvt_pk_bf16_f32 v65, v164, v184
	v_cvt_pk_bf16_f32 v66, v186, v188
	v_mfma_f32_32x32x16_bf16 v[0:15], v[112:115], v[92:95], v[0:15]
	v_cvt_pk_bf16_f32 v67, v190, v192
	s_waitcnt lgkmcnt(1)
	v_mfma_f32_32x32x16_bf16 v[80:95], v[80:83], v[100:103], 0
	s_waitcnt lgkmcnt(0)
	v_mfma_f32_32x32x16_bf16 v[80:95], v[116:119], v[96:99], v[80:95]
	ds_read_b64_tr_b16 v[68:69], v147 offset:36864
	ds_read_b64_tr_b16 v[70:71], v147 offset:38400
	ds_read_b64_tr_b16 v[114:115], v147 offset:38464
	ds_read_b64_tr_b16 v[112:113], v147 offset:36928
	ds_read_b64_tr_b16 v[116:117], v147 offset:39936
	ds_read_b64_tr_b16 v[118:119], v147 offset:41472
	ds_read_b64_tr_b16 v[174:175], v147 offset:41536
	ds_read_b64_tr_b16 v[172:173], v147 offset:40000
	v_exp_f32_e32 v194, v72
	v_exp_f32_e32 v170, v73
	v_exp_f32_e32 v168, v74
	v_exp_f32_e32 v158, v75
	v_exp_f32_e32 v156, v76
	v_exp_f32_e32 v154, v77
	v_exp_f32_e32 v152, v78
	v_exp_f32_e32 v150, v79
	v_cvt_pk_bf16_f32 v72, v194, v170
	v_cvt_pk_bf16_f32 v73, v168, v158
	v_cvt_pk_bf16_f32 v74, v156, v154
	v_cvt_pk_bf16_f32 v75, v152, v150
	s_waitcnt lgkmcnt(6)
	v_mfma_f32_32x32x16_bf16 v[48:63], v[68:71], v[64:67], v[48:63]
	v_exp_f32_e32 v131, v80
	v_exp_f32_e32 v135, v81
	v_exp_f32_e32 v165, v82
	v_exp_f32_e32 v185, v83
	v_exp_f32_e32 v187, v84
	v_exp_f32_e32 v189, v85
	v_exp_f32_e32 v191, v86
	s_waitcnt lgkmcnt(4)
	v_mfma_f32_32x32x16_bf16 v[32:47], v[112:115], v[64:67], v[32:47]
	ds_read_b128 v[64:67], v160 offset:4608
	ds_read_b128 v[176:179], v160 offset:4640
	v_exp_f32_e32 v193, v87
	v_cvt_pk_bf16_f32 v180, v131, v135
	v_cvt_pk_bf16_f32 v181, v165, v185
	v_cvt_pk_bf16_f32 v182, v187, v189
	v_cvt_pk_bf16_f32 v183, v191, v193
	s_waitcnt lgkmcnt(4)
	v_mfma_f32_32x32x16_bf16 v[48:63], v[116:119], v[72:75], v[48:63]
	s_waitcnt lgkmcnt(2)
	v_mfma_f32_32x32x16_bf16 v[32:47], v[172:175], v[72:75], v[32:47]
	s_waitcnt lgkmcnt(1)
	v_mfma_f32_32x32x16_bf16 v[72:87], v[64:67], v[108:111], 0
	s_waitcnt lgkmcnt(0)
	v_mfma_f32_32x32x16_bf16 v[72:87], v[176:179], v[104:107], v[72:87]
	v_add_f32_e64 v64, v130, 0
	v_add_f32_e64 v65, v131, 0
	v_exp_f32_e32 v195, v88
	v_pk_add_f32 v[64:65], v[134:135], v[64:65]
	v_exp_f32_e32 v171, v89
	v_pk_add_f32 v[64:65], v[164:165], v[64:65]
	v_exp_f32_e32 v169, v90
	v_pk_add_f32 v[64:65], v[184:185], v[64:65]
	v_exp_f32_e32 v159, v91
	v_pk_add_f32 v[64:65], v[186:187], v[64:65]
	v_exp_f32_e32 v157, v92
	v_exp_f32_e32 v155, v93
	v_exp_f32_e32 v153, v94
	v_exp_f32_e32 v151, v95
	v_pk_add_f32 v[64:65], v[188:189], v[64:65]
	v_cvt_pk_bf16_f32 v66, v157, v155
	v_pk_add_f32 v[64:65], v[190:191], v[64:65]
	v_cvt_pk_bf16_f32 v67, v153, v151
	v_pk_add_f32 v[64:65], v[192:193], v[64:65]
	s_nop 0
	v_pk_add_f32 v[178:179], v[194:195], v[64:65]
	v_cvt_pk_bf16_f32 v64, v195, v171
	v_cvt_pk_bf16_f32 v65, v169, v159
	v_mfma_f32_32x32x16_bf16 v[16:31], v[68:71], v[180:183], v[16:31]
	ds_read_b128 v[88:91], v160 offset:4672
	ds_read_b128 v[92:95], v160 offset:4704
	v_exp_f32_e32 v130, v72
	v_exp_f32_e32 v134, v73
	v_exp_f32_e32 v164, v74
	v_exp_f32_e32 v208, v75
	v_exp_f32_e32 v210, v76
	v_exp_f32_e32 v222, v77
	v_mfma_f32_32x32x16_bf16 v[0:15], v[112:115], v[180:183], v[0:15]
	v_exp_f32_e32 v224, v78
	v_exp_f32_e32 v226, v79
	v_cvt_pk_bf16_f32 v112, v130, v134
	v_cvt_pk_bf16_f32 v113, v164, v208
	v_cvt_pk_bf16_f32 v114, v210, v222
	v_cvt_pk_bf16_f32 v115, v224, v226
	v_mfma_f32_32x32x16_bf16 v[16:31], v[116:119], v[64:67], v[16:31]
	v_mfma_f32_32x32x16_bf16 v[0:15], v[172:175], v[64:67], v[0:15]
	s_waitcnt lgkmcnt(1)
	v_mfma_f32_32x32x16_bf16 v[64:79], v[88:91], v[100:103], 0
	s_waitcnt lgkmcnt(0)
; DI void diff_mfma_phase(const Args& A, int wave_s, int l, bool need_ctx, LAS unsigned char* lds) {
;     ...
;             for (int g = 0; g < 8; ++g) {
;                 const int c = g & 1, sub = g >> 1;
;                 bf16x8 kB0, kB1; f32x16 Sn;
;                 if (g < 7) { LAS unsigned char* kp = kl + (32 * ((g + 1) >> 1)) * KV_PITCH + (c ^ 1) * 64; kB0 = *(LAS bf16x8*)(kp); kB1 = *(LAS bf16x8*)(kp + 32); }
;                 if (c == 0) { O[1][0] = MFMA32(Vs[0], Pp0, O[1][0]); O[1][1] = MFMA32(Vs[2], Pp0, O[1][1]); O[1][0] = MFMA32(Vs[1], Pp1, O[1][0]); O[1][1] = MFMA32(Vs[3], Pp1, O[1][1]); }
;                 else        { O[0][0] = MFMA32(Vs[0], Pp0, O[0][0]); O[0][1] = MFMA32(Vs[2], Pp0, O[0][1]); O[0][0] = MFMA32(Vs[1], Pp1, O[0][0]); O[0][1] = MFMA32(Vs[3], Pp1, O[0][1]); }
;                 float t = 0.f;
; #pragma unroll
;                 for (int i = 0; i < 8; ++i) { Sc[i] = __builtin_amdgcn_exp2f(Sc[i]); t += Sc[i]; }
;                 const bf16x8 Pn0 = PACK8(Sc, 0);
;                 __builtin_amdgcn_sched_barrier(0);
;                 if (g < 7) { Sn = MFMA32(kB0, Qf[c ^ 1][0], negM); Sn = MFMA32(kB1, Qf[c ^ 1][1], Sn); }
;                 __builtin_amdgcn_sched_barrier(0);
;                 if (c == 0) { LAS unsigned char* vp = Vb + (32 * sub) * VP + voff; Vs[0] = tr_pairV(vp); Vs[1] = tr_pairV(vp + 16 * VP); Vs[2] = tr_pairV(vp + 64); Vs[3] = tr_pairV(vp + 16 * VP + 64); }
; #pragma unroll
;                 for (int i = 8; i < 16; ++i) { Sc[i] = __builtin_amdgcn_exp2f(Sc[i]); t += Sc[i]; }
;                 if (c == 0) ls0 += t; else ls1 += t;
;                 Pp0 = Pn0; Pp1 = PACK8(Sc, 1);
;                 if (g < 7) Sc = Sn;
;                 __builtin_amdgcn_sched_barrier(0);
;                 if (g == 3 && it + 1 < ntiles) {
;                     LAS unsigned char* kb2 = lds + (cur ^ 1) * DT_IMG;
;                     *(LAS v4u*)(kb2 + srow * KV_PITCH + sch * 16) = kreg[0]; *(LAS v4u*)(kb2 + (srow + 64) * KV_PITCH + sch * 16) = kreg[1];
;                     const int kr0 = (it + 1 < 64 ? kbase0 : kbase1) + (it + 1) * DT_ROWS;
;                     const char* vb_ = (const char*)(C.P + (size_t)kr0 * INW + CC_V + hd * 64);
;                     kreg[0] = *(const v4u*)(vb_ + sgoff); kreg[1] = *(const v4u*)(vb_ + (size_t)64 * INW * 2 + sgoff);
;                     __builtin_amdgcn_sched_barrier(0);
;                 }
;             }
	v_mfma_f32_32x32x16_bf16 v[64:79], v[92:95], v[96:99], v[64:79]
	ds_read_b64_tr_b16 v[116:117], v147 offset:43008
	ds_read_b64_tr_b16 v[118:119], v147 offset:44544
	ds_read_b64_tr_b16 v[194:195], v147 offset:44608
	ds_read_b64_tr_b16 v[192:193], v147 offset:43072
	ds_read_b64_tr_b16 v[196:197], v147 offset:46080
	ds_read_b64_tr_b16 v[198:199], v147 offset:47616
	ds_read_b64_tr_b16 v[202:203], v147 offset:47680
	ds_read_b64_tr_b16 v[200:201], v147 offset:46144
	v_exp_f32_e32 v188, v80
	v_exp_f32_e32 v186, v81
	v_exp_f32_e32 v184, v82
	v_exp_f32_e32 v182, v83
	v_exp_f32_e32 v180, v84
	v_exp_f32_e32 v176, v85
	v_exp_f32_e32 v174, v86
	v_exp_f32_e32 v172, v87
	v_cvt_pk_bf16_f32 v80, v188, v186
	v_cvt_pk_bf16_f32 v81, v184, v182
	v_cvt_pk_bf16_f32 v82, v180, v176
	v_cvt_pk_bf16_f32 v83, v174, v172
	s_waitcnt lgkmcnt(6)
	v_mfma_f32_32x32x16_bf16 v[48:63], v[116:119], v[112:115], v[48:63]
	v_exp_f32_e32 v131, v64
	v_exp_f32_e32 v135, v65
	v_exp_f32_e32 v165, v66
	v_exp_f32_e32 v209, v67
	v_exp_f32_e32 v211, v68
	v_pk_add_f32 v[64:65], v[130:131], 0 op_sel_hi:[1,0]
	v_exp_f32_e32 v223, v69
	s_waitcnt lgkmcnt(4)
	v_mfma_f32_32x32x16_bf16 v[32:47], v[192:195], v[112:115], v[32:47]
	v_add_f32_e64 v64, v134, v64
	v_add_f32_e64 v65, v135, v65
	ds_read_b128 v[84:87], v160 offset:9216
	ds_read_b128 v[204:207], v160 offset:9248
	v_exp_f32_e32 v225, v70
	v_pk_add_f32 v[64:65], v[164:165], v[64:65]
	v_exp_f32_e32 v227, v71
	v_pk_add_f32 v[64:65], v[208:209], v[64:65]
	v_cvt_pk_bf16_f32 v66, v211, v223
	s_waitcnt lgkmcnt(4)
	v_mfma_f32_32x32x16_bf16 v[48:63], v[196:199], v[80:83], v[48:63]
	v_add_f32_e64 v64, v210, v64
	v_add_f32_e64 v65, v211, v65
	v_cvt_pk_bf16_f32 v67, v225, v227
	v_add_f32_e64 v64, v222, v64
	v_add_f32_e64 v65, v223, v65
	v_pk_add_f32 v[64:65], v[224:225], v[64:65]
	s_nop 0
	v_pk_add_f32 v[190:191], v[226:227], v[64:65]
	s_waitcnt lgkmcnt(2)
	v_mfma_f32_32x32x16_bf16 v[32:47], v[200:203], v[80:83], v[32:47]
	v_cvt_pk_bf16_f32 v64, v131, v135
	v_cvt_pk_bf16_f32 v65, v165, v209
	s_waitcnt lgkmcnt(1)
	v_mfma_f32_32x32x16_bf16 v[80:95], v[84:87], v[108:111], 0
	s_waitcnt lgkmcnt(0)
	v_mfma_f32_32x32x16_bf16 v[80:95], v[204:207], v[104:107], v[80:95]
	v_exp_f32_e32 v189, v72
	v_exp_f32_e32 v187, v73
	v_exp_f32_e32 v185, v74
	v_exp_f32_e32 v183, v75
	v_exp_f32_e32 v181, v76
	v_exp_f32_e32 v177, v77
	v_exp_f32_e32 v175, v78
	v_exp_f32_e32 v173, v79
	v_cvt_pk_bf16_f32 v68, v189, v187
	v_cvt_pk_bf16_f32 v69, v185, v183
	v_cvt_pk_bf16_f32 v70, v181, v177
	v_cvt_pk_bf16_f32 v71, v175, v173
	s_waitcnt vmcnt(1)
	ds_write_b128 v166, v[120:123]
	s_waitcnt vmcnt(0)
	ds_write_b128 v167, v[124:127]
	global_load_dwordx4 v[128:131], v[128:129], off offset:1536
	s_nop 0
	global_load_dwordx4 v[132:135], v[132:133], off offset:1536
	v_mfma_f32_32x32x16_bf16 v[16:31], v[116:119], v[64:67], v[16:31]
	ds_read_b128 v[72:75], v160 offset:9280
	ds_read_b128 v[112:115], v160 offset:9312
	v_exp_f32_e32 v164, v80
	v_exp_f32_e32 v226, v81
	v_exp_f32_e32 v228, v82
	v_exp_f32_e32 v230, v83
	v_exp_f32_e32 v232, v84
	v_exp_f32_e32 v234, v85
	v_mfma_f32_32x32x16_bf16 v[0:15], v[192:195], v[64:67], v[0:15]
	v_exp_f32_e32 v236, v86
	v_cvt_pk_bf16_f32 v80, v164, v226
	v_cvt_pk_bf16_f32 v81, v228, v230
	v_cvt_pk_bf16_f32 v82, v232, v234
	v_mfma_f32_32x32x16_bf16 v[16:31], v[196:199], v[68:71], v[16:31]
	v_mfma_f32_32x32x16_bf16 v[0:15], v[200:203], v[68:71], v[0:15]
	v_exp_f32_e32 v200, v87
	s_nop 0
	v_cvt_pk_bf16_f32 v83, v236, v200
	s_waitcnt lgkmcnt(1)
	v_mfma_f32_32x32x16_bf16 v[64:79], v[72:75], v[100:103], 0
	s_waitcnt lgkmcnt(0)
	v_mfma_f32_32x32x16_bf16 v[64:79], v[112:115], v[96:99], v[64:79]
	ds_read_b64_tr_b16 v[112:113], v147 offset:49152
	ds_read_b64_tr_b16 v[114:115], v147 offset:50688
	ds_read_b64_tr_b16 v[118:119], v147 offset:50752
	ds_read_b64_tr_b16 v[116:117], v147 offset:49216
	ds_read_b64_tr_b16 v[120:121], v147 offset:52224
	ds_read_b64_tr_b16 v[122:123], v147 offset:53760
	ds_read_b64_tr_b16 v[126:127], v147 offset:53824
	ds_read_b64_tr_b16 v[124:125], v147 offset:52288
	v_exp_f32_e32 v208, v88
	v_exp_f32_e32 v206, v89
	v_exp_f32_e32 v204, v90
	v_exp_f32_e32 v202, v91
	v_exp_f32_e32 v198, v92
	v_exp_f32_e32 v196, v93
	v_exp_f32_e32 v194, v94
	v_exp_f32_e32 v192, v95
	v_cvt_pk_bf16_f32 v84, v208, v206
	v_cvt_pk_bf16_f32 v85, v204, v202
	v_cvt_pk_bf16_f32 v86, v198, v196
	v_cvt_pk_bf16_f32 v87, v194, v192
	s_waitcnt lgkmcnt(6)
	v_mfma_f32_32x32x16_bf16 v[48:63], v[112:115], v[80:83], v[48:63]
	v_exp_f32_e32 v165, v64
	v_exp_f32_e32 v227, v65
	v_exp_f32_e32 v229, v66
	v_exp_f32_e32 v231, v67
	v_exp_f32_e32 v233, v68
	v_pk_add_f32 v[64:65], v[164:165], 0 op_sel_hi:[1,0]
	ds_read_b128 v[88:91], v160 offset:13824
	ds_read_b128 v[222:225], v160 offset:13856
	s_waitcnt lgkmcnt(6)
	v_mfma_f32_32x32x16_bf16 v[32:47], v[116:119], v[80:83], v[32:47]
	v_exp_f32_e32 v235, v69
	v_pk_add_f32 v[64:65], v[226:227], v[64:65]
	v_exp_f32_e32 v237, v70
	v_pk_add_f32 v[64:65], v[228:229], v[64:65]
	v_exp_f32_e32 v201, v71
	v_pk_add_f32 v[64:65], v[230:231], v[64:65]
	v_cvt_pk_bf16_f32 v66, v233, v235
	s_waitcnt lgkmcnt(4)
	v_mfma_f32_32x32x16_bf16 v[48:63], v[120:123], v[84:87], v[48:63]
	v_add_f32_e64 v64, v232, v64
	v_add_f32_e64 v65, v233, v65
	v_cvt_pk_bf16_f32 v67, v237, v201
	v_add_f32_e64 v64, v234, v64
	v_add_f32_e64 v65, v235, v65
	v_pk_add_f32 v[210:211], v[236:237], v[64:65]
	v_cvt_pk_bf16_f32 v64, v165, v227
	v_cvt_pk_bf16_f32 v65, v229, v231
	s_waitcnt lgkmcnt(2)
	v_mfma_f32_32x32x16_bf16 v[32:47], v[124:127], v[84:87], v[32:47]
	s_waitcnt lgkmcnt(1)
	v_mfma_f32_32x32x16_bf16 v[80:95], v[88:91], v[108:111], 0
	s_waitcnt lgkmcnt(0)
; DI void diff_mfma_phase(const Args& A, int wave_s, int l, bool need_ctx, LAS unsigned char* lds) {
;     ...
;             for (int g = 0; g < 8; ++g) {
;                 const int c = g & 1, sub = g >> 1;
;                 bf16x8 kB0, kB1; f32x16 Sn;
;                 if (g < 7) { LAS unsigned char* kp = kl + (32 * ((g + 1) >> 1)) * KV_PITCH + (c ^ 1) * 64; kB0 = *(LAS bf16x8*)(kp); kB1 = *(LAS bf16x8*)(kp + 32); }
;                 if (c == 0) { O[1][0] = MFMA32(Vs[0], Pp0, O[1][0]); O[1][1] = MFMA32(Vs[2], Pp0, O[1][1]); O[1][0] = MFMA32(Vs[1], Pp1, O[1][0]); O[1][1] = MFMA32(Vs[3], Pp1, O[1][1]); }
;                 else        { O[0][0] = MFMA32(Vs[0], Pp0, O[0][0]); O[0][1] = MFMA32(Vs[2], Pp0, O[0][1]); O[0][0] = MFMA32(Vs[1], Pp1, O[0][0]); O[0][1] = MFMA32(Vs[3], Pp1, O[0][1]); }
;                 float t = 0.f;
; #pragma unroll
;                 for (int i = 0; i < 8; ++i) { Sc[i] = __builtin_amdgcn_exp2f(Sc[i]); t += Sc[i]; }
;                 const bf16x8 Pn0 = PACK8(Sc, 0);
;                 __builtin_amdgcn_sched_barrier(0);
;                 if (g < 7) { Sn = MFMA32(kB0, Qf[c ^ 1][0], negM); Sn = MFMA32(kB1, Qf[c ^ 1][1], Sn); }
;                 __builtin_amdgcn_sched_barrier(0);
;                 if (c == 0) { LAS unsigned char* vp = Vb + (32 * sub) * VP + voff; Vs[0] = tr_pairV(vp); Vs[1] = tr_pairV(vp + 16 * VP); Vs[2] = tr_pairV(vp + 64); Vs[3] = tr_pairV(vp + 16 * VP + 64); }
; #pragma unroll
;                 for (int i = 8; i < 16; ++i) { Sc[i] = __builtin_amdgcn_exp2f(Sc[i]); t += Sc[i]; }
;                 if (c == 0) ls0 += t; else ls1 += t;
;                 Pp0 = Pn0; Pp1 = PACK8(Sc, 1);
;                 if (g < 7) Sc = Sn;
;                 __builtin_amdgcn_sched_barrier(0);
;                 if (g == 3 && it + 1 < ntiles) {
;                     LAS unsigned char* kb2 = lds + (cur ^ 1) * DT_IMG;
;                     *(LAS v4u*)(kb2 + srow * KV_PITCH + sch * 16) = kreg[0]; *(LAS v4u*)(kb2 + (srow + 64) * KV_PITCH + sch * 16) = kreg[1];
;                     const int kr0 = (it + 1 < 64 ? kbase0 : kbase1) + (it + 1) * DT_ROWS;
;                     const char* vb_ = (const char*)(C.P + (size_t)kr0 * INW + CC_V + hd * 64);
;                     kreg[0] = *(const v4u*)(vb_ + sgoff); kreg[1] = *(const v4u*)(vb_ + (size_t)64 * INW * 2 + sgoff);
;                     __builtin_amdgcn_sched_barrier(0);
;                 }
;             }
	v_mfma_f32_32x32x16_bf16 v[80:95], v[222:225], v[104:107], v[80:95]
	v_exp_f32_e32 v209, v72
	v_exp_f32_e32 v207, v73
	v_exp_f32_e32 v205, v74
	v_exp_f32_e32 v203, v75
	v_exp_f32_e32 v199, v76
	v_exp_f32_e32 v197, v77
	v_exp_f32_e32 v195, v78
	v_exp_f32_e32 v193, v79
	v_cvt_pk_bf16_f32 v68, v209, v207
	v_cvt_pk_bf16_f32 v69, v205, v203
	v_cvt_pk_bf16_f32 v70, v199, v197
	v_cvt_pk_bf16_f32 v71, v195, v193
	v_mfma_f32_32x32x16_bf16 v[16:31], v[112:115], v[64:67], v[16:31]
	ds_read_b128 v[72:75], v160 offset:13888
	ds_read_b128 v[222:225], v160 offset:13920
	v_exp_f32_e32 v164, v80
	v_exp_f32_e32 v226, v81
	v_exp_f32_e32 v228, v82
	v_exp_f32_e32 v230, v83
	v_exp_f32_e32 v232, v84
	v_exp_f32_e32 v234, v85
	v_mfma_f32_32x32x16_bf16 v[0:15], v[116:119], v[64:67], v[0:15]
	v_exp_f32_e32 v236, v86
	v_exp_f32_e32 v238, v87
	v_cvt_pk_bf16_f32 v80, v164, v226
	v_cvt_pk_bf16_f32 v81, v228, v230
	v_cvt_pk_bf16_f32 v82, v232, v234
	v_cvt_pk_bf16_f32 v83, v236, v238
	v_mfma_f32_32x32x16_bf16 v[16:31], v[120:123], v[68:71], v[16:31]
	v_mfma_f32_32x32x16_bf16 v[0:15], v[124:127], v[68:71], v[0:15]
	s_waitcnt lgkmcnt(1)
	v_mfma_f32_32x32x16_bf16 v[64:79], v[72:75], v[100:103], 0
	s_waitcnt lgkmcnt(0)
	v_mfma_f32_32x32x16_bf16 v[64:79], v[222:225], v[96:99], v[64:79]
	ds_read_b64_tr_b16 v[120:121], v147 offset:55296
	ds_read_b64_tr_b16 v[122:123], v147 offset:56832
	ds_read_b64_tr_b16 v[126:127], v147 offset:56896
	ds_read_b64_tr_b16 v[124:125], v147 offset:55360
	ds_read_b64_tr_b16 v[116:117], v147 offset:58368
	ds_read_b64_tr_b16 v[118:119], v147 offset:59904
	ds_read_b64_tr_b16 v[114:115], v147 offset:59968
	ds_read_b64_tr_b16 v[112:113], v147 offset:58432
	v_exp_f32_e32 v222, v88
	v_exp_f32_e32 v224, v89
	v_exp_f32_e32 v240, v90
	v_exp_f32_e32 v242, v91
	v_exp_f32_e32 v244, v92
	v_exp_f32_e32 v246, v93
	v_exp_f32_e32 v250, v94
	v_exp_f32_e32 v166, v95
	v_cvt_pk_bf16_f32 v84, v222, v224
	v_cvt_pk_bf16_f32 v85, v240, v242
	v_cvt_pk_bf16_f32 v86, v244, v246
	v_cvt_pk_bf16_f32 v87, v250, v166
	s_waitcnt lgkmcnt(6)
	v_mfma_f32_32x32x16_bf16 v[48:63], v[120:123], v[80:83], v[48:63]
	v_exp_f32_e32 v165, v64
	v_exp_f32_e32 v227, v65
	v_exp_f32_e32 v229, v66
	v_exp_f32_e32 v231, v67
	v_exp_f32_e32 v233, v68
	v_exp_f32_e32 v235, v69
	v_pk_add_f32 v[64:65], v[164:165], 0 op_sel_hi:[1,0]
	s_waitcnt lgkmcnt(4)
	v_mfma_f32_32x32x16_bf16 v[32:47], v[124:127], v[80:83], v[32:47]
	v_exp_f32_e32 v237, v70
	v_exp_f32_e32 v239, v71
	v_pk_add_f32 v[64:65], v[226:227], v[64:65]
	v_cvt_pk_bf16_f32 v88, v165, v227
	v_pk_add_f32 v[64:65], v[228:229], v[64:65]
	v_cvt_pk_bf16_f32 v89, v229, v231
	v_pk_add_f32 v[64:65], v[230:231], v[64:65]
	s_waitcnt lgkmcnt(2)
	v_mfma_f32_32x32x16_bf16 v[48:63], v[116:119], v[84:87], v[48:63]
	v_add_f32_e64 v64, v232, v64
	v_add_f32_e64 v65, v233, v65
	v_cvt_pk_bf16_f32 v90, v233, v235
	v_cvt_pk_bf16_f32 v91, v237, v239
	v_add_f32_e64 v64, v234, v64
	v_add_f32_e64 v65, v235, v65
	s_waitcnt lgkmcnt(0)
	v_mfma_f32_32x32x16_bf16 v[32:47], v[112:115], v[84:87], v[32:47]
	v_exp_f32_e32 v223, v72
	v_exp_f32_e32 v225, v73
	v_exp_f32_e32 v241, v74
	v_pk_add_f32 v[66:67], v[170:171], v[178:179]
	v_pk_add_f32 v[68:69], v[188:189], v[190:191]
	v_pk_add_f32 v[70:71], v[200:201], v[210:211]
	v_pk_add_f32 v[64:65], v[236:237], v[64:65]
	v_exp_f32_e32 v243, v75
	v_pk_add_f32 v[66:67], v[168:169], v[66:67]
	v_pk_add_f32 v[68:69], v[186:187], v[68:69]
	v_pk_add_f32 v[70:71], v[208:209], v[70:71]
	v_pk_add_f32 v[64:65], v[238:239], v[64:65]
	v_exp_f32_e32 v245, v76
	v_pk_add_f32 v[66:67], v[158:159], v[66:67]
	v_pk_add_f32 v[68:69], v[184:185], v[68:69]
	v_pk_add_f32 v[70:71], v[206:207], v[70:71]
	v_pk_add_f32 v[64:65], v[222:223], v[64:65]
	v_exp_f32_e32 v247, v77
	v_pk_add_f32 v[66:67], v[156:157], v[66:67]
	v_pk_add_f32 v[68:69], v[182:183], v[68:69]
	v_pk_add_f32 v[70:71], v[204:205], v[70:71]
	v_pk_add_f32 v[64:65], v[224:225], v[64:65]
	v_exp_f32_e32 v251, v78
	v_pk_add_f32 v[66:67], v[154:155], v[66:67]
	v_pk_add_f32 v[68:69], v[180:181], v[68:69]
	v_pk_add_f32 v[70:71], v[202:203], v[70:71]
	v_pk_add_f32 v[64:65], v[240:241], v[64:65]
	v_exp_f32_e32 v167, v79
	v_pk_add_f32 v[66:67], v[152:153], v[66:67]
	v_pk_add_f32 v[68:69], v[176:177], v[68:69]
	v_pk_add_f32 v[70:71], v[198:199], v[70:71]
	v_pk_add_f32 v[64:65], v[242:243], v[64:65]
	v_pk_add_f32 v[66:67], v[150:151], v[66:67]
	v_pk_add_f32 v[68:69], v[174:175], v[68:69]
	v_pk_add_f32 v[70:71], v[196:197], v[70:71]
	v_pk_add_f32 v[64:65], v[244:245], v[64:65]
	v_pk_add_f32 v[66:67], v[148:149], v[66:67]
	v_pk_add_f32 v[68:69], v[172:173], v[68:69]
	v_pk_add_f32 v[70:71], v[194:195], v[70:71]
	v_pk_add_f32 v[64:65], v[246:247], v[64:65]
	v_pk_add_f32 v[66:67], v[66:67], v[68:69]
	v_pk_add_f32 v[68:69], v[192:193], v[70:71]
	v_pk_add_f32 v[64:65], v[250:251], v[64:65]
	v_pk_add_f32 v[66:67], v[66:67], v[68:69]
	v_pk_add_f32 v[64:65], v[166:167], v[64:65]
	v_cvt_pk_bf16_f32 v92, v223, v225
	v_cvt_pk_bf16_f32 v93, v241, v243
	v_cvt_pk_bf16_f32 v94, v245, v247
	v_cvt_pk_bf16_f32 v95, v251, v167
	v_pk_add_f32 v[148:149], v[66:67], v[64:65]
	s_mulk_i32 s15, 0x6000
	s_add_i32 s15, s15, 0
	s_add_u32 s6, s6, 0x80
	s_addc_u32 s7, s7, 0
	v_add3_u32 v64, s15, v217, v212
	v_add3_u32 v65, s15, v216, v212
	s_cmp_eq_u32 s13, s14
	s_mov_b32 s15, s14
	s_waitcnt vmcnt(1)
	ds_write_b128 v65, v[128:131] offset:36864
	s_waitcnt vmcnt(0)
	ds_write_b128 v64, v[132:135] offset:36864
	s_waitcnt lgkmcnt(0)
	s_barrier
	s_cbranch_scc0 .LBB0_406
; DI void diff_mfma_phase(const Args& A, int wave_s, int l, bool need_ctx, LAS unsigned char* lds) {
;     ...
;         for (int it = 0; it < ntiles; ++it) {
;             const int cur = it & 1;
;             if (it + 1 < ntiles) { const int kr0 = (it + 1 < 64 ? kbase0 : kbase1) + (it + 1) * DT_ROWS;
;                 const char* kb_ = (const char*)(C.P + (size_t)kr0 * INW + CC_K + hd * 64);
;                 kreg[0] = *(const v4u*)(kb_ + sgoff); kreg[1] = *(const v4u*)(kb_ + (size_t)64 * INW * 2 + sgoff); }
;             LAS unsigned char* Kb = lds + cur * DT_IMG; LAS unsigned char* Vb = lds + VOFF0 + cur * DV_IMG;
;             LAS unsigned char* kl = Kb + r * KV_PITCH + h * 16;
;             f32x16 Sc;
;             { const bf16x8 kA0 = *(LAS bf16x8*)(kl), kA1 = *(LAS bf16x8*)(kl + 32); Sc = MFMA32(kA0, Qf[0][0], negM); Sc = MFMA32(kA1, Qf[0][1], Sc); }
; #pragma unroll
;             for (int g = 0; g < 8; ++g) {
;                 const int c = g & 1, sub = g >> 1;
;                 bf16x8 kB0, kB1; f32x16 Sn;
;                 if (g < 7) { LAS unsigned char* kp = kl + (32 * ((g + 1) >> 1)) * KV_PITCH + (c ^ 1) * 64; kB0 = *(LAS bf16x8*)(kp); kB1 = *(LAS bf16x8*)(kp + 32); }
;                 if (c == 0) { O[1][0] = MFMA32(Vs[0], Pp0, O[1][0]); O[1][1] = MFMA32(Vs[2], Pp0, O[1][1]); O[1][0] = MFMA32(Vs[1], Pp1, O[1][0]); O[1][1] = MFMA32(Vs[3], Pp1, O[1][1]); }
;                 else        { O[0][0] = MFMA32(Vs[0], Pp0, O[0][0]); O[0][1] = MFMA32(Vs[2], Pp0, O[0][1]); O[0][0] = MFMA32(Vs[1], Pp1, O[0][0]); O[0][1] = MFMA32(Vs[3], Pp1, O[0][1]); }
;                 float t = 0.f;
; #pragma unroll
;                 for (int i = 0; i < 8; ++i) { Sc[i] = __builtin_amdgcn_exp2f(Sc[i]); t += Sc[i]; }
;                 const bf16x8 Pn0 = PACK8(Sc, 0);
;                 __builtin_amdgcn_sched_barrier(0);
;                 if (g < 7) { Sn = MFMA32(kB0, Qf[c ^ 1][0], negM); Sn = MFMA32(kB1, Qf[c ^ 1][1], Sn); }
;                 __builtin_amdgcn_sched_barrier(0);
;                 if (c == 0) { LAS unsigned char* vp = Vb + (32 * sub) * VP + voff; Vs[0] = tr_pairV(vp); Vs[1] = tr_pairV(vp + 16 * VP); Vs[2] = tr_pairV(vp + 64); Vs[3] = tr_pairV(vp + 16 * VP + 64); }
; #pragma unroll
;                 for (int i = 8; i < 16; ++i) { Sc[i] = __builtin_amdgcn_exp2f(Sc[i]); t += Sc[i]; }
;                 if (c == 0) ls0 += t; else ls1 += t;
	s_and_b32 s6, s13, 1
	s_mul_i32 s7, s6, 0x4800
	v_add_u32_e32 v135, s7, v218
	ds_read_b128 v[64:67], v135
	v_mfma_f32_32x32x16_bf16 v[16:31], v[120:123], v[88:91], v[16:31]
	s_mulk_i32 s6, 0x6000
	v_add_u32_e32 v134, s6, v219
	s_waitcnt lgkmcnt(0)
	v_mfma_f32_32x32x16_bf16 v[72:87], v[64:67], v[108:111], 0
	ds_read_b128 v[64:67], v135 offset:32
	v_mfma_f32_32x32x16_bf16 v[0:15], v[124:127], v[88:91], v[0:15]
	s_waitcnt lgkmcnt(0)
	v_mfma_f32_32x32x16_bf16 v[72:87], v[64:67], v[104:107], v[72:87]
	ds_read_b128 v[64:67], v135 offset:64
	ds_read_b128 v[88:91], v135 offset:96
	v_mfma_f32_32x32x16_bf16 v[16:31], v[116:119], v[92:95], v[16:31]
	s_nop 8
	v_exp_f32_e32 v68, v72
	v_exp_f32_e32 v158, v73
	v_exp_f32_e32 v164, v74
	v_exp_f32_e32 v176, v75
	v_exp_f32_e32 v178, v76
	v_exp_f32_e32 v180, v77
	v_exp_f32_e32 v182, v78
	v_exp_f32_e32 v184, v79
	v_add_f32_e32 v160, 0, v68
	v_cvt_pk_bf16_f32 v116, v68, v158
	v_cvt_pk_bf16_f32 v117, v164, v176
	v_cvt_pk_bf16_f32 v118, v178, v180
	v_cvt_pk_bf16_f32 v119, v182, v184
	v_mfma_f32_32x32x16_bf16 v[0:15], v[112:115], v[92:95], v[0:15]
	s_waitcnt lgkmcnt(1)
	v_mfma_f32_32x32x16_bf16 v[64:79], v[64:67], v[100:103], 0
	s_waitcnt lgkmcnt(0)
	v_mfma_f32_32x32x16_bf16 v[64:79], v[88:91], v[96:99], v[64:79]
	ds_read_b64_tr_b16 v[150:151], v134 offset:36864
	ds_read_b64_tr_b16 v[152:153], v134 offset:38400
	ds_read_b64_tr_b16 v[156:157], v134 offset:38464
	ds_read_b64_tr_b16 v[154:155], v134 offset:36928
	ds_read_b64_tr_b16 v[168:169], v134 offset:39936
	ds_read_b64_tr_b16 v[170:171], v134 offset:41472
	ds_read_b64_tr_b16 v[174:175], v134 offset:41536
	ds_read_b64_tr_b16 v[172:173], v134 offset:40000
	v_exp_f32_e32 v112, v80
	v_exp_f32_e32 v186, v81
	v_exp_f32_e32 v188, v82
	v_exp_f32_e32 v190, v83
	v_exp_f32_e32 v192, v84
	v_exp_f32_e32 v194, v85
	v_exp_f32_e32 v196, v86
	v_exp_f32_e32 v198, v87
	v_cvt_pk_bf16_f32 v80, v112, v186
	v_cvt_pk_bf16_f32 v81, v188, v190
	v_cvt_pk_bf16_f32 v82, v192, v194
	v_cvt_pk_bf16_f32 v83, v196, v198
	s_waitcnt lgkmcnt(6)
	v_mfma_f32_32x32x16_bf16 v[48:63], v[150:153], v[116:119], v[48:63]
	ds_read_b128 v[84:87], v135 offset:4608
	ds_read_b128 v[120:123], v135 offset:4640
	v_exp_f32_e32 v64, v64
	v_exp_f32_e32 v202, v65
	v_exp_f32_e32 v204, v66
	v_exp_f32_e32 v206, v67
	v_exp_f32_e32 v208, v68
	v_exp_f32_e32 v132, v69
	s_waitcnt lgkmcnt(6)
	v_mfma_f32_32x32x16_bf16 v[32:47], v[154:157], v[116:119], v[32:47]
	v_exp_f32_e32 v130, v70
	v_exp_f32_e32 v114, v71
	v_add_f32_e32 v200, 0, v64
	v_cvt_pk_bf16_f32 v64, v64, v202
	v_cvt_pk_bf16_f32 v65, v204, v206
	v_cvt_pk_bf16_f32 v66, v208, v132
	v_cvt_pk_bf16_f32 v67, v130, v114
	s_waitcnt lgkmcnt(4)
	v_mfma_f32_32x32x16_bf16 v[48:63], v[168:171], v[80:83], v[48:63]
	s_waitcnt lgkmcnt(2)
	v_mfma_f32_32x32x16_bf16 v[32:47], v[172:175], v[80:83], v[32:47]
	s_waitcnt lgkmcnt(1)
	v_mfma_f32_32x32x16_bf16 v[80:95], v[84:87], v[108:111], 0
	s_waitcnt lgkmcnt(0)
	v_mfma_f32_32x32x16_bf16 v[80:95], v[120:123], v[104:107], v[80:95]
	v_exp_f32_e32 v210, v72
	v_exp_f32_e32 v116, v73
	v_exp_f32_e32 v120, v74
	v_exp_f32_e32 v118, v75
	v_exp_f32_e32 v124, v76
	v_exp_f32_e32 v122, v77
	v_exp_f32_e32 v128, v78
	v_exp_f32_e32 v126, v79
	v_cvt_pk_bf16_f32 v68, v210, v116
	v_cvt_pk_bf16_f32 v69, v120, v118
	v_cvt_pk_bf16_f32 v70, v124, v122
	v_cvt_pk_bf16_f32 v71, v128, v126
	v_mfma_f32_32x32x16_bf16 v[16:31], v[150:153], v[64:67], v[16:31]
	v_exp_f32_e32 v159, v80
	v_exp_f32_e32 v165, v81
	ds_read_b128 v[72:75], v135 offset:4672
	ds_read_b128 v[150:153], v135 offset:4704
	v_exp_f32_e32 v177, v82
	v_exp_f32_e32 v179, v83
	v_exp_f32_e32 v181, v84
	v_exp_f32_e32 v183, v85
	v_mfma_f32_32x32x16_bf16 v[0:15], v[154:157], v[64:67], v[0:15]
	v_exp_f32_e32 v185, v86
	v_exp_f32_e32 v113, v87
	v_pk_add_f32 v[64:65], v[158:159], v[160:161]
	v_cvt_pk_bf16_f32 v80, v159, v165
	v_pk_add_f32 v[64:65], v[164:165], v[64:65]
	v_cvt_pk_bf16_f32 v81, v177, v179
	v_pk_add_f32 v[64:65], v[176:177], v[64:65]
	v_mfma_f32_32x32x16_bf16 v[16:31], v[168:171], v[68:71], v[16:31]
	v_add_f32_e64 v222, v178, v64
	v_add_f32_e64 v223, v179, v65
	v_cvt_pk_bf16_f32 v82, v181, v183
	v_cvt_pk_bf16_f32 v83, v185, v113
	v_mfma_f32_32x32x16_bf16 v[0:15], v[172:175], v[68:71], v[0:15]
	s_waitcnt lgkmcnt(1)
	v_mfma_f32_32x32x16_bf16 v[64:79], v[72:75], v[100:103], 0
	s_waitcnt lgkmcnt(0)
	v_mfma_f32_32x32x16_bf16 v[64:79], v[150:153], v[96:99], v[64:79]
	ds_read_b64_tr_b16 v[150:151], v134 offset:43008
	ds_read_b64_tr_b16 v[152:153], v134 offset:44544
	ds_read_b64_tr_b16 v[156:157], v134 offset:44608
	ds_read_b64_tr_b16 v[154:155], v134 offset:43072
	ds_read_b64_tr_b16 v[168:169], v134 offset:46080
	ds_read_b64_tr_b16 v[170:171], v134 offset:47616
	ds_read_b64_tr_b16 v[174:175], v134 offset:47680
	ds_read_b64_tr_b16 v[172:173], v134 offset:46144
	v_exp_f32_e32 v187, v88
	v_pk_add_f32 v[84:85], v[180:181], v[222:223]
	v_exp_f32_e32 v189, v89
	v_pk_add_f32 v[84:85], v[182:183], v[84:85]
	v_exp_f32_e32 v191, v90
	v_pk_add_f32 v[84:85], v[184:185], v[84:85]
	v_exp_f32_e32 v193, v91
	v_pk_add_f32 v[84:85], v[112:113], v[84:85]
	v_exp_f32_e32 v195, v92
	v_pk_add_f32 v[84:85], v[186:187], v[84:85]
	v_exp_f32_e32 v197, v93
	v_pk_add_f32 v[84:85], v[188:189], v[84:85]
	v_exp_f32_e32 v199, v94
	v_pk_add_f32 v[84:85], v[190:191], v[84:85]
	v_exp_f32_e32 v87, v95
	v_pk_add_f32 v[84:85], v[192:193], v[84:85]
	v_mov_b32_e32 v86, v148
	v_pk_add_f32 v[84:85], v[194:195], v[84:85]
	s_nop 0
	v_pk_add_f32 v[84:85], v[196:197], v[84:85]
	s_nop 0
	v_pk_add_f32 v[84:85], v[198:199], v[84:85]
	s_nop 0
	v_pk_add_f32 v[112:113], v[86:87], v[84:85]
	v_cvt_pk_bf16_f32 v84, v187, v189
	v_cvt_pk_bf16_f32 v85, v191, v193
	v_cvt_pk_bf16_f32 v86, v195, v197
	v_cvt_pk_bf16_f32 v87, v199, v87
	s_waitcnt lgkmcnt(6)
; #define LAS __attribute__((address_space(3)))
; #define MFMA32(a, b, c) __builtin_amdgcn_mfma_f32_32x32x16_bf16((a), (b), (c), 0, 0, 0)
; #define PACK8(x, s) __builtin_bit_cast(bf16x8, (v4u){pkbf((x)[8 * (s)], (x)[8 * (s) + 1]), pkbf((x)[8 * (s) + 2], (x)[8 * (s) + 3]), pkbf((x)[8 * (s) + 4], (x)[8 * (s) + 5]), pkbf((x)[8 * (s) + 6], (x)[8 * (s) + 7])})
; DI void diff_mfma_phase(const Args& A, int wave_s, int l, bool need_ctx, LAS unsigned char* lds) {
;     ...
;             for (int g = 0; g < 8; ++g) {
;                 const int c = g & 1, sub = g >> 1;
;                 bf16x8 kB0, kB1; f32x16 Sn;
;                 if (g < 7) { LAS unsigned char* kp = kl + (32 * ((g + 1) >> 1)) * KV_PITCH + (c ^ 1) * 64; kB0 = *(LAS bf16x8*)(kp); kB1 = *(LAS bf16x8*)(kp + 32); }
;                 if (c == 0) { O[1][0] = MFMA32(Vs[0], Pp0, O[1][0]); O[1][1] = MFMA32(Vs[2], Pp0, O[1][1]); O[1][0] = MFMA32(Vs[1], Pp1, O[1][0]); O[1][1] = MFMA32(Vs[3], Pp1, O[1][1]); }
;                 else        { O[0][0] = MFMA32(Vs[0], Pp0, O[0][0]); O[0][1] = MFMA32(Vs[2], Pp0, O[0][1]); O[0][0] = MFMA32(Vs[1], Pp1, O[0][0]); O[0][1] = MFMA32(Vs[3], Pp1, O[0][1]); }
;                 float t = 0.f;
; #pragma unroll
;                 for (int i = 0; i < 8; ++i) { Sc[i] = __builtin_amdgcn_exp2f(Sc[i]); t += Sc[i]; }
;                 const bf16x8 Pn0 = PACK8(Sc, 0);
;                 __builtin_amdgcn_sched_barrier(0);
;                 if (g < 7) { Sn = MFMA32(kB0, Qf[c ^ 1][0], negM); Sn = MFMA32(kB1, Qf[c ^ 1][1], Sn); }
;                 __builtin_amdgcn_sched_barrier(0);
;                 if (c == 0) { LAS unsigned char* vp = Vb + (32 * sub) * VP + voff; Vs[0] = tr_pairV(vp); Vs[1] = tr_pairV(vp + 16 * VP); Vs[2] = tr_pairV(vp + 64); Vs[3] = tr_pairV(vp + 16 * VP + 64); }
; #pragma unroll
;                 for (int i = 8; i < 16; ++i) { Sc[i] = __builtin_amdgcn_exp2f(Sc[i]); t += Sc[i]; }
;                 if (c == 0) ls0 += t; else ls1 += t;
;                 Pp0 = Pn0; Pp1 = PACK8(Sc, 1);
;                 if (g < 7) Sc = Sn;
	v_mfma_f32_32x32x16_bf16 v[48:63], v[150:153], v[80:83], v[48:63]
	v_exp_f32_e32 v203, v64
	v_exp_f32_e32 v205, v65
	ds_read_b128 v[88:91], v135 offset:9216
	ds_read_b128 v[176:179], v135 offset:9248
	v_exp_f32_e32 v207, v66
	v_exp_f32_e32 v209, v67
	v_mov_b32_e32 v201, v161
	v_exp_f32_e32 v133, v68
	s_waitcnt lgkmcnt(6)
	v_mfma_f32_32x32x16_bf16 v[32:47], v[154:157], v[80:83], v[32:47]
	v_exp_f32_e32 v131, v69
	v_exp_f32_e32 v115, v70
	v_exp_f32_e32 v211, v71
	v_pk_add_f32 v[64:65], v[202:203], v[200:201]
	v_cvt_pk_bf16_f32 v66, v133, v131
	v_pk_add_f32 v[64:65], v[204:205], v[64:65]
	v_cvt_pk_bf16_f32 v67, v115, v211
	v_pk_add_f32 v[64:65], v[206:207], v[64:65]
	s_waitcnt lgkmcnt(4)
	v_mfma_f32_32x32x16_bf16 v[48:63], v[168:171], v[84:87], v[48:63]
	v_add_f32_e64 v158, v208, v64
	v_add_f32_e64 v159, v209, v65
	v_cvt_pk_bf16_f32 v64, v203, v205
	v_cvt_pk_bf16_f32 v65, v207, v209
	s_waitcnt lgkmcnt(2)
	v_mfma_f32_32x32x16_bf16 v[32:47], v[172:175], v[84:87], v[32:47]
	s_waitcnt lgkmcnt(1)
	v_mfma_f32_32x32x16_bf16 v[80:95], v[88:91], v[108:111], 0
	s_waitcnt lgkmcnt(0)
	v_mfma_f32_32x32x16_bf16 v[80:95], v[176:179], v[104:107], v[80:95]
	v_exp_f32_e32 v117, v72
	v_pk_add_f32 v[68:69], v[132:133], v[158:159]
	v_exp_f32_e32 v121, v73
	v_pk_add_f32 v[68:69], v[130:131], v[68:69]
	v_exp_f32_e32 v119, v74
	v_pk_add_f32 v[68:69], v[114:115], v[68:69]
	v_exp_f32_e32 v125, v75
	v_pk_add_f32 v[68:69], v[210:211], v[68:69]
	v_exp_f32_e32 v123, v76
	v_pk_add_f32 v[68:69], v[116:117], v[68:69]
	v_exp_f32_e32 v129, v77
	v_pk_add_f32 v[68:69], v[120:121], v[68:69]
	v_exp_f32_e32 v127, v78
	v_pk_add_f32 v[68:69], v[118:119], v[68:69]
	v_exp_f32_e32 v71, v79
	v_pk_add_f32 v[68:69], v[124:125], v[68:69]
	v_mov_b32_e32 v70, v149
	v_pk_add_f32 v[68:69], v[122:123], v[68:69]
	s_nop 0
	v_pk_add_f32 v[68:69], v[128:129], v[68:69]
	s_nop 0
	v_pk_add_f32 v[68:69], v[126:127], v[68:69]
	s_nop 0
	v_pk_add_f32 v[114:115], v[70:71], v[68:69]
	v_cvt_pk_bf16_f32 v68, v117, v121
	v_cvt_pk_bf16_f32 v69, v119, v125
	v_cvt_pk_bf16_f32 v70, v123, v129
	v_cvt_pk_bf16_f32 v71, v127, v71
	v_mfma_f32_32x32x16_bf16 v[16:31], v[150:153], v[64:67], v[16:31]
	ds_read_b128 v[72:75], v135 offset:9280
	ds_read_b128 v[116:119], v135 offset:9312
	v_exp_f32_e32 v152, v81
	v_exp_f32_e32 v158, v84
	v_exp_f32_e32 v164, v85
	v_mfma_f32_32x32x16_bf16 v[0:15], v[154:157], v[64:67], v[0:15]
	v_exp_f32_e32 v64, v80
	v_exp_f32_e32 v154, v82
	v_exp_f32_e32 v156, v83
	v_cvt_pk_bf16_f32 v82, v158, v164
	v_add_f32_e32 v160, 0, v64
	v_cvt_pk_bf16_f32 v80, v64, v152
	v_cvt_pk_bf16_f32 v81, v154, v156
	v_mfma_f32_32x32x16_bf16 v[16:31], v[168:171], v[68:71], v[16:31]
	v_exp_f32_e32 v168, v86
	v_exp_f32_e32 v170, v87
	s_nop 0
	v_cvt_pk_bf16_f32 v83, v168, v170
	v_mfma_f32_32x32x16_bf16 v[0:15], v[172:175], v[68:71], v[0:15]
	s_waitcnt lgkmcnt(1)
	v_mfma_f32_32x32x16_bf16 v[64:79], v[72:75], v[100:103], 0
	s_waitcnt lgkmcnt(0)
	v_mfma_f32_32x32x16_bf16 v[64:79], v[116:119], v[96:99], v[64:79]
	ds_read_b64_tr_b16 v[122:123], v134 offset:49152
	ds_read_b64_tr_b16 v[124:125], v134 offset:50688
	ds_read_b64_tr_b16 v[128:129], v134 offset:50752
	ds_read_b64_tr_b16 v[126:127], v134 offset:49216
	ds_read_b64_tr_b16 v[130:131], v134 offset:52224
	ds_read_b64_tr_b16 v[132:133], v134 offset:53760
	ds_read_b64_tr_b16 v[150:151], v134 offset:53824
	ds_read_b64_tr_b16 v[148:149], v134 offset:52288
	v_exp_f32_e32 v172, v88
	v_exp_f32_e32 v174, v89
	v_exp_f32_e32 v176, v90
	v_exp_f32_e32 v178, v91
	v_exp_f32_e32 v180, v92
	v_exp_f32_e32 v182, v93
	v_exp_f32_e32 v184, v94
	v_exp_f32_e32 v186, v95
	v_cvt_pk_bf16_f32 v84, v172, v174
	v_cvt_pk_bf16_f32 v85, v176, v178
	v_cvt_pk_bf16_f32 v86, v180, v182
	v_cvt_pk_bf16_f32 v87, v184, v186
	s_waitcnt lgkmcnt(6)
	v_mfma_f32_32x32x16_bf16 v[48:63], v[122:125], v[80:83], v[48:63]
	ds_read_b128 v[88:91], v135 offset:13824
	ds_read_b128 v[116:119], v135 offset:13856
	v_exp_f32_e32 v64, v64
	v_exp_f32_e32 v190, v65
	v_exp_f32_e32 v192, v66
	v_exp_f32_e32 v194, v67
	v_exp_f32_e32 v196, v68
	v_exp_f32_e32 v198, v69
	s_waitcnt lgkmcnt(6)
	v_mfma_f32_32x32x16_bf16 v[32:47], v[126:129], v[80:83], v[32:47]
	v_exp_f32_e32 v200, v70
	v_exp_f32_e32 v202, v71
	v_add_f32_e32 v188, 0, v64
	v_cvt_pk_bf16_f32 v64, v64, v190
	v_cvt_pk_bf16_f32 v65, v192, v194
	v_cvt_pk_bf16_f32 v66, v196, v198
	v_cvt_pk_bf16_f32 v67, v200, v202
	s_waitcnt lgkmcnt(4)
	v_mfma_f32_32x32x16_bf16 v[48:63], v[130:133], v[84:87], v[48:63]
	s_waitcnt lgkmcnt(2)
	v_mfma_f32_32x32x16_bf16 v[32:47], v[148:151], v[84:87], v[32:47]
	s_waitcnt lgkmcnt(1)
	v_mfma_f32_32x32x16_bf16 v[80:95], v[88:91], v[108:111], 0
	s_waitcnt lgkmcnt(0)
	v_mfma_f32_32x32x16_bf16 v[80:95], v[116:119], v[104:107], v[80:95]
	v_exp_f32_e32 v204, v72
	v_exp_f32_e32 v104, v73
	v_exp_f32_e32 v108, v74
	v_exp_f32_e32 v106, v75
	v_exp_f32_e32 v116, v76
	v_exp_f32_e32 v110, v77
	v_exp_f32_e32 v120, v78
	v_exp_f32_e32 v118, v79
	v_cvt_pk_bf16_f32 v68, v204, v104
	v_cvt_pk_bf16_f32 v69, v108, v106
	v_cvt_pk_bf16_f32 v70, v116, v110
	v_cvt_pk_bf16_f32 v71, v120, v118
	v_mfma_f32_32x32x16_bf16 v[16:31], v[122:125], v[64:67], v[16:31]
	v_exp_f32_e32 v153, v80
	v_exp_f32_e32 v155, v81
	ds_read_b128 v[72:75], v135 offset:13888
	ds_read_b128 v[122:125], v135 offset:13920
	v_exp_f32_e32 v157, v82
	v_exp_f32_e32 v159, v83
	v_exp_f32_e32 v165, v84
	v_exp_f32_e32 v169, v85
	v_mfma_f32_32x32x16_bf16 v[0:15], v[126:129], v[64:67], v[0:15]
	v_exp_f32_e32 v171, v86
	v_exp_f32_e32 v173, v87
	v_pk_add_f32 v[64:65], v[152:153], v[160:161]
	v_cvt_pk_bf16_f32 v80, v153, v155
	v_pk_add_f32 v[64:65], v[154:155], v[64:65]
	v_cvt_pk_bf16_f32 v81, v157, v159
	v_pk_add_f32 v[64:65], v[156:157], v[64:65]
	v_mfma_f32_32x32x16_bf16 v[16:31], v[130:133], v[68:71], v[16:31]
	v_add_f32_e64 v126, v158, v64
	v_add_f32_e64 v127, v159, v65
	v_cvt_pk_bf16_f32 v82, v165, v169
	v_cvt_pk_bf16_f32 v83, v171, v173
	v_mfma_f32_32x32x16_bf16 v[0:15], v[148:151], v[68:71], v[0:15]
	s_waitcnt lgkmcnt(1)
; DI float shx_(int lane, float v, int m) { return __builtin_bit_cast(float, __builtin_amdgcn_ds_bpermute((lane ^ m) << 2, __builtin_bit_cast(int, v))); }
; #define MFMA32(a, b, c) __builtin_amdgcn_mfma_f32_32x32x16_bf16((a), (b), (c), 0, 0, 0)
; DI void diff_mfma_phase(const Args& A, int wave_s, int l, bool need_ctx, LAS unsigned char* lds) {
;     ...
;         O[1][0] = MFMA32(Vs[0], Pp0, O[1][0]); O[1][1] = MFMA32(Vs[2], Pp0, O[1][1]); O[1][0] = MFMA32(Vs[1], Pp1, O[1][0]); O[1][1] = MFMA32(Vs[3], Pp1, O[1][1]);
;         ls0 += shx_(C.lane, ls0, 32); ls1 += shx_(C.lane, ls1, 32);
;         const float inv0 = 1.f / ls0, inv1 = lam / ls1;
;         float ss = 0.f;
; #pragma unroll
;         for (int mt = 0; mt < 2; ++mt)
; #pragma unroll
;             for (int i = 0; i < 16; ++i) { const float o = O[0][mt][i] * inv0 - O[1][mt][i] * inv1; O[0][mt][i] = o; ss += o * o; }
	v_mfma_f32_32x32x16_bf16 v[64:79], v[72:75], v[100:103], 0
	s_waitcnt lgkmcnt(0)
	v_mfma_f32_32x32x16_bf16 v[64:79], v[122:125], v[96:99], v[64:79]
	v_exp_f32_e32 v175, v88
	v_exp_f32_e32 v177, v89
	v_pk_add_f32 v[88:89], v[164:165], v[126:127]
	ds_read_b64_tr_b16 v[84:85], v134 offset:55296
	ds_read_b64_tr_b16 v[86:87], v134 offset:56832
	ds_read_b64_tr_b16 v[98:99], v134 offset:56896
	ds_read_b64_tr_b16 v[96:97], v134 offset:55360
	ds_read_b64_tr_b16 v[100:101], v134 offset:58368
	ds_read_b64_tr_b16 v[102:103], v134 offset:59904
	ds_read_b64_tr_b16 v[124:125], v134 offset:59968
	ds_read_b64_tr_b16 v[122:123], v134 offset:58432
	v_pk_add_f32 v[88:89], v[168:169], v[88:89]
	v_exp_f32_e32 v179, v90
	v_pk_add_f32 v[88:89], v[170:171], v[88:89]
	v_exp_f32_e32 v181, v91
	v_pk_add_f32 v[88:89], v[172:173], v[88:89]
	v_exp_f32_e32 v183, v92
	v_pk_add_f32 v[88:89], v[174:175], v[88:89]
	v_exp_f32_e32 v185, v93
	v_pk_add_f32 v[88:89], v[176:177], v[88:89]
	v_exp_f32_e32 v187, v94
	v_exp_f32_e32 v92, v95
	v_pk_add_f32 v[88:89], v[178:179], v[88:89]
	v_pk_add_f32 v[90:91], v[112:113], v[112:113] op_sel:[0,1] op_sel_hi:[1,0]
	v_pk_add_f32 v[88:89], v[180:181], v[88:89]
	v_mov_b32_e32 v91, v92
	v_pk_add_f32 v[88:89], v[182:183], v[88:89]
	s_nop 0
	v_pk_add_f32 v[88:89], v[184:185], v[88:89]
	s_nop 0
	v_pk_add_f32 v[88:89], v[186:187], v[88:89]
	s_nop 0
	v_pk_add_f32 v[88:89], v[90:91], v[88:89]
	v_cvt_pk_bf16_f32 v90, v183, v185
	v_add_f32_e32 v93, v88, v89
	v_cvt_pk_bf16_f32 v88, v175, v177
	v_cvt_pk_bf16_f32 v89, v179, v181
	v_cvt_pk_bf16_f32 v91, v187, v92
	s_waitcnt lgkmcnt(6)
	v_mfma_f32_32x32x16_bf16 v[48:63], v[84:87], v[80:83], v[48:63]
	v_exp_f32_e32 v191, v64
	v_exp_f32_e32 v193, v65
	v_exp_f32_e32 v195, v66
	v_exp_f32_e32 v197, v67
	v_mov_b32_e32 v189, v161
	v_exp_f32_e32 v199, v68
	v_exp_f32_e32 v201, v69
	s_waitcnt lgkmcnt(4)
	v_mfma_f32_32x32x16_bf16 v[32:47], v[96:99], v[80:83], v[32:47]
	v_exp_f32_e32 v203, v70
	v_exp_f32_e32 v205, v71
	v_pk_add_f32 v[64:65], v[190:191], v[188:189]
	v_cvt_pk_bf16_f32 v66, v199, v201
	v_pk_add_f32 v[64:65], v[192:193], v[64:65]
	v_cvt_pk_bf16_f32 v67, v203, v205
	v_pk_add_f32 v[64:65], v[194:195], v[64:65]
	s_waitcnt lgkmcnt(2)
	v_mfma_f32_32x32x16_bf16 v[48:63], v[100:103], v[88:91], v[48:63]
	v_add_f32_e64 v80, v196, v64
	v_add_f32_e64 v81, v197, v65
	v_cvt_pk_bf16_f32 v64, v191, v193
	v_cvt_pk_bf16_f32 v65, v195, v197
	s_waitcnt lgkmcnt(0)
	v_mfma_f32_32x32x16_bf16 v[32:47], v[122:125], v[88:91], v[32:47]
	v_exp_f32_e32 v105, v72
	v_pk_add_f32 v[68:69], v[198:199], v[80:81]
	v_exp_f32_e32 v109, v73
	v_pk_add_f32 v[68:69], v[200:201], v[68:69]
	v_exp_f32_e32 v107, v74
	v_pk_add_f32 v[68:69], v[202:203], v[68:69]
	v_exp_f32_e32 v117, v75
	v_pk_add_f32 v[68:69], v[204:205], v[68:69]
	v_exp_f32_e32 v111, v76
	v_pk_add_f32 v[68:69], v[104:105], v[68:69]
	v_exp_f32_e32 v121, v77
	v_pk_add_f32 v[68:69], v[108:109], v[68:69]
	v_exp_f32_e32 v119, v78
	v_exp_f32_e32 v72, v79
	v_pk_add_f32 v[68:69], v[106:107], v[68:69]
	v_pk_add_f32 v[70:71], v[114:115], v[114:115] op_sel:[0,1] op_sel_hi:[1,0]
	v_pk_add_f32 v[68:69], v[116:117], v[68:69]
	v_mov_b32_e32 v71, v72
	v_pk_add_f32 v[68:69], v[110:111], v[68:69]
	s_nop 0
	v_pk_add_f32 v[68:69], v[120:121], v[68:69]
	s_nop 0
	v_pk_add_f32 v[68:69], v[118:119], v[68:69]
	s_nop 0
	v_pk_add_f32 v[68:69], v[70:71], v[68:69]
	v_cvt_pk_bf16_f32 v70, v111, v121
	v_add_f32_e32 v73, v68, v69
	v_cvt_pk_bf16_f32 v68, v105, v109
	v_cvt_pk_bf16_f32 v69, v107, v117
	v_cvt_pk_bf16_f32 v71, v119, v72
	v_mfma_f32_32x32x16_bf16 v[16:31], v[84:87], v[64:67], v[16:31]
	s_barrier
	s_lshl_b64 s[4:5], s[4:5], 11
	s_add_u32 s4, s88, s4
	s_addc_u32 s5, s89, s5
	s_add_u32 s4, s4, s9
	v_mfma_f32_32x32x16_bf16 v[0:15], v[96:99], v[64:67], v[0:15]
	ds_bpermute_b32 v64, v220, v93
	ds_bpermute_b32 v65, v220, v73
	s_addc_u32 s5, s5, 0
	v_mov_b32_e32 v147, v161
	s_add_i32 s8, s8, s90
	s_waitcnt lgkmcnt(1)
	v_add_f32_e32 v64, v93, v64
	v_div_scale_f32 v66, s[6:7], v64, v64, 1.0
	v_rcp_f32_e32 v67, v66
	v_mfma_f32_32x32x16_bf16 v[16:31], v[100:103], v[68:71], v[16:31]
	s_waitcnt lgkmcnt(0)
	v_add_f32_e32 v65, v73, v65
	v_lshl_add_u64 v[72:73], s[4:5], 0, v[146:147]
	v_lshl_add_u64 v[72:73], v[136:137], 1, v[72:73]
	s_mov_b64 s[4:5], 0x7a00600
	s_cmp_ge_i32 s8, s2
	v_mfma_f32_32x32x16_bf16 v[0:15], v[122:125], v[68:71], v[0:15]
	v_fma_f32 v68, -v66, v67, 1.0
	v_fmac_f32_e32 v67, v68, v67
	v_div_scale_f32 v68, vcc, 1.0, v64, 1.0
	v_mul_f32_e32 v69, v68, v67
	v_fma_f32 v70, -v66, v69, v68
	v_fmac_f32_e32 v69, v70, v67
	v_fma_f32 v66, -v66, v69, v68
	v_div_fmas_f32 v66, v66, v67, v69
	v_div_fixup_f32 v64, v66, v64, 1.0
	v_div_scale_f32 v66, s[6:7], v65, v65, v163
	v_rcp_f32_e32 v67, v66
	s_nop 0
	v_fma_f32 v68, -v66, v67, 1.0
	v_fmac_f32_e32 v67, v68, v67
	v_div_scale_f32 v68, vcc, v163, v65, v163
	v_mul_f32_e32 v69, v68, v67
	v_fma_f32 v70, -v66, v69, v68
	v_fmac_f32_e32 v69, v70, v67
	v_fma_f32 v66, -v66, v69, v68
	v_div_fmas_f32 v66, v66, v67, v69
	v_div_fixup_f32 v66, v66, v65, v163
	v_pk_mul_f32 v[12:13], v[12:13], v[66:67] op_sel_hi:[1,0]
	v_pk_mul_f32 v[14:15], v[14:15], v[66:67] op_sel_hi:[1,0]
	v_pk_fma_f32 v[12:13], v[44:45], v[64:65], v[12:13] op_sel_hi:[1,0,1] neg_lo:[0,0,1] neg_hi:[0,0,1]
	v_pk_fma_f32 v[14:15], v[46:47], v[64:65], v[14:15] op_sel_hi:[1,0,1] neg_lo:[0,0,1] neg_hi:[0,0,1]
	global_load_dwordx4 v[44:47], v[144:145], off
	v_pk_mul_f32 v[0:1], v[0:1], v[66:67] op_sel_hi:[1,0]
	v_pk_mul_f32 v[16:17], v[16:17], v[66:67] op_sel_hi:[1,0]
	v_pk_fma_f32 v[32:33], v[32:33], v[64:65], v[0:1] op_sel_hi:[1,0,1] neg_lo:[0,0,1] neg_hi:[0,0,1]
	v_pk_mul_f32 v[0:1], v[6:7], v[66:67] op_sel_hi:[1,0]
; DI float shx_(int lane, float v, int m) { return __builtin_bit_cast(float, __builtin_amdgcn_ds_bpermute((lane ^ m) << 2, __builtin_bit_cast(int, v))); }
; DI unsigned pkbf(float a, float b) { fv2 v = {a, b}; return __builtin_bit_cast(unsigned, __builtin_convertvector(v, bfv2)); }
; DI void diff_mfma_phase(const Args& A, int wave_s, int l, bool need_ctx, LAS unsigned char* lds) {
;     ...
; #pragma unroll
;         for (int mt = 0; mt < 2; ++mt)
; #pragma unroll
;             for (int i = 0; i < 16; ++i) { const float o = O[0][mt][i] * inv0 - O[1][mt][i] * inv1; O[0][mt][i] = o; ss += o * o; }
;         ss += shx_(C.lane, ss, 32);
;         const float rs = rsqrtf(ss * (1.f / 64.f) + EPS) * (1.f - lam_init);
;         bf16* op = C.MIX + (size_t)qrow0 * 1024 + 768 + hd * 64 + (unsigned)((wave * 32 + r) * 1024);
; #pragma unroll
;         for (int mt = 0; mt < 2; ++mt)
; #pragma unroll
;             for (int g = 0; g < 4; ++g) { const int dv0 = 32 * mt + 8 * g + 4 * h; const f32x4 og = *(const f32x4*)(C.dog + l * 64 + dv0);
;                 v2u w; w.x = pkbf(O[0][mt][4 * g] * rs * og.x, O[0][mt][4 * g + 1] * rs * og.y); w.y = pkbf(O[0][mt][4 * g + 2] * rs * og.z, O[0][mt][4 * g + 3] * rs * og.w);
;                 *(v2u*)(op + dv0) = w; }
	v_pk_mul_f32 v[18:19], v[18:19], v[66:67] op_sel_hi:[1,0]
	v_pk_fma_f32 v[48:49], v[48:49], v[64:65], v[16:17] op_sel_hi:[1,0,1] neg_lo:[0,0,1] neg_hi:[0,0,1]
	v_pk_fma_f32 v[6:7], v[38:39], v[64:65], v[0:1] op_sel_hi:[1,0,1] neg_lo:[0,0,1] neg_hi:[0,0,1]
	v_pk_mul_f32 v[0:1], v[4:5], v[66:67] op_sel_hi:[1,0]
	v_pk_fma_f32 v[18:19], v[50:51], v[64:65], v[18:19] op_sel_hi:[1,0,1] neg_lo:[0,0,1] neg_hi:[0,0,1]
	v_pk_mul_f32 v[74:75], v[48:49], v[48:49]
	v_pk_fma_f32 v[36:37], v[36:37], v[64:65], v[0:1] op_sel_hi:[1,0,1] neg_lo:[0,0,1] neg_hi:[0,0,1]
	v_pk_mul_f32 v[0:1], v[10:11], v[66:67] op_sel_hi:[1,0]
	v_pk_mul_f32 v[50:51], v[18:19], v[18:19]
	v_pk_mul_f32 v[20:21], v[20:21], v[66:67] op_sel_hi:[1,0]
	v_pk_fma_f32 v[0:1], v[42:43], v[64:65], v[0:1] op_sel_hi:[1,0,1] neg_lo:[0,0,1] neg_hi:[0,0,1]
	v_add_f32_e32 v42, v74, v75
	v_pk_fma_f32 v[20:21], v[52:53], v[64:65], v[20:21] op_sel_hi:[1,0,1] neg_lo:[0,0,1] neg_hi:[0,0,1]
	v_add_f32_e32 v42, v50, v42
	v_pk_mul_f32 v[22:23], v[22:23], v[66:67] op_sel_hi:[1,0]
	v_pk_mul_f32 v[52:53], v[20:21], v[20:21]
	v_add_f32_e32 v42, v51, v42
	v_pk_fma_f32 v[22:23], v[54:55], v[64:65], v[22:23] op_sel_hi:[1,0,1] neg_lo:[0,0,1] neg_hi:[0,0,1]
	v_add_f32_e32 v42, v52, v42
	v_pk_mul_f32 v[54:55], v[22:23], v[22:23]
	v_pk_mul_f32 v[24:25], v[24:25], v[66:67] op_sel_hi:[1,0]
	v_add_f32_e32 v42, v53, v42
	v_pk_fma_f32 v[24:25], v[56:57], v[64:65], v[24:25] op_sel_hi:[1,0,1] neg_lo:[0,0,1] neg_hi:[0,0,1]
	v_add_f32_e32 v42, v54, v42
	v_pk_mul_f32 v[26:27], v[26:27], v[66:67] op_sel_hi:[1,0]
	v_pk_mul_f32 v[56:57], v[24:25], v[24:25]
	v_add_f32_e32 v42, v55, v42
	v_pk_fma_f32 v[26:27], v[58:59], v[64:65], v[26:27] op_sel_hi:[1,0,1] neg_lo:[0,0,1] neg_hi:[0,0,1]
	v_add_f32_e32 v42, v56, v42
	v_pk_mul_f32 v[58:59], v[26:27], v[26:27]
	v_pk_mul_f32 v[28:29], v[28:29], v[66:67] op_sel_hi:[1,0]
	v_add_f32_e32 v42, v57, v42
	v_pk_fma_f32 v[28:29], v[60:61], v[64:65], v[28:29] op_sel_hi:[1,0,1] neg_lo:[0,0,1] neg_hi:[0,0,1]
	v_add_f32_e32 v42, v58, v42
	v_pk_mul_f32 v[30:31], v[30:31], v[66:67] op_sel_hi:[1,0]
	v_pk_mul_f32 v[60:61], v[28:29], v[28:29]
	v_add_f32_e32 v42, v59, v42
	v_pk_fma_f32 v[30:31], v[62:63], v[64:65], v[30:31] op_sel_hi:[1,0,1] neg_lo:[0,0,1] neg_hi:[0,0,1]
	v_add_f32_e32 v42, v60, v42
	v_pk_mul_f32 v[62:63], v[30:31], v[30:31]
	v_add_f32_e32 v42, v61, v42
	v_add_f32_e32 v42, v62, v42
	v_pk_mul_f32 v[2:3], v[2:3], v[66:67] op_sel_hi:[1,0]
	v_pk_mul_f32 v[76:77], v[32:33], v[32:33]
	v_add_f32_e32 v42, v63, v42
	v_pk_fma_f32 v[34:35], v[34:35], v[64:65], v[2:3] op_sel_hi:[1,0,1] neg_lo:[0,0,1] neg_hi:[0,0,1]
	v_add_f32_e32 v42, v76, v42
	v_pk_mul_f32 v[2:3], v[34:35], v[34:35]
	v_add_f32_e32 v42, v77, v42
	v_add_f32_e32 v2, v2, v42
	v_pk_mul_f32 v[4:5], v[36:37], v[36:37]
	v_add_f32_e32 v2, v3, v2
	v_add_f32_e32 v2, v4, v2
	v_pk_mul_f32 v[38:39], v[6:7], v[6:7]
	v_pk_mul_f32 v[8:9], v[8:9], v[66:67] op_sel_hi:[1,0]
	v_add_f32_e32 v2, v5, v2
	v_pk_fma_f32 v[8:9], v[40:41], v[64:65], v[8:9] op_sel_hi:[1,0,1] neg_lo:[0,0,1] neg_hi:[0,0,1]
	v_add_f32_e32 v2, v38, v2
	v_pk_mul_f32 v[40:41], v[8:9], v[8:9]
	v_add_f32_e32 v2, v39, v2
	v_add_f32_e32 v2, v40, v2
	v_pk_mul_f32 v[10:11], v[0:1], v[0:1]
	v_add_f32_e32 v2, v41, v2
	v_add_f32_e32 v2, v10, v2
	v_pk_mul_f32 v[68:69], v[12:13], v[12:13]
	v_add_f32_e32 v2, v11, v2
	v_add_f32_e32 v2, v68, v2
	v_pk_mul_f32 v[70:71], v[14:15], v[14:15]
	v_add_f32_e32 v2, v69, v2
	v_add_f32_e32 v2, v70, v2
	v_add_f32_e32 v2, v71, v2
	ds_bpermute_b32 v3, v220, v2
	v_lshl_add_u64 v[16:17], v[72:73], 0, s[4:5]
	s_mov_b32 s4, 0x7a00000
	s_waitcnt lgkmcnt(0)
	v_add_f32_e32 v2, v2, v3
	v_fmamk_f32 v2, v2, 0x3c800000, v162
	v_cmp_gt_f32_e32 vcc, s78, v2
	v_mul_f32_e32 v3, 0x4b800000, v2
	s_nop 0
	v_cndmask_b32_e32 v2, v2, v3, vcc
	v_rsq_f32_e32 v2, v2
	s_nop 0
	v_mul_f32_e32 v3, 0x45800000, v2
	v_cndmask_b32_e32 v2, v2, v3, vcc
	v_mul_f32_e32 v10, v221, v2
	v_pk_mul_f32 v[2:3], v[48:49], v[10:11] op_sel_hi:[1,0]
	v_pk_mul_f32 v[4:5], v[18:19], v[10:11] op_sel_hi:[1,0]
	s_waitcnt vmcnt(0)
	v_pk_mul_f32 v[2:3], v[44:45], v[2:3]
	v_pk_mul_f32 v[4:5], v[46:47], v[4:5]
	v_cvt_pk_bf16_f32 v2, v2, v3
	v_cvt_pk_bf16_f32 v3, v4, v5
	v_add_co_u32_e32 v4, vcc, s4, v72
	v_pk_mul_f32 v[18:19], v[20:21], v[10:11] op_sel_hi:[1,0]
	s_nop 0
	v_addc_co_u32_e32 v5, vcc, 0, v73, vcc
	global_store_dwordx2 v[4:5], v[2:3], off offset:1536 sc1
	global_load_dwordx4 v[2:5], v[144:145], off offset:32
	v_pk_mul_f32 v[6:7], v[6:7], v[10:11] op_sel_hi:[1,0]
	v_pk_mul_f32 v[0:1], v[0:1], v[10:11] op_sel_hi:[1,0]
	s_waitcnt vmcnt(0)
	v_pk_mul_f32 v[2:3], v[2:3], v[18:19]
	v_pk_mul_f32 v[18:19], v[22:23], v[10:11] op_sel_hi:[1,0]
	v_cvt_pk_bf16_f32 v2, v2, v3
	v_pk_mul_f32 v[4:5], v[4:5], v[18:19]
	v_pk_mul_f32 v[18:19], v[24:25], v[10:11] op_sel_hi:[1,0]
	v_cvt_pk_bf16_f32 v3, v4, v5
	global_store_dwordx2 v[16:17], v[2:3], off offset:16 sc1
	global_load_dwordx4 v[2:5], v[144:145], off offset:64
	s_waitcnt vmcnt(0)
	v_pk_mul_f32 v[2:3], v[2:3], v[18:19]
	v_pk_mul_f32 v[18:19], v[26:27], v[10:11] op_sel_hi:[1,0]
	v_cvt_pk_bf16_f32 v2, v2, v3
	v_pk_mul_f32 v[4:5], v[4:5], v[18:19]
	v_pk_mul_f32 v[18:19], v[28:29], v[10:11] op_sel_hi:[1,0]
	v_cvt_pk_bf16_f32 v3, v4, v5
	global_store_dwordx2 v[16:17], v[2:3], off offset:32 sc1
	global_load_dwordx4 v[2:5], v[144:145], off offset:96
	s_waitcnt vmcnt(0)
	v_pk_mul_f32 v[2:3], v[2:3], v[18:19]
	v_pk_mul_f32 v[18:19], v[30:31], v[10:11] op_sel_hi:[1,0]
	v_cvt_pk_bf16_f32 v2, v2, v3
	v_pk_mul_f32 v[4:5], v[4:5], v[18:19]
	v_pk_mul_f32 v[18:19], v[32:33], v[10:11] op_sel_hi:[1,0]
	v_cvt_pk_bf16_f32 v3, v4, v5
	global_store_dwordx2 v[16:17], v[2:3], off offset:48 sc1
	global_load_dwordx4 v[2:5], v[144:145], off offset:128
	s_waitcnt vmcnt(0)
	v_pk_mul_f32 v[2:3], v[2:3], v[18:19]
	v_pk_mul_f32 v[18:19], v[34:35], v[10:11] op_sel_hi:[1,0]
	v_cvt_pk_bf16_f32 v2, v2, v3
	v_pk_mul_f32 v[4:5], v[4:5], v[18:19]
	v_pk_mul_f32 v[18:19], v[36:37], v[10:11] op_sel_hi:[1,0]
	v_cvt_pk_bf16_f32 v3, v4, v5
	global_store_dwordx2 v[16:17], v[2:3], off offset:64 sc1
	global_load_dwordx4 v[2:5], v[144:145], off offset:160
	s_waitcnt vmcnt(0)
	v_pk_mul_f32 v[2:3], v[2:3], v[18:19]
	v_pk_mul_f32 v[4:5], v[4:5], v[6:7]
	v_cvt_pk_bf16_f32 v2, v2, v3
	v_cvt_pk_bf16_f32 v3, v4, v5
	global_store_dwordx2 v[16:17], v[2:3], off offset:80 sc1
	global_load_dwordx4 v[2:5], v[144:145], off offset:192
	v_pk_mul_f32 v[6:7], v[8:9], v[10:11] op_sel_hi:[1,0]
	s_waitcnt vmcnt(0)
	v_pk_mul_f32 v[0:1], v[4:5], v[0:1]
	v_pk_mul_f32 v[2:3], v[2:3], v[6:7]
	v_pk_mul_f32 v[4:5], v[12:13], v[10:11] op_sel_hi:[1,0]
	v_cvt_pk_bf16_f32 v2, v2, v3
	v_cvt_pk_bf16_f32 v3, v0, v1
	global_store_dwordx2 v[16:17], v[2:3], off offset:96 sc1
	global_load_dwordx4 v[0:3], v[144:145], off offset:224
	s_waitcnt vmcnt(0)
	v_pk_mul_f32 v[0:1], v[0:1], v[4:5]
	v_pk_mul_f32 v[4:5], v[14:15], v[10:11] op_sel_hi:[1,0]
	v_cvt_pk_bf16_f32 v0, v0, v1
	v_pk_mul_f32 v[2:3], v[2:3], v[4:5]
	s_nop 0
	v_cvt_pk_bf16_f32 v1, v2, v3
	global_store_dwordx2 v[16:17], v[0:1], off offset:112 sc1
	s_cbranch_scc0 .LBB0_401

; DI void norm_phase(const Args& A, int wave_s, int l, int which, int rows) {
;     const Ctx C = make_ctx(A, wave_s);
;     const float* gn = (which == 1 ? C.n1g : C.n2g) + l * 1024;
;     const bool from_in = (l == 0 && which == 1);
;     f32x4 g[4];
; #pragma unroll
;     for (int j = 0; j < 4; ++j) g[j] = *(const f32x4*)(gn + 4 * (C.lane + 64 * j));
;     for (int m0 = C.gw * 2; m0 < rows; m0 += C.NGW * 2) {
;         f32x4 xv[2][4];
;         const float* modp[2];
; #pragma unroll
;         for (int rr = 0; rr < 2; ++rr) {
;             const int m = m0 + rr; const float* xr; int v;
;             if (m < NLAT) { xr = (from_in ? C.x : C.out) + (size_t)m * 1024; v = m >> 13; }
;             else { xr = (from_in ? C.ctx : C.XC) + (size_t)(m - NLAT) * 1024; v = 4; }
;             modp[rr] = C.SM + SM_MOD + (l * 5 + v) * 6144 + (which == 1 ? 0 : 3072);
; #pragma unroll
;             for (int j = 0; j < 4; ++j) xv[rr][j] = ((const f32x4*)xr)[C.lane + 64 * j];
.LBB0_528:
	s_or_b64 exec, exec, s[4:5]
	v_readlane_b32 s4, v254, 41
	s_cmp_ge_i32 s4, s42
	s_waitcnt lgkmcnt(0)
	s_barrier
	v_readlane_b32 s5, v254, 42
	v_mbcnt_lo_u32_b32 v48, -1, 0
	v_mbcnt_hi_u32_b32 v48, -1, v48
	v_mbcnt_lo_u32_b32 v0, -1, 0
	v_mbcnt_hi_u32_b32 v0, -1, v0
	v_readlane_b32 s6, v255, 32
	v_lshlrev_b32_e32 v1, 5, v0
	v_lshlrev_b32_e32 v2, 4, v0
	v_xor_b32_e32 v4, 1, v0
	v_xor_b32_e32 v5, 2, v0
	v_xor_b32_e32 v6, 4, v0
	v_xor_b32_e32 v7, 8, v0
	v_xor_b32_e32 v8, 16, v0
	v_xor_b32_e32 v9, 32, v0
	v_lshlrev_b32_e32 v4, 2, v4
	v_lshlrev_b32_e32 v5, 2, v5
	v_lshlrev_b32_e32 v6, 2, v6
	v_lshlrev_b32_e32 v7, 2, v7
	v_lshlrev_b32_e32 v8, 2, v8
	v_lshlrev_b32_e32 v9, 2, v9
	v_mov_b32_e32 v60, 0x358637bd
	s_lshr_b32 s6, s6, 10
	s_lshr_b32 s4, s94, 6
	s_lshl_b32 s5, s65, 3
	s_add_u32 s4, s4, s5
	s_lshr_b32 s5, s4, 9
	s_mul_i32 s7, s6, 5
	s_add_u32 s5, s7, s5
	s_mul_i32 s5, s5, 0x6000
	s_add_u32 s24, s88, 0x103000
	s_addc_u32 s25, s89, 0
	s_add_u32 s24, s24, s5
	s_addc_u32 s25, s25, 0
	s_add_u32 s26, s24, 0x1000
	s_addc_u32 s27, s25, 0
	v_readlane_b32 s28, v252, 48
	v_readlane_b32 s29, v252, 49
	s_lshl_b32 s7, s6, 12
	s_nop 1
	s_add_u32 s28, s28, s7
	s_addc_u32 s29, s29, 0
	v_readlane_b32 s8, v252, 31
	v_readlane_b32 s9, v252, 32
	s_add_u32 s30, s88, 0x3400000
	s_addc_u32 s31, s89, 0
	s_nop 1
	s_cmp_gt_u32 s42, 0x8000
	s_cselect_b32 s2, 1, 0
	s_cmp_lt_u32 s4, 0x400
	s_cselect_b32 s2, s2, 0
	s_and_b32 s7, s4, 0x3ff
	s_lshl_b32 s5, s7, 12
	s_add_u32 s30, s30, s5
	s_addc_u32 s31, s31, 0
	s_lshl_b32 s5, s4, 16
	s_add_u32 s8, s8, s5
	s_addc_u32 s9, s9, 0
	s_add_u32 s10, s88, 0x3800000
	s_addc_u32 s11, s89, 0
	s_lshl_b32 s5, s4, 15
	s_add_u32 s10, s10, s5
	s_addc_u32 s11, s11, 0
	s_mov_b32 s32, 0x3a800000
	global_load_dwordx4 v[24:27], v1, s[28:29]
	global_load_dwordx4 v[28:31], v1, s[28:29] offset:16
	global_load_dwordx4 v[32:35], v1, s[28:29] offset:2048
	global_load_dwordx4 v[36:39], v1, s[28:29] offset:2064
	global_load_dwordx4 v[40:43], v1, s[26:27]
	global_load_dwordx4 v[64:67], v1, s[26:27] offset:16
	global_load_dwordx4 v[68:71], v1, s[26:27] offset:2048
	global_load_dwordx4 v[72:75], v1, s[26:27] offset:2064
	global_load_dwordx4 v[80:83], v1, s[24:25]
	global_load_dwordx4 v[84:87], v1, s[24:25] offset:16
	global_load_dwordx4 v[88:91], v1, s[24:25] offset:2048
	global_load_dwordx4 v[92:95], v1, s[24:25] offset:2064
	global_load_dwordx4 v[96:99], v1, s[8:9]
	global_load_dwordx4 v[100:103], v1, s[8:9] offset:16
	global_load_dwordx4 v[104:107], v1, s[8:9] offset:2048
	global_load_dwordx4 v[108:111], v1, s[8:9] offset:2064
	s_add_u32 s8, s8, 0x1000
	s_addc_u32 s9, s9, 0
	global_load_dwordx4 v[112:115], v1, s[8:9]
	global_load_dwordx4 v[116:119], v1, s[8:9] offset:16
	global_load_dwordx4 v[120:123], v1, s[8:9] offset:2048
	global_load_dwordx4 v[124:127], v1, s[8:9] offset:2064
	s_add_u32 s8, s8, 0x1000
	s_addc_u32 s9, s9, 0
	global_load_dwordx4 v[128:131], v1, s[8:9]
	global_load_dwordx4 v[132:135], v1, s[8:9] offset:16
	global_load_dwordx4 v[136:139], v1, s[8:9] offset:2048
	global_load_dwordx4 v[140:143], v1, s[8:9] offset:2064
	s_add_u32 s8, s8, 0x1000
	s_addc_u32 s9, s9, 0
	global_load_dwordx4 v[144:147], v1, s[8:9]
	global_load_dwordx4 v[148:151], v1, s[8:9] offset:16
	global_load_dwordx4 v[152:155], v1, s[8:9] offset:2048
	global_load_dwordx4 v[156:159], v1, s[8:9] offset:2064
	s_add_u32 s8, s8, 0x1000
	s_addc_u32 s9, s9, 0
	global_load_dwordx4 v[164:167], v1, s[8:9]
	global_load_dwordx4 v[168:171], v1, s[8:9] offset:16
	global_load_dwordx4 v[172:175], v1, s[8:9] offset:2048
	global_load_dwordx4 v[176:179], v1, s[8:9] offset:2064
	s_add_u32 s8, s8, 0x1000
	s_addc_u32 s9, s9, 0
	global_load_dwordx4 v[180:183], v1, s[8:9]
	global_load_dwordx4 v[184:187], v1, s[8:9] offset:16
	global_load_dwordx4 v[188:191], v1, s[8:9] offset:2048
	global_load_dwordx4 v[192:195], v1, s[8:9] offset:2064
	s_add_u32 s8, s8, 0x1000
	s_addc_u32 s9, s9, 0
	global_load_dwordx4 v[196:199], v1, s[8:9]
	global_load_dwordx4 v[200:203], v1, s[8:9] offset:16
	global_load_dwordx4 v[204:207], v1, s[8:9] offset:2048
	global_load_dwordx4 v[208:211], v1, s[8:9] offset:2064
	s_add_u32 s8, s8, 0x1000
	s_addc_u32 s9, s9, 0
	global_load_dwordx4 v[212:215], v1, s[8:9]
	global_load_dwordx4 v[216:219], v1, s[8:9] offset:16
	global_load_dwordx4 v[220:223], v1, s[8:9] offset:2048
	global_load_dwordx4 v[224:227], v1, s[8:9] offset:2064
	s_add_u32 s8, s8, 0x1000
	s_addc_u32 s9, s9, 0
	s_waitcnt vmcnt(32)
	v_pk_add_f32 v[40:41], v[40:41], 1.0 op_sel_hi:[1,0]
	v_pk_add_f32 v[42:43], v[42:43], 1.0 op_sel_hi:[1,0]
	v_pk_add_f32 v[64:65], v[64:65], 1.0 op_sel_hi:[1,0]
	v_pk_add_f32 v[66:67], v[66:67], 1.0 op_sel_hi:[1,0]
	v_pk_add_f32 v[68:69], v[68:69], 1.0 op_sel_hi:[1,0]
	v_pk_add_f32 v[70:71], v[70:71], 1.0 op_sel_hi:[1,0]
	v_pk_add_f32 v[72:73], v[72:73], 1.0 op_sel_hi:[1,0]
	v_pk_add_f32 v[74:75], v[74:75], 1.0 op_sel_hi:[1,0]
	s_waitcnt vmcnt(16)
; DI unsigned pk2(float lo, float hi) { return f2bf(lo) | (f2bf(hi) << 16); }
; DI void norm_phase(const Args& A, int wave_s, int l, int which, int rows) {
;     ...
;             float ss = 0.f;
; #pragma unroll
;             for (int j = 0; j < 4; ++j) ss += (xv[rr][j].x * xv[rr][j].x + xv[rr][j].y * xv[rr][j].y) + (xv[rr][j].z * xv[rr][j].z + xv[rr][j].w * xv[rr][j].w);
;             ss = wave_sum(C.lane, ss);
;             const float rs = rsqrtf(ss * (1.f / 1024.f) + EPS);
; #pragma unroll
;             for (int j = 0; j < 4; ++j) { const int col = 4 * (C.lane + 64 * j);
;                 const f32x4 y = xv[rr][j] * rs * g[j] * (sc[j] + 1.f) + sh[j];
;                 v2u o; o.x = pk2(y.x, y.y); o.y = pk2(y.z, y.w);
;                 *(v2u*)(C.H + (size_t)m * 1024 + col) = o; }
	v_mul_f32_e32 v10, v96, v96
	v_fmac_f32_e32 v10, v97, v97
	v_fmac_f32_e32 v10, v98, v98
	v_fmac_f32_e32 v10, v99, v99
	v_fmac_f32_e32 v10, v100, v100
	v_fmac_f32_e32 v10, v101, v101
	v_fmac_f32_e32 v10, v102, v102
	v_fmac_f32_e32 v10, v103, v103
	v_fmac_f32_e32 v10, v104, v104
	v_fmac_f32_e32 v10, v105, v105
	v_fmac_f32_e32 v10, v106, v106
	v_fmac_f32_e32 v10, v107, v107
	v_fmac_f32_e32 v10, v108, v108
	v_fmac_f32_e32 v10, v109, v109
	v_fmac_f32_e32 v10, v110, v110
	v_fmac_f32_e32 v10, v111, v111
	v_mul_f32_e32 v11, v112, v112
	v_fmac_f32_e32 v11, v113, v113
	v_fmac_f32_e32 v11, v114, v114
	v_fmac_f32_e32 v11, v115, v115
	v_fmac_f32_e32 v11, v116, v116
	v_fmac_f32_e32 v11, v117, v117
	v_fmac_f32_e32 v11, v118, v118
	v_fmac_f32_e32 v11, v119, v119
	v_fmac_f32_e32 v11, v120, v120
	v_fmac_f32_e32 v11, v121, v121
	v_fmac_f32_e32 v11, v122, v122
	v_fmac_f32_e32 v11, v123, v123
	v_fmac_f32_e32 v11, v124, v124
	v_fmac_f32_e32 v11, v125, v125
	v_fmac_f32_e32 v11, v126, v126
	v_fmac_f32_e32 v11, v127, v127
	v_mul_f32_e32 v12, v128, v128
	v_fmac_f32_e32 v12, v129, v129
	v_fmac_f32_e32 v12, v130, v130
	v_fmac_f32_e32 v12, v131, v131
	v_fmac_f32_e32 v12, v132, v132
	v_fmac_f32_e32 v12, v133, v133
	v_fmac_f32_e32 v12, v134, v134
	v_fmac_f32_e32 v12, v135, v135
	v_fmac_f32_e32 v12, v136, v136
	v_fmac_f32_e32 v12, v137, v137
	v_fmac_f32_e32 v12, v138, v138
	v_fmac_f32_e32 v12, v139, v139
	v_fmac_f32_e32 v12, v140, v140
	v_fmac_f32_e32 v12, v141, v141
	v_fmac_f32_e32 v12, v142, v142
	v_fmac_f32_e32 v12, v143, v143
	v_mul_f32_e32 v13, v144, v144
	v_fmac_f32_e32 v13, v145, v145
	v_fmac_f32_e32 v13, v146, v146
	v_fmac_f32_e32 v13, v147, v147
	v_fmac_f32_e32 v13, v148, v148
	v_fmac_f32_e32 v13, v149, v149
	v_fmac_f32_e32 v13, v150, v150
	v_fmac_f32_e32 v13, v151, v151
	v_fmac_f32_e32 v13, v152, v152
	v_fmac_f32_e32 v13, v153, v153
	v_fmac_f32_e32 v13, v154, v154
	v_fmac_f32_e32 v13, v155, v155
	v_fmac_f32_e32 v13, v156, v156
	v_fmac_f32_e32 v13, v157, v157
	v_fmac_f32_e32 v13, v158, v158
	v_fmac_f32_e32 v13, v159, v159
	ds_bpermute_b32 v14, v4, v10
	ds_bpermute_b32 v15, v4, v11
	ds_bpermute_b32 v16, v4, v12
	ds_bpermute_b32 v17, v4, v13
	s_waitcnt lgkmcnt(0)
	v_add_f32_e32 v10, v10, v14
	v_add_f32_e32 v11, v11, v15
	v_add_f32_e32 v12, v12, v16
	v_add_f32_e32 v13, v13, v17
	ds_bpermute_b32 v14, v5, v10
	ds_bpermute_b32 v15, v5, v11
	ds_bpermute_b32 v16, v5, v12
	ds_bpermute_b32 v17, v5, v13
	s_waitcnt lgkmcnt(0)
	v_add_f32_e32 v10, v10, v14
	v_add_f32_e32 v11, v11, v15
	v_add_f32_e32 v12, v12, v16
	v_add_f32_e32 v13, v13, v17
	ds_bpermute_b32 v14, v6, v10
	ds_bpermute_b32 v15, v6, v11
	ds_bpermute_b32 v16, v6, v12
	ds_bpermute_b32 v17, v6, v13
	s_waitcnt lgkmcnt(0)
	v_add_f32_e32 v10, v10, v14
	v_add_f32_e32 v11, v11, v15
	v_add_f32_e32 v12, v12, v16
	v_add_f32_e32 v13, v13, v17
	ds_bpermute_b32 v14, v7, v10
	ds_bpermute_b32 v15, v7, v11
	ds_bpermute_b32 v16, v7, v12
	ds_bpermute_b32 v17, v7, v13
	s_waitcnt lgkmcnt(0)
	v_add_f32_e32 v10, v10, v14
	v_add_f32_e32 v11, v11, v15
	v_add_f32_e32 v12, v12, v16
	v_add_f32_e32 v13, v13, v17
	ds_bpermute_b32 v14, v8, v10
	ds_bpermute_b32 v15, v8, v11
	ds_bpermute_b32 v16, v8, v12
	ds_bpermute_b32 v17, v8, v13
	s_waitcnt lgkmcnt(0)
	v_add_f32_e32 v10, v10, v14
	v_add_f32_e32 v11, v11, v15
	v_add_f32_e32 v12, v12, v16
	v_add_f32_e32 v13, v13, v17
	ds_bpermute_b32 v14, v9, v10
	ds_bpermute_b32 v15, v9, v11
	ds_bpermute_b32 v16, v9, v12
	ds_bpermute_b32 v17, v9, v13
	s_waitcnt lgkmcnt(0)
	v_add_f32_e32 v10, v10, v14
	v_add_f32_e32 v11, v11, v15
	v_add_f32_e32 v12, v12, v16
	v_add_f32_e32 v13, v13, v17
	v_fma_f32 v10, v10, s32, v60
	v_fma_f32 v11, v11, s32, v60
	v_fma_f32 v12, v12, s32, v60
	v_fma_f32 v13, v13, s32, v60
	v_rsq_f32_e32 v18, v10
	v_rsq_f32_e32 v20, v11
	v_rsq_f32_e32 v22, v12
	v_rsq_f32_e32 v62, v13
	s_nop 0
	v_pk_mul_f32 v[96:97], v[96:97], v[18:19] op_sel_hi:[1,0]
	v_pk_mul_f32 v[98:99], v[98:99], v[18:19] op_sel_hi:[1,0]
	v_pk_mul_f32 v[100:101], v[100:101], v[18:19] op_sel_hi:[1,0]
	v_pk_mul_f32 v[102:103], v[102:103], v[18:19] op_sel_hi:[1,0]
	v_pk_mul_f32 v[104:105], v[104:105], v[18:19] op_sel_hi:[1,0]
	v_pk_mul_f32 v[106:107], v[106:107], v[18:19] op_sel_hi:[1,0]
	v_pk_mul_f32 v[108:109], v[108:109], v[18:19] op_sel_hi:[1,0]
	v_pk_mul_f32 v[110:111], v[110:111], v[18:19] op_sel_hi:[1,0]
	v_pk_mul_f32 v[96:97], v[24:25], v[96:97]
	v_pk_mul_f32 v[98:99], v[26:27], v[98:99]
	v_pk_mul_f32 v[100:101], v[28:29], v[100:101]
	v_pk_mul_f32 v[102:103], v[30:31], v[102:103]
	v_pk_mul_f32 v[104:105], v[32:33], v[104:105]
	v_pk_mul_f32 v[106:107], v[34:35], v[106:107]
	v_pk_mul_f32 v[108:109], v[36:37], v[108:109]
	v_pk_mul_f32 v[110:111], v[38:39], v[110:111]
	v_pk_fma_f32 v[96:97], v[40:41], v[96:97], v[80:81]
	v_pk_fma_f32 v[98:99], v[42:43], v[98:99], v[82:83]
	v_pk_fma_f32 v[100:101], v[64:65], v[100:101], v[84:85]
	v_pk_fma_f32 v[102:103], v[66:67], v[102:103], v[86:87]
	v_pk_fma_f32 v[104:105], v[68:69], v[104:105], v[88:89]
	v_pk_fma_f32 v[106:107], v[70:71], v[106:107], v[90:91]
	v_pk_fma_f32 v[108:109], v[72:73], v[108:109], v[92:93]
	v_pk_fma_f32 v[110:111], v[74:75], v[110:111], v[94:95]
	v_cvt_pk_bf16_f32 v96, v96, v97
	v_cvt_pk_bf16_f32 v97, v98, v99
	v_cvt_pk_bf16_f32 v98, v100, v101
	v_cvt_pk_bf16_f32 v99, v102, v103
	v_cvt_pk_bf16_f32 v104, v104, v105
	v_cvt_pk_bf16_f32 v105, v106, v107
	v_cvt_pk_bf16_f32 v106, v108, v109
	v_cvt_pk_bf16_f32 v107, v110, v111
	global_store_dwordx4 v2, v[96:99], s[10:11] sc1
	global_store_dwordx4 v2, v[104:107], s[10:11] offset:1024 sc1
	s_add_u32 s10, s10, 0x800
	s_addc_u32 s11, s11, 0
	v_pk_mul_f32 v[112:113], v[112:113], v[20:21] op_sel_hi:[1,0]
; DI unsigned pk2(float lo, float hi) { return f2bf(lo) | (f2bf(hi) << 16); }
; DI void norm_phase(const Args& A, int wave_s, int l, int which, int rows) {
;     ...
;         for (int rr = 0; rr < 2; ++rr) {
;             const int m = m0 + rr; const float* xr; int v;
;             if (m < NLAT) { xr = (from_in ? C.x : C.out) + (size_t)m * 1024; v = m >> 13; }
;             else { xr = (from_in ? C.ctx : C.XC) + (size_t)(m - NLAT) * 1024; v = 4; }
;             modp[rr] = C.SM + SM_MOD + (l * 5 + v) * 6144 + (which == 1 ? 0 : 3072);
; #pragma unroll
;             for (int j = 0; j < 4; ++j) xv[rr][j] = ((const f32x4*)xr)[C.lane + 64 * j];
;     ...
;             for (int j = 0; j < 4; ++j) { const int col = 4 * (C.lane + 64 * j);
;                 const f32x4 y = xv[rr][j] * rs * g[j] * (sc[j] + 1.f) + sh[j];
;                 v2u o; o.x = pk2(y.x, y.y); o.y = pk2(y.z, y.w);
;                 *(v2u*)(C.H + (size_t)m * 1024 + col) = o; }
	v_pk_mul_f32 v[114:115], v[114:115], v[20:21] op_sel_hi:[1,0]
	v_pk_mul_f32 v[116:117], v[116:117], v[20:21] op_sel_hi:[1,0]
	v_pk_mul_f32 v[118:119], v[118:119], v[20:21] op_sel_hi:[1,0]
	v_pk_mul_f32 v[120:121], v[120:121], v[20:21] op_sel_hi:[1,0]
	v_pk_mul_f32 v[122:123], v[122:123], v[20:21] op_sel_hi:[1,0]
	v_pk_mul_f32 v[124:125], v[124:125], v[20:21] op_sel_hi:[1,0]
	v_pk_mul_f32 v[126:127], v[126:127], v[20:21] op_sel_hi:[1,0]
	v_pk_mul_f32 v[112:113], v[24:25], v[112:113]
	v_pk_mul_f32 v[114:115], v[26:27], v[114:115]
	v_pk_mul_f32 v[116:117], v[28:29], v[116:117]
	v_pk_mul_f32 v[118:119], v[30:31], v[118:119]
	v_pk_mul_f32 v[120:121], v[32:33], v[120:121]
	v_pk_mul_f32 v[122:123], v[34:35], v[122:123]
	v_pk_mul_f32 v[124:125], v[36:37], v[124:125]
	v_pk_mul_f32 v[126:127], v[38:39], v[126:127]
	v_pk_fma_f32 v[112:113], v[40:41], v[112:113], v[80:81]
	v_pk_fma_f32 v[114:115], v[42:43], v[114:115], v[82:83]
	v_pk_fma_f32 v[116:117], v[64:65], v[116:117], v[84:85]
	v_pk_fma_f32 v[118:119], v[66:67], v[118:119], v[86:87]
	v_pk_fma_f32 v[120:121], v[68:69], v[120:121], v[88:89]
	v_pk_fma_f32 v[122:123], v[70:71], v[122:123], v[90:91]
	v_pk_fma_f32 v[124:125], v[72:73], v[124:125], v[92:93]
	v_pk_fma_f32 v[126:127], v[74:75], v[126:127], v[94:95]
	v_cvt_pk_bf16_f32 v112, v112, v113
	v_cvt_pk_bf16_f32 v113, v114, v115
	v_cvt_pk_bf16_f32 v114, v116, v117
	v_cvt_pk_bf16_f32 v115, v118, v119
	v_cvt_pk_bf16_f32 v120, v120, v121
	v_cvt_pk_bf16_f32 v121, v122, v123
	v_cvt_pk_bf16_f32 v122, v124, v125
	v_cvt_pk_bf16_f32 v123, v126, v127
	global_store_dwordx4 v2, v[112:115], s[10:11] sc1
	global_store_dwordx4 v2, v[120:123], s[10:11] offset:1024 sc1
	s_add_u32 s10, s10, 0x800
	s_addc_u32 s11, s11, 0
	v_pk_mul_f32 v[128:129], v[128:129], v[22:23] op_sel_hi:[1,0]
	v_pk_mul_f32 v[130:131], v[130:131], v[22:23] op_sel_hi:[1,0]
	v_pk_mul_f32 v[132:133], v[132:133], v[22:23] op_sel_hi:[1,0]
	v_pk_mul_f32 v[134:135], v[134:135], v[22:23] op_sel_hi:[1,0]
	v_pk_mul_f32 v[136:137], v[136:137], v[22:23] op_sel_hi:[1,0]
	v_pk_mul_f32 v[138:139], v[138:139], v[22:23] op_sel_hi:[1,0]
	v_pk_mul_f32 v[140:141], v[140:141], v[22:23] op_sel_hi:[1,0]
	v_pk_mul_f32 v[142:143], v[142:143], v[22:23] op_sel_hi:[1,0]
	v_pk_mul_f32 v[128:129], v[24:25], v[128:129]
	v_pk_mul_f32 v[130:131], v[26:27], v[130:131]
	v_pk_mul_f32 v[132:133], v[28:29], v[132:133]
	v_pk_mul_f32 v[134:135], v[30:31], v[134:135]
	v_pk_mul_f32 v[136:137], v[32:33], v[136:137]
	v_pk_mul_f32 v[138:139], v[34:35], v[138:139]
	v_pk_mul_f32 v[140:141], v[36:37], v[140:141]
	v_pk_mul_f32 v[142:143], v[38:39], v[142:143]
	v_pk_fma_f32 v[128:129], v[40:41], v[128:129], v[80:81]
	v_pk_fma_f32 v[130:131], v[42:43], v[130:131], v[82:83]
	v_pk_fma_f32 v[132:133], v[64:65], v[132:133], v[84:85]
	v_pk_fma_f32 v[134:135], v[66:67], v[134:135], v[86:87]
	v_pk_fma_f32 v[136:137], v[68:69], v[136:137], v[88:89]
	v_pk_fma_f32 v[138:139], v[70:71], v[138:139], v[90:91]
	v_pk_fma_f32 v[140:141], v[72:73], v[140:141], v[92:93]
	v_pk_fma_f32 v[142:143], v[74:75], v[142:143], v[94:95]
	v_cvt_pk_bf16_f32 v128, v128, v129
	v_cvt_pk_bf16_f32 v129, v130, v131
	v_cvt_pk_bf16_f32 v130, v132, v133
	v_cvt_pk_bf16_f32 v131, v134, v135
	v_cvt_pk_bf16_f32 v136, v136, v137
	v_cvt_pk_bf16_f32 v137, v138, v139
	v_cvt_pk_bf16_f32 v138, v140, v141
	v_cvt_pk_bf16_f32 v139, v142, v143
	global_store_dwordx4 v2, v[128:131], s[10:11] sc1
	global_store_dwordx4 v2, v[136:139], s[10:11] offset:1024 sc1
	s_add_u32 s10, s10, 0x800
	s_addc_u32 s11, s11, 0
	v_pk_mul_f32 v[144:145], v[144:145], v[62:63] op_sel_hi:[1,0]
	v_pk_mul_f32 v[146:147], v[146:147], v[62:63] op_sel_hi:[1,0]
	v_pk_mul_f32 v[148:149], v[148:149], v[62:63] op_sel_hi:[1,0]
	v_pk_mul_f32 v[150:151], v[150:151], v[62:63] op_sel_hi:[1,0]
	v_pk_mul_f32 v[152:153], v[152:153], v[62:63] op_sel_hi:[1,0]
	v_pk_mul_f32 v[154:155], v[154:155], v[62:63] op_sel_hi:[1,0]
	v_pk_mul_f32 v[156:157], v[156:157], v[62:63] op_sel_hi:[1,0]
	v_pk_mul_f32 v[158:159], v[158:159], v[62:63] op_sel_hi:[1,0]
	v_pk_mul_f32 v[144:145], v[24:25], v[144:145]
	v_pk_mul_f32 v[146:147], v[26:27], v[146:147]
	v_pk_mul_f32 v[148:149], v[28:29], v[148:149]
	v_pk_mul_f32 v[150:151], v[30:31], v[150:151]
	v_pk_mul_f32 v[152:153], v[32:33], v[152:153]
	v_pk_mul_f32 v[154:155], v[34:35], v[154:155]
	v_pk_mul_f32 v[156:157], v[36:37], v[156:157]
	v_pk_mul_f32 v[158:159], v[38:39], v[158:159]
	v_pk_fma_f32 v[144:145], v[40:41], v[144:145], v[80:81]
	v_pk_fma_f32 v[146:147], v[42:43], v[146:147], v[82:83]
	v_pk_fma_f32 v[148:149], v[64:65], v[148:149], v[84:85]
	v_pk_fma_f32 v[150:151], v[66:67], v[150:151], v[86:87]
	v_pk_fma_f32 v[152:153], v[68:69], v[152:153], v[88:89]
	v_pk_fma_f32 v[154:155], v[70:71], v[154:155], v[90:91]
	v_pk_fma_f32 v[156:157], v[72:73], v[156:157], v[92:93]
	v_pk_fma_f32 v[158:159], v[74:75], v[158:159], v[94:95]
	v_cvt_pk_bf16_f32 v144, v144, v145
	v_cvt_pk_bf16_f32 v145, v146, v147
	v_cvt_pk_bf16_f32 v146, v148, v149
	v_cvt_pk_bf16_f32 v147, v150, v151
	v_cvt_pk_bf16_f32 v152, v152, v153
	v_cvt_pk_bf16_f32 v153, v154, v155
	v_cvt_pk_bf16_f32 v154, v156, v157
	v_cvt_pk_bf16_f32 v155, v158, v159
	global_store_dwordx4 v2, v[144:147], s[10:11] sc1
	global_store_dwordx4 v2, v[152:155], s[10:11] offset:1024 sc1
	s_add_u32 s10, s10, 0x800
	s_addc_u32 s11, s11, 0
	global_load_dwordx4 v[96:99], v1, s[8:9]
	global_load_dwordx4 v[100:103], v1, s[8:9] offset:16
	global_load_dwordx4 v[104:107], v1, s[8:9] offset:2048
	global_load_dwordx4 v[108:111], v1, s[8:9] offset:2064
	s_add_u32 s8, s8, 0x1000
	s_addc_u32 s9, s9, 0
	global_load_dwordx4 v[112:115], v1, s[8:9]
	global_load_dwordx4 v[116:119], v1, s[8:9] offset:16
	global_load_dwordx4 v[120:123], v1, s[8:9] offset:2048
	global_load_dwordx4 v[124:127], v1, s[8:9] offset:2064
	s_add_u32 s8, s8, 0x1000
	s_addc_u32 s9, s9, 0
	global_load_dwordx4 v[128:131], v1, s[8:9]
	global_load_dwordx4 v[132:135], v1, s[8:9] offset:16
	global_load_dwordx4 v[136:139], v1, s[8:9] offset:2048
	global_load_dwordx4 v[140:143], v1, s[8:9] offset:2064
	s_add_u32 s8, s8, 0x1000
	s_addc_u32 s9, s9, 0
	global_load_dwordx4 v[144:147], v1, s[8:9]
	global_load_dwordx4 v[148:151], v1, s[8:9] offset:16
	global_load_dwordx4 v[152:155], v1, s[8:9] offset:2048
	global_load_dwordx4 v[156:159], v1, s[8:9] offset:2064
	s_add_u32 s8, s8, 0x1000
	s_addc_u32 s9, s9, 0
	s_waitcnt vmcnt(24)
; DI unsigned pk2(float lo, float hi) { return f2bf(lo) | (f2bf(hi) << 16); }
; DI void norm_phase(const Args& A, int wave_s, int l, int which, int rows) {
;     ...
;             float ss = 0.f;
; #pragma unroll
;             for (int j = 0; j < 4; ++j) ss += (xv[rr][j].x * xv[rr][j].x + xv[rr][j].y * xv[rr][j].y) + (xv[rr][j].z * xv[rr][j].z + xv[rr][j].w * xv[rr][j].w);
;             ss = wave_sum(C.lane, ss);
;             const float rs = rsqrtf(ss * (1.f / 1024.f) + EPS);
; #pragma unroll
;             for (int j = 0; j < 4; ++j) { const int col = 4 * (C.lane + 64 * j);
;                 const f32x4 y = xv[rr][j] * rs * g[j] * (sc[j] + 1.f) + sh[j];
;                 v2u o; o.x = pk2(y.x, y.y); o.y = pk2(y.z, y.w);
;                 *(v2u*)(C.H + (size_t)m * 1024 + col) = o; }
	v_mul_f32_e32 v10, v164, v164
	v_fmac_f32_e32 v10, v165, v165
	v_fmac_f32_e32 v10, v166, v166
	v_fmac_f32_e32 v10, v167, v167
	v_fmac_f32_e32 v10, v168, v168
	v_fmac_f32_e32 v10, v169, v169
	v_fmac_f32_e32 v10, v170, v170
	v_fmac_f32_e32 v10, v171, v171
	v_fmac_f32_e32 v10, v172, v172
	v_fmac_f32_e32 v10, v173, v173
	v_fmac_f32_e32 v10, v174, v174
	v_fmac_f32_e32 v10, v175, v175
	v_fmac_f32_e32 v10, v176, v176
	v_fmac_f32_e32 v10, v177, v177
	v_fmac_f32_e32 v10, v178, v178
	v_fmac_f32_e32 v10, v179, v179
	v_mul_f32_e32 v11, v180, v180
	v_fmac_f32_e32 v11, v181, v181
	v_fmac_f32_e32 v11, v182, v182
	v_fmac_f32_e32 v11, v183, v183
	v_fmac_f32_e32 v11, v184, v184
	v_fmac_f32_e32 v11, v185, v185
	v_fmac_f32_e32 v11, v186, v186
	v_fmac_f32_e32 v11, v187, v187
	v_fmac_f32_e32 v11, v188, v188
	v_fmac_f32_e32 v11, v189, v189
	v_fmac_f32_e32 v11, v190, v190
	v_fmac_f32_e32 v11, v191, v191
	v_fmac_f32_e32 v11, v192, v192
	v_fmac_f32_e32 v11, v193, v193
	v_fmac_f32_e32 v11, v194, v194
	v_fmac_f32_e32 v11, v195, v195
	v_mul_f32_e32 v12, v196, v196
	v_fmac_f32_e32 v12, v197, v197
	v_fmac_f32_e32 v12, v198, v198
	v_fmac_f32_e32 v12, v199, v199
	v_fmac_f32_e32 v12, v200, v200
	v_fmac_f32_e32 v12, v201, v201
	v_fmac_f32_e32 v12, v202, v202
	v_fmac_f32_e32 v12, v203, v203
	v_fmac_f32_e32 v12, v204, v204
	v_fmac_f32_e32 v12, v205, v205
	v_fmac_f32_e32 v12, v206, v206
	v_fmac_f32_e32 v12, v207, v207
	v_fmac_f32_e32 v12, v208, v208
	v_fmac_f32_e32 v12, v209, v209
	v_fmac_f32_e32 v12, v210, v210
	v_fmac_f32_e32 v12, v211, v211
	v_mul_f32_e32 v13, v212, v212
	v_fmac_f32_e32 v13, v213, v213
	v_fmac_f32_e32 v13, v214, v214
	v_fmac_f32_e32 v13, v215, v215
	v_fmac_f32_e32 v13, v216, v216
	v_fmac_f32_e32 v13, v217, v217
	v_fmac_f32_e32 v13, v218, v218
	v_fmac_f32_e32 v13, v219, v219
	v_fmac_f32_e32 v13, v220, v220
	v_fmac_f32_e32 v13, v221, v221
	v_fmac_f32_e32 v13, v222, v222
	v_fmac_f32_e32 v13, v223, v223
	v_fmac_f32_e32 v13, v224, v224
	v_fmac_f32_e32 v13, v225, v225
	v_fmac_f32_e32 v13, v226, v226
	v_fmac_f32_e32 v13, v227, v227
	ds_bpermute_b32 v14, v4, v10
	ds_bpermute_b32 v15, v4, v11
	ds_bpermute_b32 v16, v4, v12
	ds_bpermute_b32 v17, v4, v13
	s_waitcnt lgkmcnt(0)
	v_add_f32_e32 v10, v10, v14
	v_add_f32_e32 v11, v11, v15
	v_add_f32_e32 v12, v12, v16
	v_add_f32_e32 v13, v13, v17
	ds_bpermute_b32 v14, v5, v10
	ds_bpermute_b32 v15, v5, v11
	ds_bpermute_b32 v16, v5, v12
	ds_bpermute_b32 v17, v5, v13
	s_waitcnt lgkmcnt(0)
	v_add_f32_e32 v10, v10, v14
	v_add_f32_e32 v11, v11, v15
	v_add_f32_e32 v12, v12, v16
	v_add_f32_e32 v13, v13, v17
	ds_bpermute_b32 v14, v6, v10
	ds_bpermute_b32 v15, v6, v11
	ds_bpermute_b32 v16, v6, v12
	ds_bpermute_b32 v17, v6, v13
	s_waitcnt lgkmcnt(0)
	v_add_f32_e32 v10, v10, v14
	v_add_f32_e32 v11, v11, v15
	v_add_f32_e32 v12, v12, v16
	v_add_f32_e32 v13, v13, v17
	ds_bpermute_b32 v14, v7, v10
	ds_bpermute_b32 v15, v7, v11
	ds_bpermute_b32 v16, v7, v12
	ds_bpermute_b32 v17, v7, v13
	s_waitcnt lgkmcnt(0)
	v_add_f32_e32 v10, v10, v14
	v_add_f32_e32 v11, v11, v15
	v_add_f32_e32 v12, v12, v16
	v_add_f32_e32 v13, v13, v17
	ds_bpermute_b32 v14, v8, v10
	ds_bpermute_b32 v15, v8, v11
	ds_bpermute_b32 v16, v8, v12
	ds_bpermute_b32 v17, v8, v13
	s_waitcnt lgkmcnt(0)
	v_add_f32_e32 v10, v10, v14
	v_add_f32_e32 v11, v11, v15
	v_add_f32_e32 v12, v12, v16
	v_add_f32_e32 v13, v13, v17
	ds_bpermute_b32 v14, v9, v10
	ds_bpermute_b32 v15, v9, v11
	ds_bpermute_b32 v16, v9, v12
	ds_bpermute_b32 v17, v9, v13
	s_waitcnt lgkmcnt(0)
	v_add_f32_e32 v10, v10, v14
	v_add_f32_e32 v11, v11, v15
	v_add_f32_e32 v12, v12, v16
	v_add_f32_e32 v13, v13, v17
	v_fma_f32 v10, v10, s32, v60
	v_fma_f32 v11, v11, s32, v60
	v_fma_f32 v12, v12, s32, v60
	v_fma_f32 v13, v13, s32, v60
	v_rsq_f32_e32 v18, v10
	v_rsq_f32_e32 v20, v11
	v_rsq_f32_e32 v22, v12
	v_rsq_f32_e32 v62, v13
	s_nop 0
	v_pk_mul_f32 v[164:165], v[164:165], v[18:19] op_sel_hi:[1,0]
	v_pk_mul_f32 v[166:167], v[166:167], v[18:19] op_sel_hi:[1,0]
	v_pk_mul_f32 v[168:169], v[168:169], v[18:19] op_sel_hi:[1,0]
	v_pk_mul_f32 v[170:171], v[170:171], v[18:19] op_sel_hi:[1,0]
	v_pk_mul_f32 v[172:173], v[172:173], v[18:19] op_sel_hi:[1,0]
	v_pk_mul_f32 v[174:175], v[174:175], v[18:19] op_sel_hi:[1,0]
	v_pk_mul_f32 v[176:177], v[176:177], v[18:19] op_sel_hi:[1,0]
	v_pk_mul_f32 v[178:179], v[178:179], v[18:19] op_sel_hi:[1,0]
	v_pk_mul_f32 v[164:165], v[24:25], v[164:165]
	v_pk_mul_f32 v[166:167], v[26:27], v[166:167]
	v_pk_mul_f32 v[168:169], v[28:29], v[168:169]
	v_pk_mul_f32 v[170:171], v[30:31], v[170:171]
	v_pk_mul_f32 v[172:173], v[32:33], v[172:173]
	v_pk_mul_f32 v[174:175], v[34:35], v[174:175]
	v_pk_mul_f32 v[176:177], v[36:37], v[176:177]
	v_pk_mul_f32 v[178:179], v[38:39], v[178:179]
	v_pk_fma_f32 v[164:165], v[40:41], v[164:165], v[80:81]
	v_pk_fma_f32 v[166:167], v[42:43], v[166:167], v[82:83]
	v_pk_fma_f32 v[168:169], v[64:65], v[168:169], v[84:85]
	v_pk_fma_f32 v[170:171], v[66:67], v[170:171], v[86:87]
	v_pk_fma_f32 v[172:173], v[68:69], v[172:173], v[88:89]
	v_pk_fma_f32 v[174:175], v[70:71], v[174:175], v[90:91]
	v_pk_fma_f32 v[176:177], v[72:73], v[176:177], v[92:93]
	v_pk_fma_f32 v[178:179], v[74:75], v[178:179], v[94:95]
	v_cvt_pk_bf16_f32 v164, v164, v165
	v_cvt_pk_bf16_f32 v165, v166, v167
	v_cvt_pk_bf16_f32 v166, v168, v169
	v_cvt_pk_bf16_f32 v167, v170, v171
	v_cvt_pk_bf16_f32 v172, v172, v173
	v_cvt_pk_bf16_f32 v173, v174, v175
	v_cvt_pk_bf16_f32 v174, v176, v177
	v_cvt_pk_bf16_f32 v175, v178, v179
	global_store_dwordx4 v2, v[164:167], s[10:11] sc1
	global_store_dwordx4 v2, v[172:175], s[10:11] offset:1024 sc1
	s_add_u32 s10, s10, 0x800
	s_addc_u32 s11, s11, 0
	v_pk_mul_f32 v[180:181], v[180:181], v[20:21] op_sel_hi:[1,0]
; DI unsigned pk2(float lo, float hi) { return f2bf(lo) | (f2bf(hi) << 16); }
; DI void norm_phase(const Args& A, int wave_s, int l, int which, int rows) {
;     ...
;         for (int rr = 0; rr < 2; ++rr) {
;             const int m = m0 + rr; const float* xr; int v;
;             if (m < NLAT) { xr = (from_in ? C.x : C.out) + (size_t)m * 1024; v = m >> 13; }
;             else { xr = (from_in ? C.ctx : C.XC) + (size_t)(m - NLAT) * 1024; v = 4; }
;             modp[rr] = C.SM + SM_MOD + (l * 5 + v) * 6144 + (which == 1 ? 0 : 3072);
; #pragma unroll
;             for (int j = 0; j < 4; ++j) xv[rr][j] = ((const f32x4*)xr)[C.lane + 64 * j];
;     ...
;             for (int j = 0; j < 4; ++j) { const int col = 4 * (C.lane + 64 * j);
;                 const f32x4 y = xv[rr][j] * rs * g[j] * (sc[j] + 1.f) + sh[j];
;                 v2u o; o.x = pk2(y.x, y.y); o.y = pk2(y.z, y.w);
;                 *(v2u*)(C.H + (size_t)m * 1024 + col) = o; }
	v_pk_mul_f32 v[182:183], v[182:183], v[20:21] op_sel_hi:[1,0]
	v_pk_mul_f32 v[184:185], v[184:185], v[20:21] op_sel_hi:[1,0]
	v_pk_mul_f32 v[186:187], v[186:187], v[20:21] op_sel_hi:[1,0]
	v_pk_mul_f32 v[188:189], v[188:189], v[20:21] op_sel_hi:[1,0]
	v_pk_mul_f32 v[190:191], v[190:191], v[20:21] op_sel_hi:[1,0]
	v_pk_mul_f32 v[192:193], v[192:193], v[20:21] op_sel_hi:[1,0]
	v_pk_mul_f32 v[194:195], v[194:195], v[20:21] op_sel_hi:[1,0]
	v_pk_mul_f32 v[180:181], v[24:25], v[180:181]
	v_pk_mul_f32 v[182:183], v[26:27], v[182:183]
	v_pk_mul_f32 v[184:185], v[28:29], v[184:185]
	v_pk_mul_f32 v[186:187], v[30:31], v[186:187]
	v_pk_mul_f32 v[188:189], v[32:33], v[188:189]
	v_pk_mul_f32 v[190:191], v[34:35], v[190:191]
	v_pk_mul_f32 v[192:193], v[36:37], v[192:193]
	v_pk_mul_f32 v[194:195], v[38:39], v[194:195]
	v_pk_fma_f32 v[180:181], v[40:41], v[180:181], v[80:81]
	v_pk_fma_f32 v[182:183], v[42:43], v[182:183], v[82:83]
	v_pk_fma_f32 v[184:185], v[64:65], v[184:185], v[84:85]
	v_pk_fma_f32 v[186:187], v[66:67], v[186:187], v[86:87]
	v_pk_fma_f32 v[188:189], v[68:69], v[188:189], v[88:89]
	v_pk_fma_f32 v[190:191], v[70:71], v[190:191], v[90:91]
	v_pk_fma_f32 v[192:193], v[72:73], v[192:193], v[92:93]
	v_pk_fma_f32 v[194:195], v[74:75], v[194:195], v[94:95]
	v_cvt_pk_bf16_f32 v180, v180, v181
	v_cvt_pk_bf16_f32 v181, v182, v183
	v_cvt_pk_bf16_f32 v182, v184, v185
	v_cvt_pk_bf16_f32 v183, v186, v187
	v_cvt_pk_bf16_f32 v188, v188, v189
	v_cvt_pk_bf16_f32 v189, v190, v191
	v_cvt_pk_bf16_f32 v190, v192, v193
	v_cvt_pk_bf16_f32 v191, v194, v195
	global_store_dwordx4 v2, v[180:183], s[10:11] sc1
	global_store_dwordx4 v2, v[188:191], s[10:11] offset:1024 sc1
	s_add_u32 s10, s10, 0x800
	s_addc_u32 s11, s11, 0
	v_pk_mul_f32 v[196:197], v[196:197], v[22:23] op_sel_hi:[1,0]
	v_pk_mul_f32 v[198:199], v[198:199], v[22:23] op_sel_hi:[1,0]
	v_pk_mul_f32 v[200:201], v[200:201], v[22:23] op_sel_hi:[1,0]
	v_pk_mul_f32 v[202:203], v[202:203], v[22:23] op_sel_hi:[1,0]
	v_pk_mul_f32 v[204:205], v[204:205], v[22:23] op_sel_hi:[1,0]
	v_pk_mul_f32 v[206:207], v[206:207], v[22:23] op_sel_hi:[1,0]
	v_pk_mul_f32 v[208:209], v[208:209], v[22:23] op_sel_hi:[1,0]
	v_pk_mul_f32 v[210:211], v[210:211], v[22:23] op_sel_hi:[1,0]
	v_pk_mul_f32 v[196:197], v[24:25], v[196:197]
	v_pk_mul_f32 v[198:199], v[26:27], v[198:199]
	v_pk_mul_f32 v[200:201], v[28:29], v[200:201]
	v_pk_mul_f32 v[202:203], v[30:31], v[202:203]
	v_pk_mul_f32 v[204:205], v[32:33], v[204:205]
	v_pk_mul_f32 v[206:207], v[34:35], v[206:207]
	v_pk_mul_f32 v[208:209], v[36:37], v[208:209]
	v_pk_mul_f32 v[210:211], v[38:39], v[210:211]
	v_pk_fma_f32 v[196:197], v[40:41], v[196:197], v[80:81]
	v_pk_fma_f32 v[198:199], v[42:43], v[198:199], v[82:83]
	v_pk_fma_f32 v[200:201], v[64:65], v[200:201], v[84:85]
	v_pk_fma_f32 v[202:203], v[66:67], v[202:203], v[86:87]
	v_pk_fma_f32 v[204:205], v[68:69], v[204:205], v[88:89]
	v_pk_fma_f32 v[206:207], v[70:71], v[206:207], v[90:91]
	v_pk_fma_f32 v[208:209], v[72:73], v[208:209], v[92:93]
	v_pk_fma_f32 v[210:211], v[74:75], v[210:211], v[94:95]
	v_cvt_pk_bf16_f32 v196, v196, v197
	v_cvt_pk_bf16_f32 v197, v198, v199
	v_cvt_pk_bf16_f32 v198, v200, v201
	v_cvt_pk_bf16_f32 v199, v202, v203
	v_cvt_pk_bf16_f32 v204, v204, v205
	v_cvt_pk_bf16_f32 v205, v206, v207
	v_cvt_pk_bf16_f32 v206, v208, v209
	v_cvt_pk_bf16_f32 v207, v210, v211
	global_store_dwordx4 v2, v[196:199], s[10:11] sc1
	global_store_dwordx4 v2, v[204:207], s[10:11] offset:1024 sc1
	s_add_u32 s10, s10, 0x800
	s_addc_u32 s11, s11, 0
	v_pk_mul_f32 v[212:213], v[212:213], v[62:63] op_sel_hi:[1,0]
	v_pk_mul_f32 v[214:215], v[214:215], v[62:63] op_sel_hi:[1,0]
	v_pk_mul_f32 v[216:217], v[216:217], v[62:63] op_sel_hi:[1,0]
	v_pk_mul_f32 v[218:219], v[218:219], v[62:63] op_sel_hi:[1,0]
	v_pk_mul_f32 v[220:221], v[220:221], v[62:63] op_sel_hi:[1,0]
	v_pk_mul_f32 v[222:223], v[222:223], v[62:63] op_sel_hi:[1,0]
	v_pk_mul_f32 v[224:225], v[224:225], v[62:63] op_sel_hi:[1,0]
	v_pk_mul_f32 v[226:227], v[226:227], v[62:63] op_sel_hi:[1,0]
	v_pk_mul_f32 v[212:213], v[24:25], v[212:213]
	v_pk_mul_f32 v[214:215], v[26:27], v[214:215]
	v_pk_mul_f32 v[216:217], v[28:29], v[216:217]
	v_pk_mul_f32 v[218:219], v[30:31], v[218:219]
	v_pk_mul_f32 v[220:221], v[32:33], v[220:221]
	v_pk_mul_f32 v[222:223], v[34:35], v[222:223]
	v_pk_mul_f32 v[224:225], v[36:37], v[224:225]
	v_pk_mul_f32 v[226:227], v[38:39], v[226:227]
	v_pk_fma_f32 v[212:213], v[40:41], v[212:213], v[80:81]
	v_pk_fma_f32 v[214:215], v[42:43], v[214:215], v[82:83]
	v_pk_fma_f32 v[216:217], v[64:65], v[216:217], v[84:85]
	v_pk_fma_f32 v[218:219], v[66:67], v[218:219], v[86:87]
	v_pk_fma_f32 v[220:221], v[68:69], v[220:221], v[88:89]
	v_pk_fma_f32 v[222:223], v[70:71], v[222:223], v[90:91]
	v_pk_fma_f32 v[224:225], v[72:73], v[224:225], v[92:93]
	v_pk_fma_f32 v[226:227], v[74:75], v[226:227], v[94:95]
	v_cvt_pk_bf16_f32 v212, v212, v213
	v_cvt_pk_bf16_f32 v213, v214, v215
	v_cvt_pk_bf16_f32 v214, v216, v217
	v_cvt_pk_bf16_f32 v215, v218, v219
	v_cvt_pk_bf16_f32 v220, v220, v221
	v_cvt_pk_bf16_f32 v221, v222, v223
	v_cvt_pk_bf16_f32 v222, v224, v225
	v_cvt_pk_bf16_f32 v223, v226, v227
	global_store_dwordx4 v2, v[212:215], s[10:11] sc1
	global_store_dwordx4 v2, v[220:223], s[10:11] offset:1024 sc1
	s_add_u32 s10, s10, 0x800
	s_addc_u32 s11, s11, 0
	global_load_dwordx4 v[164:167], v1, s[8:9]
	global_load_dwordx4 v[168:171], v1, s[8:9] offset:16
	global_load_dwordx4 v[172:175], v1, s[8:9] offset:2048
	global_load_dwordx4 v[176:179], v1, s[8:9] offset:2064
	s_add_u32 s8, s8, 0x1000
	s_addc_u32 s9, s9, 0
	global_load_dwordx4 v[180:183], v1, s[8:9]
	global_load_dwordx4 v[184:187], v1, s[8:9] offset:16
	global_load_dwordx4 v[188:191], v1, s[8:9] offset:2048
	global_load_dwordx4 v[192:195], v1, s[8:9] offset:2064
	s_add_u32 s8, s8, 0x1000
	s_addc_u32 s9, s9, 0
	global_load_dwordx4 v[196:199], v1, s[8:9]
	global_load_dwordx4 v[200:203], v1, s[8:9] offset:16
	global_load_dwordx4 v[204:207], v1, s[8:9] offset:2048
	global_load_dwordx4 v[208:211], v1, s[8:9] offset:2064
	s_add_u32 s8, s8, 0x1000
	s_addc_u32 s9, s9, 0
	global_load_dwordx4 v[212:215], v1, s[8:9]
	global_load_dwordx4 v[216:219], v1, s[8:9] offset:16
	global_load_dwordx4 v[220:223], v1, s[8:9] offset:2048
	global_load_dwordx4 v[224:227], v1, s[8:9] offset:2064
	s_add_u32 s8, s8, 0x1000
	s_addc_u32 s9, s9, 0
	s_waitcnt vmcnt(24)
; DI unsigned pk2(float lo, float hi) { return f2bf(lo) | (f2bf(hi) << 16); }
; DI void norm_phase(const Args& A, int wave_s, int l, int which, int rows) {
;     ...
;             float ss = 0.f;
; #pragma unroll
;             for (int j = 0; j < 4; ++j) ss += (xv[rr][j].x * xv[rr][j].x + xv[rr][j].y * xv[rr][j].y) + (xv[rr][j].z * xv[rr][j].z + xv[rr][j].w * xv[rr][j].w);
;             ss = wave_sum(C.lane, ss);
;             const float rs = rsqrtf(ss * (1.f / 1024.f) + EPS);
; #pragma unroll
;             for (int j = 0; j < 4; ++j) { const int col = 4 * (C.lane + 64 * j);
;                 const f32x4 y = xv[rr][j] * rs * g[j] * (sc[j] + 1.f) + sh[j];
;                 v2u o; o.x = pk2(y.x, y.y); o.y = pk2(y.z, y.w);
;                 *(v2u*)(C.H + (size_t)m * 1024 + col) = o; }
	v_mul_f32_e32 v10, v96, v96
	v_fmac_f32_e32 v10, v97, v97
	v_fmac_f32_e32 v10, v98, v98
	v_fmac_f32_e32 v10, v99, v99
	v_fmac_f32_e32 v10, v100, v100
	v_fmac_f32_e32 v10, v101, v101
	v_fmac_f32_e32 v10, v102, v102
	v_fmac_f32_e32 v10, v103, v103
	v_fmac_f32_e32 v10, v104, v104
	v_fmac_f32_e32 v10, v105, v105
	v_fmac_f32_e32 v10, v106, v106
	v_fmac_f32_e32 v10, v107, v107
	v_fmac_f32_e32 v10, v108, v108
	v_fmac_f32_e32 v10, v109, v109
	v_fmac_f32_e32 v10, v110, v110
	v_fmac_f32_e32 v10, v111, v111
	v_mul_f32_e32 v11, v112, v112
	v_fmac_f32_e32 v11, v113, v113
	v_fmac_f32_e32 v11, v114, v114
	v_fmac_f32_e32 v11, v115, v115
	v_fmac_f32_e32 v11, v116, v116
	v_fmac_f32_e32 v11, v117, v117
	v_fmac_f32_e32 v11, v118, v118
	v_fmac_f32_e32 v11, v119, v119
	v_fmac_f32_e32 v11, v120, v120
	v_fmac_f32_e32 v11, v121, v121
	v_fmac_f32_e32 v11, v122, v122
	v_fmac_f32_e32 v11, v123, v123
	v_fmac_f32_e32 v11, v124, v124
	v_fmac_f32_e32 v11, v125, v125
	v_fmac_f32_e32 v11, v126, v126
	v_fmac_f32_e32 v11, v127, v127
	v_mul_f32_e32 v12, v128, v128
	v_fmac_f32_e32 v12, v129, v129
	v_fmac_f32_e32 v12, v130, v130
	v_fmac_f32_e32 v12, v131, v131
	v_fmac_f32_e32 v12, v132, v132
	v_fmac_f32_e32 v12, v133, v133
	v_fmac_f32_e32 v12, v134, v134
	v_fmac_f32_e32 v12, v135, v135
	v_fmac_f32_e32 v12, v136, v136
	v_fmac_f32_e32 v12, v137, v137
	v_fmac_f32_e32 v12, v138, v138
	v_fmac_f32_e32 v12, v139, v139
	v_fmac_f32_e32 v12, v140, v140
	v_fmac_f32_e32 v12, v141, v141
	v_fmac_f32_e32 v12, v142, v142
	v_fmac_f32_e32 v12, v143, v143
	v_mul_f32_e32 v13, v144, v144
	v_fmac_f32_e32 v13, v145, v145
	v_fmac_f32_e32 v13, v146, v146
	v_fmac_f32_e32 v13, v147, v147
	v_fmac_f32_e32 v13, v148, v148
	v_fmac_f32_e32 v13, v149, v149
	v_fmac_f32_e32 v13, v150, v150
	v_fmac_f32_e32 v13, v151, v151
	v_fmac_f32_e32 v13, v152, v152
	v_fmac_f32_e32 v13, v153, v153
	v_fmac_f32_e32 v13, v154, v154
	v_fmac_f32_e32 v13, v155, v155
	v_fmac_f32_e32 v13, v156, v156
	v_fmac_f32_e32 v13, v157, v157
	v_fmac_f32_e32 v13, v158, v158
	v_fmac_f32_e32 v13, v159, v159
	ds_bpermute_b32 v14, v4, v10
	ds_bpermute_b32 v15, v4, v11
	ds_bpermute_b32 v16, v4, v12
	ds_bpermute_b32 v17, v4, v13
	s_waitcnt lgkmcnt(0)
	v_add_f32_e32 v10, v10, v14
	v_add_f32_e32 v11, v11, v15
	v_add_f32_e32 v12, v12, v16
	v_add_f32_e32 v13, v13, v17
	ds_bpermute_b32 v14, v5, v10
	ds_bpermute_b32 v15, v5, v11
	ds_bpermute_b32 v16, v5, v12
	ds_bpermute_b32 v17, v5, v13
	s_waitcnt lgkmcnt(0)
	v_add_f32_e32 v10, v10, v14
	v_add_f32_e32 v11, v11, v15
	v_add_f32_e32 v12, v12, v16
	v_add_f32_e32 v13, v13, v17
	ds_bpermute_b32 v14, v6, v10
	ds_bpermute_b32 v15, v6, v11
	ds_bpermute_b32 v16, v6, v12
	ds_bpermute_b32 v17, v6, v13
	s_waitcnt lgkmcnt(0)
	v_add_f32_e32 v10, v10, v14
	v_add_f32_e32 v11, v11, v15
	v_add_f32_e32 v12, v12, v16
	v_add_f32_e32 v13, v13, v17
	ds_bpermute_b32 v14, v7, v10
	ds_bpermute_b32 v15, v7, v11
	ds_bpermute_b32 v16, v7, v12
	ds_bpermute_b32 v17, v7, v13
	s_waitcnt lgkmcnt(0)
	v_add_f32_e32 v10, v10, v14
	v_add_f32_e32 v11, v11, v15
	v_add_f32_e32 v12, v12, v16
	v_add_f32_e32 v13, v13, v17
	ds_bpermute_b32 v14, v8, v10
	ds_bpermute_b32 v15, v8, v11
	ds_bpermute_b32 v16, v8, v12
	ds_bpermute_b32 v17, v8, v13
	s_waitcnt lgkmcnt(0)
	v_add_f32_e32 v10, v10, v14
	v_add_f32_e32 v11, v11, v15
	v_add_f32_e32 v12, v12, v16
	v_add_f32_e32 v13, v13, v17
	ds_bpermute_b32 v14, v9, v10
	ds_bpermute_b32 v15, v9, v11
	ds_bpermute_b32 v16, v9, v12
	ds_bpermute_b32 v17, v9, v13
	s_waitcnt lgkmcnt(0)
	v_add_f32_e32 v10, v10, v14
	v_add_f32_e32 v11, v11, v15
	v_add_f32_e32 v12, v12, v16
	v_add_f32_e32 v13, v13, v17
	v_fma_f32 v10, v10, s32, v60
	v_fma_f32 v11, v11, s32, v60
	v_fma_f32 v12, v12, s32, v60
	v_fma_f32 v13, v13, s32, v60
	v_rsq_f32_e32 v18, v10
	v_rsq_f32_e32 v20, v11
	v_rsq_f32_e32 v22, v12
	v_rsq_f32_e32 v62, v13
	s_nop 0
	v_pk_mul_f32 v[96:97], v[96:97], v[18:19] op_sel_hi:[1,0]
	v_pk_mul_f32 v[98:99], v[98:99], v[18:19] op_sel_hi:[1,0]
	v_pk_mul_f32 v[100:101], v[100:101], v[18:19] op_sel_hi:[1,0]
	v_pk_mul_f32 v[102:103], v[102:103], v[18:19] op_sel_hi:[1,0]
	v_pk_mul_f32 v[104:105], v[104:105], v[18:19] op_sel_hi:[1,0]
	v_pk_mul_f32 v[106:107], v[106:107], v[18:19] op_sel_hi:[1,0]
	v_pk_mul_f32 v[108:109], v[108:109], v[18:19] op_sel_hi:[1,0]
	v_pk_mul_f32 v[110:111], v[110:111], v[18:19] op_sel_hi:[1,0]
	v_pk_mul_f32 v[96:97], v[24:25], v[96:97]
	v_pk_mul_f32 v[98:99], v[26:27], v[98:99]
	v_pk_mul_f32 v[100:101], v[28:29], v[100:101]
	v_pk_mul_f32 v[102:103], v[30:31], v[102:103]
	v_pk_mul_f32 v[104:105], v[32:33], v[104:105]
	v_pk_mul_f32 v[106:107], v[34:35], v[106:107]
	v_pk_mul_f32 v[108:109], v[36:37], v[108:109]
	v_pk_mul_f32 v[110:111], v[38:39], v[110:111]
	v_pk_fma_f32 v[96:97], v[40:41], v[96:97], v[80:81]
	v_pk_fma_f32 v[98:99], v[42:43], v[98:99], v[82:83]
	v_pk_fma_f32 v[100:101], v[64:65], v[100:101], v[84:85]
	v_pk_fma_f32 v[102:103], v[66:67], v[102:103], v[86:87]
	v_pk_fma_f32 v[104:105], v[68:69], v[104:105], v[88:89]
	v_pk_fma_f32 v[106:107], v[70:71], v[106:107], v[90:91]
	v_pk_fma_f32 v[108:109], v[72:73], v[108:109], v[92:93]
	v_pk_fma_f32 v[110:111], v[74:75], v[110:111], v[94:95]
	v_cvt_pk_bf16_f32 v96, v96, v97
	v_cvt_pk_bf16_f32 v97, v98, v99
	v_cvt_pk_bf16_f32 v98, v100, v101
	v_cvt_pk_bf16_f32 v99, v102, v103
	v_cvt_pk_bf16_f32 v104, v104, v105
	v_cvt_pk_bf16_f32 v105, v106, v107
	v_cvt_pk_bf16_f32 v106, v108, v109
	v_cvt_pk_bf16_f32 v107, v110, v111
	global_store_dwordx4 v2, v[96:99], s[10:11] sc1
	global_store_dwordx4 v2, v[104:107], s[10:11] offset:1024 sc1
	s_add_u32 s10, s10, 0x800
	s_addc_u32 s11, s11, 0
	v_pk_mul_f32 v[112:113], v[112:113], v[20:21] op_sel_hi:[1,0]
; DI unsigned pk2(float lo, float hi) { return f2bf(lo) | (f2bf(hi) << 16); }
; DI void norm_phase(const Args& A, int wave_s, int l, int which, int rows) {
;     ...
;             if (m < NLAT) { xr = (from_in ? C.x : C.out) + (size_t)m * 1024; v = m >> 13; }
;             else { xr = (from_in ? C.ctx : C.XC) + (size_t)(m - NLAT) * 1024; v = 4; }
;             modp[rr] = C.SM + SM_MOD + (l * 5 + v) * 6144 + (which == 1 ? 0 : 3072);
; #pragma unroll
;             for (int j = 0; j < 4; ++j) xv[rr][j] = ((const f32x4*)xr)[C.lane + 64 * j];
;     ...
;             for (int j = 0; j < 4; ++j) { const int col = 4 * (C.lane + 64 * j);
;                 const f32x4 y = xv[rr][j] * rs * g[j] * (sc[j] + 1.f) + sh[j];
;                 v2u o; o.x = pk2(y.x, y.y); o.y = pk2(y.z, y.w);
;                 *(v2u*)(C.H + (size_t)m * 1024 + col) = o; }
	v_pk_mul_f32 v[114:115], v[114:115], v[20:21] op_sel_hi:[1,0]
	v_pk_mul_f32 v[116:117], v[116:117], v[20:21] op_sel_hi:[1,0]
	v_pk_mul_f32 v[118:119], v[118:119], v[20:21] op_sel_hi:[1,0]
	v_pk_mul_f32 v[120:121], v[120:121], v[20:21] op_sel_hi:[1,0]
	v_pk_mul_f32 v[122:123], v[122:123], v[20:21] op_sel_hi:[1,0]
	v_pk_mul_f32 v[124:125], v[124:125], v[20:21] op_sel_hi:[1,0]
	v_pk_mul_f32 v[126:127], v[126:127], v[20:21] op_sel_hi:[1,0]
	v_pk_mul_f32 v[112:113], v[24:25], v[112:113]
	v_pk_mul_f32 v[114:115], v[26:27], v[114:115]
	v_pk_mul_f32 v[116:117], v[28:29], v[116:117]
	v_pk_mul_f32 v[118:119], v[30:31], v[118:119]
	v_pk_mul_f32 v[120:121], v[32:33], v[120:121]
	v_pk_mul_f32 v[122:123], v[34:35], v[122:123]
	v_pk_mul_f32 v[124:125], v[36:37], v[124:125]
	v_pk_mul_f32 v[126:127], v[38:39], v[126:127]
	v_pk_fma_f32 v[112:113], v[40:41], v[112:113], v[80:81]
	v_pk_fma_f32 v[114:115], v[42:43], v[114:115], v[82:83]
	v_pk_fma_f32 v[116:117], v[64:65], v[116:117], v[84:85]
	v_pk_fma_f32 v[118:119], v[66:67], v[118:119], v[86:87]
	v_pk_fma_f32 v[120:121], v[68:69], v[120:121], v[88:89]
	v_pk_fma_f32 v[122:123], v[70:71], v[122:123], v[90:91]
	v_pk_fma_f32 v[124:125], v[72:73], v[124:125], v[92:93]
	v_pk_fma_f32 v[126:127], v[74:75], v[126:127], v[94:95]
	v_cvt_pk_bf16_f32 v112, v112, v113
	v_cvt_pk_bf16_f32 v113, v114, v115
	v_cvt_pk_bf16_f32 v114, v116, v117
	v_cvt_pk_bf16_f32 v115, v118, v119
	v_cvt_pk_bf16_f32 v120, v120, v121
	v_cvt_pk_bf16_f32 v121, v122, v123
	v_cvt_pk_bf16_f32 v122, v124, v125
	v_cvt_pk_bf16_f32 v123, v126, v127
	global_store_dwordx4 v2, v[112:115], s[10:11] sc1
	global_store_dwordx4 v2, v[120:123], s[10:11] offset:1024 sc1
	s_add_u32 s10, s10, 0x800
	s_addc_u32 s11, s11, 0
	v_pk_mul_f32 v[128:129], v[128:129], v[22:23] op_sel_hi:[1,0]
	v_pk_mul_f32 v[130:131], v[130:131], v[22:23] op_sel_hi:[1,0]
	v_pk_mul_f32 v[132:133], v[132:133], v[22:23] op_sel_hi:[1,0]
	v_pk_mul_f32 v[134:135], v[134:135], v[22:23] op_sel_hi:[1,0]
	v_pk_mul_f32 v[136:137], v[136:137], v[22:23] op_sel_hi:[1,0]
	v_pk_mul_f32 v[138:139], v[138:139], v[22:23] op_sel_hi:[1,0]
	v_pk_mul_f32 v[140:141], v[140:141], v[22:23] op_sel_hi:[1,0]
	v_pk_mul_f32 v[142:143], v[142:143], v[22:23] op_sel_hi:[1,0]
	v_pk_mul_f32 v[128:129], v[24:25], v[128:129]
	v_pk_mul_f32 v[130:131], v[26:27], v[130:131]
	v_pk_mul_f32 v[132:133], v[28:29], v[132:133]
	v_pk_mul_f32 v[134:135], v[30:31], v[134:135]
	v_pk_mul_f32 v[136:137], v[32:33], v[136:137]
	v_pk_mul_f32 v[138:139], v[34:35], v[138:139]
	v_pk_mul_f32 v[140:141], v[36:37], v[140:141]
	v_pk_mul_f32 v[142:143], v[38:39], v[142:143]
	v_pk_fma_f32 v[128:129], v[40:41], v[128:129], v[80:81]
	v_pk_fma_f32 v[130:131], v[42:43], v[130:131], v[82:83]
	v_pk_fma_f32 v[132:133], v[64:65], v[132:133], v[84:85]
	v_pk_fma_f32 v[134:135], v[66:67], v[134:135], v[86:87]
	v_pk_fma_f32 v[136:137], v[68:69], v[136:137], v[88:89]
	v_pk_fma_f32 v[138:139], v[70:71], v[138:139], v[90:91]
	v_pk_fma_f32 v[140:141], v[72:73], v[140:141], v[92:93]
	v_pk_fma_f32 v[142:143], v[74:75], v[142:143], v[94:95]
	v_cvt_pk_bf16_f32 v128, v128, v129
	v_cvt_pk_bf16_f32 v129, v130, v131
	v_cvt_pk_bf16_f32 v130, v132, v133
	v_cvt_pk_bf16_f32 v131, v134, v135
	v_cvt_pk_bf16_f32 v136, v136, v137
	v_cvt_pk_bf16_f32 v137, v138, v139
	v_cvt_pk_bf16_f32 v138, v140, v141
	v_cvt_pk_bf16_f32 v139, v142, v143
	global_store_dwordx4 v2, v[128:131], s[10:11] sc1
	global_store_dwordx4 v2, v[136:139], s[10:11] offset:1024 sc1
	s_add_u32 s10, s10, 0x800
	s_addc_u32 s11, s11, 0
	v_pk_mul_f32 v[144:145], v[144:145], v[62:63] op_sel_hi:[1,0]
	v_pk_mul_f32 v[146:147], v[146:147], v[62:63] op_sel_hi:[1,0]
	v_pk_mul_f32 v[148:149], v[148:149], v[62:63] op_sel_hi:[1,0]
	v_pk_mul_f32 v[150:151], v[150:151], v[62:63] op_sel_hi:[1,0]
	v_pk_mul_f32 v[152:153], v[152:153], v[62:63] op_sel_hi:[1,0]
	v_pk_mul_f32 v[154:155], v[154:155], v[62:63] op_sel_hi:[1,0]
	v_pk_mul_f32 v[156:157], v[156:157], v[62:63] op_sel_hi:[1,0]
	v_pk_mul_f32 v[158:159], v[158:159], v[62:63] op_sel_hi:[1,0]
	v_pk_mul_f32 v[144:145], v[24:25], v[144:145]
	v_pk_mul_f32 v[146:147], v[26:27], v[146:147]
	v_pk_mul_f32 v[148:149], v[28:29], v[148:149]
	v_pk_mul_f32 v[150:151], v[30:31], v[150:151]
	v_pk_mul_f32 v[152:153], v[32:33], v[152:153]
	v_pk_mul_f32 v[154:155], v[34:35], v[154:155]
	v_pk_mul_f32 v[156:157], v[36:37], v[156:157]
	v_pk_mul_f32 v[158:159], v[38:39], v[158:159]
	v_pk_fma_f32 v[144:145], v[40:41], v[144:145], v[80:81]
	v_pk_fma_f32 v[146:147], v[42:43], v[146:147], v[82:83]
	v_pk_fma_f32 v[148:149], v[64:65], v[148:149], v[84:85]
	v_pk_fma_f32 v[150:151], v[66:67], v[150:151], v[86:87]
	v_pk_fma_f32 v[152:153], v[68:69], v[152:153], v[88:89]
	v_pk_fma_f32 v[154:155], v[70:71], v[154:155], v[90:91]
	v_pk_fma_f32 v[156:157], v[72:73], v[156:157], v[92:93]
	v_pk_fma_f32 v[158:159], v[74:75], v[158:159], v[94:95]
	v_cvt_pk_bf16_f32 v144, v144, v145
	v_cvt_pk_bf16_f32 v145, v146, v147
	v_cvt_pk_bf16_f32 v146, v148, v149
	v_cvt_pk_bf16_f32 v147, v150, v151
	v_cvt_pk_bf16_f32 v152, v152, v153
	v_cvt_pk_bf16_f32 v153, v154, v155
	v_cvt_pk_bf16_f32 v154, v156, v157
	v_cvt_pk_bf16_f32 v155, v158, v159
	global_store_dwordx4 v2, v[144:147], s[10:11] sc1
	global_store_dwordx4 v2, v[152:155], s[10:11] offset:1024 sc1
	s_add_u32 s10, s10, 0x800
	s_addc_u32 s11, s11, 0
	s_mul_i32 s5, s6, 5
	s_add_u32 s5, s5, 4
	s_mul_i32 s5, s5, 0x6000
	s_add_u32 s24, s88, 0x103000
	s_addc_u32 s25, s89, 0
	s_add_u32 s24, s24, s5
	s_addc_u32 s25, s25, 0
	s_add_u32 s26, s24, 0x1000
	s_addc_u32 s27, s25, 0
	global_load_dwordx4 v[96:99], v1, s[30:31]
	global_load_dwordx4 v[100:103], v1, s[30:31] offset:16
	global_load_dwordx4 v[104:107], v1, s[30:31] offset:2048
	global_load_dwordx4 v[108:111], v1, s[30:31] offset:2064
	global_load_dwordx4 v[112:115], v1, s[26:27]
	global_load_dwordx4 v[116:119], v1, s[26:27] offset:16
	global_load_dwordx4 v[120:123], v1, s[26:27] offset:2048
	global_load_dwordx4 v[124:127], v1, s[26:27] offset:2064
	global_load_dwordx4 v[128:131], v1, s[24:25]
	global_load_dwordx4 v[132:135], v1, s[24:25] offset:16
	global_load_dwordx4 v[136:139], v1, s[24:25] offset:2048
	global_load_dwordx4 v[140:143], v1, s[24:25] offset:2064
	s_waitcnt vmcnt(20)
; DI unsigned pk2(float lo, float hi) { return f2bf(lo) | (f2bf(hi) << 16); }
; DI void norm_phase(const Args& A, int wave_s, int l, int which, int rows) {
;     ...
;             float ss = 0.f;
; #pragma unroll
;             for (int j = 0; j < 4; ++j) ss += (xv[rr][j].x * xv[rr][j].x + xv[rr][j].y * xv[rr][j].y) + (xv[rr][j].z * xv[rr][j].z + xv[rr][j].w * xv[rr][j].w);
;             ss = wave_sum(C.lane, ss);
;             const float rs = rsqrtf(ss * (1.f / 1024.f) + EPS);
; #pragma unroll
;             for (int j = 0; j < 4; ++j) { const int col = 4 * (C.lane + 64 * j);
;                 const f32x4 y = xv[rr][j] * rs * g[j] * (sc[j] + 1.f) + sh[j];
;                 v2u o; o.x = pk2(y.x, y.y); o.y = pk2(y.z, y.w);
;                 *(v2u*)(C.H + (size_t)m * 1024 + col) = o; }
	v_mul_f32_e32 v10, v164, v164
	v_fmac_f32_e32 v10, v165, v165
	v_fmac_f32_e32 v10, v166, v166
	v_fmac_f32_e32 v10, v167, v167
	v_fmac_f32_e32 v10, v168, v168
	v_fmac_f32_e32 v10, v169, v169
	v_fmac_f32_e32 v10, v170, v170
	v_fmac_f32_e32 v10, v171, v171
	v_fmac_f32_e32 v10, v172, v172
	v_fmac_f32_e32 v10, v173, v173
	v_fmac_f32_e32 v10, v174, v174
	v_fmac_f32_e32 v10, v175, v175
	v_fmac_f32_e32 v10, v176, v176
	v_fmac_f32_e32 v10, v177, v177
	v_fmac_f32_e32 v10, v178, v178
	v_fmac_f32_e32 v10, v179, v179
	v_mul_f32_e32 v11, v180, v180
	v_fmac_f32_e32 v11, v181, v181
	v_fmac_f32_e32 v11, v182, v182
	v_fmac_f32_e32 v11, v183, v183
	v_fmac_f32_e32 v11, v184, v184
	v_fmac_f32_e32 v11, v185, v185
	v_fmac_f32_e32 v11, v186, v186
	v_fmac_f32_e32 v11, v187, v187
	v_fmac_f32_e32 v11, v188, v188
	v_fmac_f32_e32 v11, v189, v189
	v_fmac_f32_e32 v11, v190, v190
	v_fmac_f32_e32 v11, v191, v191
	v_fmac_f32_e32 v11, v192, v192
	v_fmac_f32_e32 v11, v193, v193
	v_fmac_f32_e32 v11, v194, v194
	v_fmac_f32_e32 v11, v195, v195
	v_mul_f32_e32 v12, v196, v196
	v_fmac_f32_e32 v12, v197, v197
	v_fmac_f32_e32 v12, v198, v198
	v_fmac_f32_e32 v12, v199, v199
	v_fmac_f32_e32 v12, v200, v200
	v_fmac_f32_e32 v12, v201, v201
	v_fmac_f32_e32 v12, v202, v202
	v_fmac_f32_e32 v12, v203, v203
	v_fmac_f32_e32 v12, v204, v204
	v_fmac_f32_e32 v12, v205, v205
	v_fmac_f32_e32 v12, v206, v206
	v_fmac_f32_e32 v12, v207, v207
	v_fmac_f32_e32 v12, v208, v208
	v_fmac_f32_e32 v12, v209, v209
	v_fmac_f32_e32 v12, v210, v210
	v_fmac_f32_e32 v12, v211, v211
	v_mul_f32_e32 v13, v212, v212
	v_fmac_f32_e32 v13, v213, v213
	v_fmac_f32_e32 v13, v214, v214
	v_fmac_f32_e32 v13, v215, v215
	v_fmac_f32_e32 v13, v216, v216
	v_fmac_f32_e32 v13, v217, v217
	v_fmac_f32_e32 v13, v218, v218
	v_fmac_f32_e32 v13, v219, v219
	v_fmac_f32_e32 v13, v220, v220
	v_fmac_f32_e32 v13, v221, v221
	v_fmac_f32_e32 v13, v222, v222
	v_fmac_f32_e32 v13, v223, v223
	v_fmac_f32_e32 v13, v224, v224
	v_fmac_f32_e32 v13, v225, v225
	v_fmac_f32_e32 v13, v226, v226
	v_fmac_f32_e32 v13, v227, v227
	ds_bpermute_b32 v14, v4, v10
	ds_bpermute_b32 v15, v4, v11
	ds_bpermute_b32 v16, v4, v12
	ds_bpermute_b32 v17, v4, v13
	s_waitcnt lgkmcnt(0)
	v_add_f32_e32 v10, v10, v14
	v_add_f32_e32 v11, v11, v15
	v_add_f32_e32 v12, v12, v16
	v_add_f32_e32 v13, v13, v17
	ds_bpermute_b32 v14, v5, v10
	ds_bpermute_b32 v15, v5, v11
	ds_bpermute_b32 v16, v5, v12
	ds_bpermute_b32 v17, v5, v13
	s_waitcnt lgkmcnt(0)
	v_add_f32_e32 v10, v10, v14
	v_add_f32_e32 v11, v11, v15
	v_add_f32_e32 v12, v12, v16
	v_add_f32_e32 v13, v13, v17
	ds_bpermute_b32 v14, v6, v10
	ds_bpermute_b32 v15, v6, v11
	ds_bpermute_b32 v16, v6, v12
	ds_bpermute_b32 v17, v6, v13
	s_waitcnt lgkmcnt(0)
	v_add_f32_e32 v10, v10, v14
	v_add_f32_e32 v11, v11, v15
	v_add_f32_e32 v12, v12, v16
	v_add_f32_e32 v13, v13, v17
	ds_bpermute_b32 v14, v7, v10
	ds_bpermute_b32 v15, v7, v11
	ds_bpermute_b32 v16, v7, v12
	ds_bpermute_b32 v17, v7, v13
	s_waitcnt lgkmcnt(0)
	v_add_f32_e32 v10, v10, v14
	v_add_f32_e32 v11, v11, v15
	v_add_f32_e32 v12, v12, v16
	v_add_f32_e32 v13, v13, v17
	ds_bpermute_b32 v14, v8, v10
	ds_bpermute_b32 v15, v8, v11
	ds_bpermute_b32 v16, v8, v12
	ds_bpermute_b32 v17, v8, v13
	s_waitcnt lgkmcnt(0)
	v_add_f32_e32 v10, v10, v14
	v_add_f32_e32 v11, v11, v15
	v_add_f32_e32 v12, v12, v16
	v_add_f32_e32 v13, v13, v17
	ds_bpermute_b32 v14, v9, v10
	ds_bpermute_b32 v15, v9, v11
	ds_bpermute_b32 v16, v9, v12
	ds_bpermute_b32 v17, v9, v13
	s_waitcnt lgkmcnt(0)
	v_add_f32_e32 v10, v10, v14
	v_add_f32_e32 v11, v11, v15
	v_add_f32_e32 v12, v12, v16
	v_add_f32_e32 v13, v13, v17
	v_fma_f32 v10, v10, s32, v60
	v_fma_f32 v11, v11, s32, v60
	v_fma_f32 v12, v12, s32, v60
	v_fma_f32 v13, v13, s32, v60
	v_rsq_f32_e32 v18, v10
	v_rsq_f32_e32 v20, v11
	v_rsq_f32_e32 v22, v12
	v_rsq_f32_e32 v62, v13
	s_nop 0
	v_pk_mul_f32 v[164:165], v[164:165], v[18:19] op_sel_hi:[1,0]
	v_pk_mul_f32 v[166:167], v[166:167], v[18:19] op_sel_hi:[1,0]
	v_pk_mul_f32 v[168:169], v[168:169], v[18:19] op_sel_hi:[1,0]
	v_pk_mul_f32 v[170:171], v[170:171], v[18:19] op_sel_hi:[1,0]
	v_pk_mul_f32 v[172:173], v[172:173], v[18:19] op_sel_hi:[1,0]
	v_pk_mul_f32 v[174:175], v[174:175], v[18:19] op_sel_hi:[1,0]
	v_pk_mul_f32 v[176:177], v[176:177], v[18:19] op_sel_hi:[1,0]
	v_pk_mul_f32 v[178:179], v[178:179], v[18:19] op_sel_hi:[1,0]
	v_pk_mul_f32 v[164:165], v[24:25], v[164:165]
	v_pk_mul_f32 v[166:167], v[26:27], v[166:167]
	v_pk_mul_f32 v[168:169], v[28:29], v[168:169]
	v_pk_mul_f32 v[170:171], v[30:31], v[170:171]
	v_pk_mul_f32 v[172:173], v[32:33], v[172:173]
	v_pk_mul_f32 v[174:175], v[34:35], v[174:175]
	v_pk_mul_f32 v[176:177], v[36:37], v[176:177]
	v_pk_mul_f32 v[178:179], v[38:39], v[178:179]
	v_pk_fma_f32 v[164:165], v[40:41], v[164:165], v[80:81]
	v_pk_fma_f32 v[166:167], v[42:43], v[166:167], v[82:83]
	v_pk_fma_f32 v[168:169], v[64:65], v[168:169], v[84:85]
	v_pk_fma_f32 v[170:171], v[66:67], v[170:171], v[86:87]
	v_pk_fma_f32 v[172:173], v[68:69], v[172:173], v[88:89]
	v_pk_fma_f32 v[174:175], v[70:71], v[174:175], v[90:91]
	v_pk_fma_f32 v[176:177], v[72:73], v[176:177], v[92:93]
	v_pk_fma_f32 v[178:179], v[74:75], v[178:179], v[94:95]
	v_cvt_pk_bf16_f32 v164, v164, v165
	v_cvt_pk_bf16_f32 v165, v166, v167
	v_cvt_pk_bf16_f32 v166, v168, v169
	v_cvt_pk_bf16_f32 v167, v170, v171
	v_cvt_pk_bf16_f32 v172, v172, v173
	v_cvt_pk_bf16_f32 v173, v174, v175
	v_cvt_pk_bf16_f32 v174, v176, v177
	v_cvt_pk_bf16_f32 v175, v178, v179
	global_store_dwordx4 v2, v[164:167], s[10:11] sc1
	global_store_dwordx4 v2, v[172:175], s[10:11] offset:1024 sc1
	s_add_u32 s10, s10, 0x800
	s_addc_u32 s11, s11, 0
	v_pk_mul_f32 v[180:181], v[180:181], v[20:21] op_sel_hi:[1,0]
; DI unsigned pk2(float lo, float hi) { return f2bf(lo) | (f2bf(hi) << 16); }
; DI void norm_phase(const Args& A, int wave_s, int l, int which, int rows) {
;     ...
;             if (m < NLAT) { xr = (from_in ? C.x : C.out) + (size_t)m * 1024; v = m >> 13; }
;             else { xr = (from_in ? C.ctx : C.XC) + (size_t)(m - NLAT) * 1024; v = 4; }
;             modp[rr] = C.SM + SM_MOD + (l * 5 + v) * 6144 + (which == 1 ? 0 : 3072);
;     ...
;             for (int j = 0; j < 4; ++j) { const int col = 4 * (C.lane + 64 * j);
;                 const f32x4 y = xv[rr][j] * rs * g[j] * (sc[j] + 1.f) + sh[j];
;                 v2u o; o.x = pk2(y.x, y.y); o.y = pk2(y.z, y.w);
;                 *(v2u*)(C.H + (size_t)m * 1024 + col) = o; }
	v_pk_mul_f32 v[182:183], v[182:183], v[20:21] op_sel_hi:[1,0]
	v_pk_mul_f32 v[184:185], v[184:185], v[20:21] op_sel_hi:[1,0]
	v_pk_mul_f32 v[186:187], v[186:187], v[20:21] op_sel_hi:[1,0]
	v_pk_mul_f32 v[188:189], v[188:189], v[20:21] op_sel_hi:[1,0]
	v_pk_mul_f32 v[190:191], v[190:191], v[20:21] op_sel_hi:[1,0]
	v_pk_mul_f32 v[192:193], v[192:193], v[20:21] op_sel_hi:[1,0]
	v_pk_mul_f32 v[194:195], v[194:195], v[20:21] op_sel_hi:[1,0]
	v_pk_mul_f32 v[180:181], v[24:25], v[180:181]
	v_pk_mul_f32 v[182:183], v[26:27], v[182:183]
	v_pk_mul_f32 v[184:185], v[28:29], v[184:185]
	v_pk_mul_f32 v[186:187], v[30:31], v[186:187]
	v_pk_mul_f32 v[188:189], v[32:33], v[188:189]
	v_pk_mul_f32 v[190:191], v[34:35], v[190:191]
	v_pk_mul_f32 v[192:193], v[36:37], v[192:193]
	v_pk_mul_f32 v[194:195], v[38:39], v[194:195]
	v_pk_fma_f32 v[180:181], v[40:41], v[180:181], v[80:81]
	v_pk_fma_f32 v[182:183], v[42:43], v[182:183], v[82:83]
	v_pk_fma_f32 v[184:185], v[64:65], v[184:185], v[84:85]
	v_pk_fma_f32 v[186:187], v[66:67], v[186:187], v[86:87]
	v_pk_fma_f32 v[188:189], v[68:69], v[188:189], v[88:89]
	v_pk_fma_f32 v[190:191], v[70:71], v[190:191], v[90:91]
	v_pk_fma_f32 v[192:193], v[72:73], v[192:193], v[92:93]
	v_pk_fma_f32 v[194:195], v[74:75], v[194:195], v[94:95]
	v_cvt_pk_bf16_f32 v180, v180, v181
	v_cvt_pk_bf16_f32 v181, v182, v183
	v_cvt_pk_bf16_f32 v182, v184, v185
	v_cvt_pk_bf16_f32 v183, v186, v187
	v_cvt_pk_bf16_f32 v188, v188, v189
	v_cvt_pk_bf16_f32 v189, v190, v191
	v_cvt_pk_bf16_f32 v190, v192, v193
	v_cvt_pk_bf16_f32 v191, v194, v195
	global_store_dwordx4 v2, v[180:183], s[10:11] sc1
	global_store_dwordx4 v2, v[188:191], s[10:11] offset:1024 sc1
	s_add_u32 s10, s10, 0x800
	s_addc_u32 s11, s11, 0
	v_pk_mul_f32 v[196:197], v[196:197], v[22:23] op_sel_hi:[1,0]
	v_pk_mul_f32 v[198:199], v[198:199], v[22:23] op_sel_hi:[1,0]
	v_pk_mul_f32 v[200:201], v[200:201], v[22:23] op_sel_hi:[1,0]
	v_pk_mul_f32 v[202:203], v[202:203], v[22:23] op_sel_hi:[1,0]
	v_pk_mul_f32 v[204:205], v[204:205], v[22:23] op_sel_hi:[1,0]
	v_pk_mul_f32 v[206:207], v[206:207], v[22:23] op_sel_hi:[1,0]
	v_pk_mul_f32 v[208:209], v[208:209], v[22:23] op_sel_hi:[1,0]
	v_pk_mul_f32 v[210:211], v[210:211], v[22:23] op_sel_hi:[1,0]
	v_pk_mul_f32 v[196:197], v[24:25], v[196:197]
	v_pk_mul_f32 v[198:199], v[26:27], v[198:199]
	v_pk_mul_f32 v[200:201], v[28:29], v[200:201]
	v_pk_mul_f32 v[202:203], v[30:31], v[202:203]
	v_pk_mul_f32 v[204:205], v[32:33], v[204:205]
	v_pk_mul_f32 v[206:207], v[34:35], v[206:207]
	v_pk_mul_f32 v[208:209], v[36:37], v[208:209]
	v_pk_mul_f32 v[210:211], v[38:39], v[210:211]
	v_pk_fma_f32 v[196:197], v[40:41], v[196:197], v[80:81]
	v_pk_fma_f32 v[198:199], v[42:43], v[198:199], v[82:83]
	v_pk_fma_f32 v[200:201], v[64:65], v[200:201], v[84:85]
	v_pk_fma_f32 v[202:203], v[66:67], v[202:203], v[86:87]
	v_pk_fma_f32 v[204:205], v[68:69], v[204:205], v[88:89]
	v_pk_fma_f32 v[206:207], v[70:71], v[206:207], v[90:91]
	v_pk_fma_f32 v[208:209], v[72:73], v[208:209], v[92:93]
	v_pk_fma_f32 v[210:211], v[74:75], v[210:211], v[94:95]
	v_cvt_pk_bf16_f32 v196, v196, v197
	v_cvt_pk_bf16_f32 v197, v198, v199
	v_cvt_pk_bf16_f32 v198, v200, v201
	v_cvt_pk_bf16_f32 v199, v202, v203
	v_cvt_pk_bf16_f32 v204, v204, v205
	v_cvt_pk_bf16_f32 v205, v206, v207
	v_cvt_pk_bf16_f32 v206, v208, v209
	v_cvt_pk_bf16_f32 v207, v210, v211
	global_store_dwordx4 v2, v[196:199], s[10:11] sc1
	global_store_dwordx4 v2, v[204:207], s[10:11] offset:1024 sc1
	s_add_u32 s10, s10, 0x800
	s_addc_u32 s11, s11, 0
	v_pk_mul_f32 v[212:213], v[212:213], v[62:63] op_sel_hi:[1,0]
	v_pk_mul_f32 v[214:215], v[214:215], v[62:63] op_sel_hi:[1,0]
	v_pk_mul_f32 v[216:217], v[216:217], v[62:63] op_sel_hi:[1,0]
	v_pk_mul_f32 v[218:219], v[218:219], v[62:63] op_sel_hi:[1,0]
	v_pk_mul_f32 v[220:221], v[220:221], v[62:63] op_sel_hi:[1,0]
	v_pk_mul_f32 v[222:223], v[222:223], v[62:63] op_sel_hi:[1,0]
	v_pk_mul_f32 v[224:225], v[224:225], v[62:63] op_sel_hi:[1,0]
	v_pk_mul_f32 v[226:227], v[226:227], v[62:63] op_sel_hi:[1,0]
	v_pk_mul_f32 v[212:213], v[24:25], v[212:213]
	v_pk_mul_f32 v[214:215], v[26:27], v[214:215]
	v_pk_mul_f32 v[216:217], v[28:29], v[216:217]
	v_pk_mul_f32 v[218:219], v[30:31], v[218:219]
	v_pk_mul_f32 v[220:221], v[32:33], v[220:221]
	v_pk_mul_f32 v[222:223], v[34:35], v[222:223]
	v_pk_mul_f32 v[224:225], v[36:37], v[224:225]
	v_pk_mul_f32 v[226:227], v[38:39], v[226:227]
	v_pk_fma_f32 v[212:213], v[40:41], v[212:213], v[80:81]
	v_pk_fma_f32 v[214:215], v[42:43], v[214:215], v[82:83]
	v_pk_fma_f32 v[216:217], v[64:65], v[216:217], v[84:85]
	v_pk_fma_f32 v[218:219], v[66:67], v[218:219], v[86:87]
	v_pk_fma_f32 v[220:221], v[68:69], v[220:221], v[88:89]
	v_pk_fma_f32 v[222:223], v[70:71], v[222:223], v[90:91]
	v_pk_fma_f32 v[224:225], v[72:73], v[224:225], v[92:93]
	v_pk_fma_f32 v[226:227], v[74:75], v[226:227], v[94:95]
	v_cvt_pk_bf16_f32 v212, v212, v213
	v_cvt_pk_bf16_f32 v213, v214, v215
	v_cvt_pk_bf16_f32 v214, v216, v217
	v_cvt_pk_bf16_f32 v215, v218, v219
	v_cvt_pk_bf16_f32 v220, v220, v221
	v_cvt_pk_bf16_f32 v221, v222, v223
	v_cvt_pk_bf16_f32 v222, v224, v225
	v_cvt_pk_bf16_f32 v223, v226, v227
	global_store_dwordx4 v2, v[212:215], s[10:11] sc1
	global_store_dwordx4 v2, v[220:223], s[10:11] offset:1024 sc1
	s_add_u32 s10, s10, 0x800
	s_addc_u32 s11, s11, 0
	s_add_u32 s10, s88, 0x3800000
	s_addc_u32 s11, s89, 0
	s_add_u32 s10, s10, 0x4000000
	s_addc_u32 s11, s11, 0
	s_lshl_b32 s5, s7, 11
	s_add_u32 s10, s10, s5
	s_addc_u32 s11, s11, 0
	s_waitcnt vmcnt(8)
	v_pk_add_f32 v[112:113], v[112:113], 1.0 op_sel_hi:[1,0]
	v_pk_add_f32 v[114:115], v[114:115], 1.0 op_sel_hi:[1,0]
	v_pk_add_f32 v[116:117], v[116:117], 1.0 op_sel_hi:[1,0]
	v_pk_add_f32 v[118:119], v[118:119], 1.0 op_sel_hi:[1,0]
	v_pk_add_f32 v[120:121], v[120:121], 1.0 op_sel_hi:[1,0]
	v_pk_add_f32 v[122:123], v[122:123], 1.0 op_sel_hi:[1,0]
	v_pk_add_f32 v[124:125], v[124:125], 1.0 op_sel_hi:[1,0]
	v_pk_add_f32 v[126:127], v[126:127], 1.0 op_sel_hi:[1,0]
	s_cmp_eq_u32 s2, 0
	s_cbranch_scc1 .Lnorm_n2_done
; DI unsigned pk2(float lo, float hi) { return f2bf(lo) | (f2bf(hi) << 16); }
; DI void norm_phase(const Args& A, int wave_s, int l, int which, int rows) {
;     ...
;             float ss = 0.f;
; #pragma unroll
;             for (int j = 0; j < 4; ++j) ss += (xv[rr][j].x * xv[rr][j].x + xv[rr][j].y * xv[rr][j].y) + (xv[rr][j].z * xv[rr][j].z + xv[rr][j].w * xv[rr][j].w);
;             ss = wave_sum(C.lane, ss);
;             const float rs = rsqrtf(ss * (1.f / 1024.f) + EPS);
; #pragma unroll
;             for (int j = 0; j < 4; ++j) { const int col = 4 * (C.lane + 64 * j);
;                 const f32x4 y = xv[rr][j] * rs * g[j] * (sc[j] + 1.f) + sh[j];
;                 v2u o; o.x = pk2(y.x, y.y); o.y = pk2(y.z, y.w);
;                 *(v2u*)(C.H + (size_t)m * 1024 + col) = o; }
	v_mul_f32_e32 v10, v96, v96
	v_fmac_f32_e32 v10, v97, v97
	v_fmac_f32_e32 v10, v98, v98
	v_fmac_f32_e32 v10, v99, v99
	v_fmac_f32_e32 v10, v100, v100
	v_fmac_f32_e32 v10, v101, v101
	v_fmac_f32_e32 v10, v102, v102
	v_fmac_f32_e32 v10, v103, v103
	v_fmac_f32_e32 v10, v104, v104
	v_fmac_f32_e32 v10, v105, v105
	v_fmac_f32_e32 v10, v106, v106
	v_fmac_f32_e32 v10, v107, v107
	v_fmac_f32_e32 v10, v108, v108
	v_fmac_f32_e32 v10, v109, v109
	v_fmac_f32_e32 v10, v110, v110
	v_fmac_f32_e32 v10, v111, v111
	ds_bpermute_b32 v14, v4, v10
	s_waitcnt lgkmcnt(0)
	v_add_f32_e32 v10, v10, v14
	ds_bpermute_b32 v14, v5, v10
	s_waitcnt lgkmcnt(0)
	v_add_f32_e32 v10, v10, v14
	ds_bpermute_b32 v14, v6, v10
	s_waitcnt lgkmcnt(0)
	v_add_f32_e32 v10, v10, v14
	ds_bpermute_b32 v14, v7, v10
	s_waitcnt lgkmcnt(0)
	v_add_f32_e32 v10, v10, v14
	ds_bpermute_b32 v14, v8, v10
	s_waitcnt lgkmcnt(0)
	v_add_f32_e32 v10, v10, v14
	ds_bpermute_b32 v14, v9, v10
	s_waitcnt lgkmcnt(0)
	v_add_f32_e32 v10, v10, v14
	v_fma_f32 v10, v10, s32, v60
	v_rsq_f32_e32 v18, v10
	s_nop 0
	v_pk_mul_f32 v[96:97], v[96:97], v[18:19] op_sel_hi:[1,0]
	v_pk_mul_f32 v[98:99], v[98:99], v[18:19] op_sel_hi:[1,0]
	v_pk_mul_f32 v[100:101], v[100:101], v[18:19] op_sel_hi:[1,0]
	v_pk_mul_f32 v[102:103], v[102:103], v[18:19] op_sel_hi:[1,0]
	v_pk_mul_f32 v[104:105], v[104:105], v[18:19] op_sel_hi:[1,0]
	v_pk_mul_f32 v[106:107], v[106:107], v[18:19] op_sel_hi:[1,0]
	v_pk_mul_f32 v[108:109], v[108:109], v[18:19] op_sel_hi:[1,0]
	v_pk_mul_f32 v[110:111], v[110:111], v[18:19] op_sel_hi:[1,0]
	v_pk_mul_f32 v[96:97], v[24:25], v[96:97]
	v_pk_mul_f32 v[98:99], v[26:27], v[98:99]
	v_pk_mul_f32 v[100:101], v[28:29], v[100:101]
	v_pk_mul_f32 v[102:103], v[30:31], v[102:103]
	v_pk_mul_f32 v[104:105], v[32:33], v[104:105]
	v_pk_mul_f32 v[106:107], v[34:35], v[106:107]
	v_pk_mul_f32 v[108:109], v[36:37], v[108:109]
	v_pk_mul_f32 v[110:111], v[38:39], v[110:111]
	v_pk_fma_f32 v[96:97], v[112:113], v[96:97], v[128:129]
	v_pk_fma_f32 v[98:99], v[114:115], v[98:99], v[130:131]
	v_pk_fma_f32 v[100:101], v[116:117], v[100:101], v[132:133]
	v_pk_fma_f32 v[102:103], v[118:119], v[102:103], v[134:135]
	v_pk_fma_f32 v[104:105], v[120:121], v[104:105], v[136:137]
	v_pk_fma_f32 v[106:107], v[122:123], v[106:107], v[138:139]
	v_pk_fma_f32 v[108:109], v[124:125], v[108:109], v[140:141]
	v_pk_fma_f32 v[110:111], v[126:127], v[110:111], v[142:143]
	v_cvt_pk_bf16_f32 v96, v96, v97
	v_cvt_pk_bf16_f32 v97, v98, v99
	v_cvt_pk_bf16_f32 v98, v100, v101
	v_cvt_pk_bf16_f32 v99, v102, v103
	v_cvt_pk_bf16_f32 v104, v104, v105
	v_cvt_pk_bf16_f32 v105, v106, v107
	v_cvt_pk_bf16_f32 v106, v108, v109
	v_cvt_pk_bf16_f32 v107, v110, v111
	global_store_dwordx4 v2, v[96:99], s[10:11] sc1
	global_store_dwordx4 v2, v[104:107], s[10:11] offset:1024 sc1
